# v60 + EPF: f32-residual mode of the out-proj/FF2 epilogues streams its residual three blocks ahead with counted waits
# speedup vs baseline: 1.0029x; 1.0029x over previous
; __device__ __forceinline__ u32x4 pack8(const f32x4 a, const f32x4 b) { u32x4 w; w.x = cvt_pk_bf16(a[0], a[1]); w.y = cvt_pk_bf16(a[2], a[3]); w.z = cvt_pk_bf16(b[0], b[1]); w.w = cvt_pk_bf16(b[2], b[3]); return w; }
;     __device__ __forceinline__ void operator()(const f32x4 (&acc)[2][2][4][2], const Unit& u, int wr, int wc, int fr, int fq) const {
;     ...
;         const float* ib = lat ? rinL : rinC - (size_t)32768 * 1024; float* ob = lat ? routL : routC - (size_t)32768 * 1024;
;         const bool tobf = lat && vout != nullptr;
; #pragma unroll
;         for (int ai = 0; ai < 2; ++ai)
; #pragma unroll
;             for (int m = 0; m < 4; ++m) { const size_t off = (size_t)(rowb + ai * HALF + m * 16) * 1024 + col0;
; #pragma unroll
;                 for (int bj = 0; bj < 2; ++bj) { f32x4 o[2];
;                     if (lat && rinB) { const u32x4 w = *(const u32x4*)(rinB + off + bj * 32);
;                         const f32x4 b0 = {__builtin_bit_cast(float, w.x << 16), __builtin_bit_cast(float, w.x & 0xffff0000u), __builtin_bit_cast(float, w.y << 16), __builtin_bit_cast(float, w.y & 0xffff0000u)};
;                         const f32x4 b1 = {__builtin_bit_cast(float, w.z << 16), __builtin_bit_cast(float, w.z & 0xffff0000u), __builtin_bit_cast(float, w.w << 16), __builtin_bit_cast(float, w.w & 0xffff0000u)};
;                         o[0] = b0 * 1.6817928305074290f + gv[bj][0] * acc[ai][bj][m][0]; o[1] = b1 * 1.6817928305074290f + gv[bj][1] * acc[ai][bj][m][1]; }
;                     else {
; #pragma unroll
;                     for (int n = 0; n < 2; ++n) { const f32x4 bs = *(const f32x4*)(ib + off + bj * 32 + n * 4); o[n] = bs * 1.6817928305074290f + gv[bj][n] * acc[ai][bj][m][n]; } }
;                     if (tobf) *(u32x4*)(vout + off + bj * 32) = pack8(o[0], o[1]);
;                     else { *(f32x4*)(ob + off + bj * 32) = o[0]; *(f32x4*)(ob + off + bj * 32 + 4) = o[1]; } }
.LBB0_891:
	s_andn2_b64 vcc, exec, s[30:31]
	v_lshl_add_u64 v[196:197], v[192:193], 2, s[34:35]
	s_cbranch_vccnz .LBB0_893
	v_lshlrev_b32_e32 v251, 1, v250
	global_load_dwordx4 v[208:211], v251, s[34:35]
	global_load_dwordx4 v[226:229], v251, s[34:35] offset:16
	v_lshlrev_b32_e32 v251, 1, v250
	global_load_dwordx4 v[230:233], v251, s[34:35] offset:128
	global_load_dwordx4 v[234:237], v251, s[34:35] offset:144
	v_lshlrev_b32_e32 v251, 1, v250
	v_add_u32_e32 v251, 0x10000, v251
	global_load_dwordx4 v[238:241], v251, s[34:35]
	global_load_dwordx4 v[242:245], v251, s[34:35] offset:16
	s_waitcnt vmcnt(4)
	v_mov_b32_e32 v162, v208
	v_mov_b32_e32 v163, v209
	v_mov_b32_e32 v164, v210
	v_mov_b32_e32 v165, v211
	v_mov_b32_e32 v166, v226
	v_mov_b32_e32 v167, v227
	v_mov_b32_e32 v168, v228
	v_mov_b32_e32 v169, v229
	v_lshlrev_b32_e32 v251, 1, v250
	v_add_u32_e32 v251, 0x10000, v251
	global_load_dwordx4 v[208:211], v251, s[34:35] offset:128
	global_load_dwordx4 v[226:229], v251, s[34:35] offset:144
	v_pk_mul_f32 v[164:165], v[164:165], s[86:87] op_sel_hi:[1,0]
	v_pk_mul_f32 v[162:163], v[162:163], s[86:87] op_sel_hi:[1,0]
	v_pk_fma_f32 v[164:165], v[144:145], v[160:161], v[164:165]
	v_pk_fma_f32 v[162:163], v[142:143], v[158:159], v[162:163]

; __device__ __forceinline__ u32x4 pack8(const f32x4 a, const f32x4 b) { u32x4 w; w.x = cvt_pk_bf16(a[0], a[1]); w.y = cvt_pk_bf16(a[2], a[3]); w.z = cvt_pk_bf16(b[0], b[1]); w.w = cvt_pk_bf16(b[2], b[3]); return w; }
;     __device__ __forceinline__ void operator()(const f32x4 (&acc)[2][2][4][2], const Unit& u, int wr, int wc, int fr, int fq) const {
;     ...
;                 for (int bj = 0; bj < 2; ++bj) { f32x4 o[2];
;                     if (lat && rinB) { const u32x4 w = *(const u32x4*)(rinB + off + bj * 32);
;                         const f32x4 b0 = {__builtin_bit_cast(float, w.x << 16), __builtin_bit_cast(float, w.x & 0xffff0000u), __builtin_bit_cast(float, w.y << 16), __builtin_bit_cast(float, w.y & 0xffff0000u)};
;                         const f32x4 b1 = {__builtin_bit_cast(float, w.z << 16), __builtin_bit_cast(float, w.z & 0xffff0000u), __builtin_bit_cast(float, w.w << 16), __builtin_bit_cast(float, w.w & 0xffff0000u)};
;                         o[0] = b0 * 1.6817928305074290f + gv[bj][0] * acc[ai][bj][m][0]; o[1] = b1 * 1.6817928305074290f + gv[bj][1] * acc[ai][bj][m][1]; }
;                     else {
; #pragma unroll
;                     for (int n = 0; n < 2; ++n) { const f32x4 bs = *(const f32x4*)(ib + off + bj * 32 + n * 4); o[n] = bs * 1.6817928305074290f + gv[bj][n] * acc[ai][bj][m][n]; } }
;                     if (tobf) *(u32x4*)(vout + off + bj * 32) = pack8(o[0], o[1]);
;                     else { *(f32x4*)(ob + off + bj * 32) = o[0]; *(f32x4*)(ob + off + bj * 32 + 4) = o[1]; } }
.LBB0_901:
	s_andn2_b64 vcc, exec, s[36:37]
	s_cbranch_vccnz .LBB0_903
	s_waitcnt vmcnt(5)
	v_mov_b32_e32 v162, v230
	v_mov_b32_e32 v163, v231
	v_mov_b32_e32 v164, v232
	v_mov_b32_e32 v165, v233
	v_mov_b32_e32 v174, v234
	v_mov_b32_e32 v175, v235
	v_mov_b32_e32 v176, v236
	v_mov_b32_e32 v177, v237
	v_lshlrev_b32_e32 v251, 1, v250
	v_add_u32_e32 v251, 0x20000, v251
	global_load_dwordx4 v[230:233], v251, s[34:35]
	global_load_dwordx4 v[234:237], v251, s[34:35] offset:16
	v_pk_mul_f32 v[164:165], v[164:165], s[86:87] op_sel_hi:[1,0]
	v_pk_mul_f32 v[162:163], v[162:163], s[86:87] op_sel_hi:[1,0]
	v_pk_fma_f32 v[168:169], v[132:133], v[152:153], v[164:165]
	v_pk_fma_f32 v[166:167], v[130:131], v[150:151], v[162:163]

; __device__ __forceinline__ u32x4 pack8(const f32x4 a, const f32x4 b) { u32x4 w; w.x = cvt_pk_bf16(a[0], a[1]); w.y = cvt_pk_bf16(a[2], a[3]); w.z = cvt_pk_bf16(b[0], b[1]); w.w = cvt_pk_bf16(b[2], b[3]); return w; }
;     __device__ __forceinline__ void operator()(const f32x4 (&acc)[2][2][4][2], const Unit& u, int wr, int wc, int fr, int fq) const {
;     ...
;                 for (int bj = 0; bj < 2; ++bj) { f32x4 o[2];
;                     if (lat && rinB) { const u32x4 w = *(const u32x4*)(rinB + off + bj * 32);
;                         const f32x4 b0 = {__builtin_bit_cast(float, w.x << 16), __builtin_bit_cast(float, w.x & 0xffff0000u), __builtin_bit_cast(float, w.y << 16), __builtin_bit_cast(float, w.y & 0xffff0000u)};
;                         const f32x4 b1 = {__builtin_bit_cast(float, w.z << 16), __builtin_bit_cast(float, w.z & 0xffff0000u), __builtin_bit_cast(float, w.w << 16), __builtin_bit_cast(float, w.w & 0xffff0000u)};
;                         o[0] = b0 * 1.6817928305074290f + gv[bj][0] * acc[ai][bj][m][0]; o[1] = b1 * 1.6817928305074290f + gv[bj][1] * acc[ai][bj][m][1]; }
;                     else {
; #pragma unroll
;                     for (int n = 0; n < 2; ++n) { const f32x4 bs = *(const f32x4*)(ib + off + bj * 32 + n * 4); o[n] = bs * 1.6817928305074290f + gv[bj][n] * acc[ai][bj][m][n]; } }
;                     if (tobf) *(u32x4*)(vout + off + bj * 32) = pack8(o[0], o[1]);
;                     else { *(f32x4*)(ob + off + bj * 32) = o[0]; *(f32x4*)(ob + off + bj * 32 + 4) = o[1]; } }
.LBB0_909:
	s_andn2_b64 vcc, exec, s[36:37]
	v_lshl_add_u64 v[196:197], v[192:193], 2, s[34:35]
	s_cbranch_vccnz .LBB0_911
	s_waitcnt vmcnt(6)
	v_mov_b32_e32 v162, v238
	v_mov_b32_e32 v163, v239
	v_mov_b32_e32 v164, v240
	v_mov_b32_e32 v165, v241
	v_mov_b32_e32 v166, v242
	v_mov_b32_e32 v167, v243
	v_mov_b32_e32 v168, v244
	v_mov_b32_e32 v169, v245
	v_lshlrev_b32_e32 v251, 1, v250
	v_add_u32_e32 v251, 0x20000, v251
	global_load_dwordx4 v[238:241], v251, s[34:35] offset:128
	global_load_dwordx4 v[242:245], v251, s[34:35] offset:144
	v_pk_mul_f32 v[164:165], v[164:165], s[86:87] op_sel_hi:[1,0]
	v_pk_mul_f32 v[162:163], v[162:163], s[86:87] op_sel_hi:[1,0]
	v_pk_fma_f32 v[164:165], v[136:137], v[160:161], v[164:165]
	v_pk_fma_f32 v[162:163], v[134:135], v[158:159], v[162:163]

; __device__ __forceinline__ u32x4 pack8(const f32x4 a, const f32x4 b) { u32x4 w; w.x = cvt_pk_bf16(a[0], a[1]); w.y = cvt_pk_bf16(a[2], a[3]); w.z = cvt_pk_bf16(b[0], b[1]); w.w = cvt_pk_bf16(b[2], b[3]); return w; }
;     __device__ __forceinline__ void operator()(const f32x4 (&acc)[2][2][4][2], const Unit& u, int wr, int wc, int fr, int fq) const {
;     ...
;                 for (int bj = 0; bj < 2; ++bj) { f32x4 o[2];
;                     if (lat && rinB) { const u32x4 w = *(const u32x4*)(rinB + off + bj * 32);
;                         const f32x4 b0 = {__builtin_bit_cast(float, w.x << 16), __builtin_bit_cast(float, w.x & 0xffff0000u), __builtin_bit_cast(float, w.y << 16), __builtin_bit_cast(float, w.y & 0xffff0000u)};
;                         const f32x4 b1 = {__builtin_bit_cast(float, w.z << 16), __builtin_bit_cast(float, w.z & 0xffff0000u), __builtin_bit_cast(float, w.w << 16), __builtin_bit_cast(float, w.w & 0xffff0000u)};
;                         o[0] = b0 * 1.6817928305074290f + gv[bj][0] * acc[ai][bj][m][0]; o[1] = b1 * 1.6817928305074290f + gv[bj][1] * acc[ai][bj][m][1]; }
;                     else {
; #pragma unroll
;                     for (int n = 0; n < 2; ++n) { const f32x4 bs = *(const f32x4*)(ib + off + bj * 32 + n * 4); o[n] = bs * 1.6817928305074290f + gv[bj][n] * acc[ai][bj][m][n]; } }
;                     if (tobf) *(u32x4*)(vout + off + bj * 32) = pack8(o[0], o[1]);
;                     else { *(f32x4*)(ob + off + bj * 32) = o[0]; *(f32x4*)(ob + off + bj * 32 + 4) = o[1]; } }
.LBB0_917:
	s_andn2_b64 vcc, exec, s[36:37]
	s_cbranch_vccnz .LBB0_919
	s_waitcnt vmcnt(7)
	v_mov_b32_e32 v162, v208
	v_mov_b32_e32 v163, v209
	v_mov_b32_e32 v164, v210
	v_mov_b32_e32 v165, v211
	v_mov_b32_e32 v170, v226
	v_mov_b32_e32 v171, v227
	v_mov_b32_e32 v172, v228
	v_mov_b32_e32 v173, v229
	v_lshlrev_b32_e32 v251, 1, v250
	v_add_u32_e32 v251, 0x30000, v251
	global_load_dwordx4 v[208:211], v251, s[34:35]
	global_load_dwordx4 v[226:229], v251, s[34:35] offset:16
	v_pk_mul_f32 v[164:165], v[164:165], s[86:87] op_sel_hi:[1,0]
	v_pk_mul_f32 v[162:163], v[162:163], s[86:87] op_sel_hi:[1,0]
	v_pk_fma_f32 v[168:169], v[100:101], v[152:153], v[164:165]
	v_pk_fma_f32 v[166:167], v[98:99], v[150:151], v[162:163]

; __device__ __forceinline__ u32x4 pack8(const f32x4 a, const f32x4 b) { u32x4 w; w.x = cvt_pk_bf16(a[0], a[1]); w.y = cvt_pk_bf16(a[2], a[3]); w.z = cvt_pk_bf16(b[0], b[1]); w.w = cvt_pk_bf16(b[2], b[3]); return w; }
;     __device__ __forceinline__ void operator()(const f32x4 (&acc)[2][2][4][2], const Unit& u, int wr, int wc, int fr, int fq) const {
;     ...
;                 for (int bj = 0; bj < 2; ++bj) { f32x4 o[2];
;                     if (lat && rinB) { const u32x4 w = *(const u32x4*)(rinB + off + bj * 32);
;                         const f32x4 b0 = {__builtin_bit_cast(float, w.x << 16), __builtin_bit_cast(float, w.x & 0xffff0000u), __builtin_bit_cast(float, w.y << 16), __builtin_bit_cast(float, w.y & 0xffff0000u)};
;                         const f32x4 b1 = {__builtin_bit_cast(float, w.z << 16), __builtin_bit_cast(float, w.z & 0xffff0000u), __builtin_bit_cast(float, w.w << 16), __builtin_bit_cast(float, w.w & 0xffff0000u)};
;                         o[0] = b0 * 1.6817928305074290f + gv[bj][0] * acc[ai][bj][m][0]; o[1] = b1 * 1.6817928305074290f + gv[bj][1] * acc[ai][bj][m][1]; }
;                     else {
; #pragma unroll
;                     for (int n = 0; n < 2; ++n) { const f32x4 bs = *(const f32x4*)(ib + off + bj * 32 + n * 4); o[n] = bs * 1.6817928305074290f + gv[bj][n] * acc[ai][bj][m][n]; } }
;                     if (tobf) *(u32x4*)(vout + off + bj * 32) = pack8(o[0], o[1]);
;                     else { *(f32x4*)(ob + off + bj * 32) = o[0]; *(f32x4*)(ob + off + bj * 32 + 4) = o[1]; } }
.LBB0_925:
	s_andn2_b64 vcc, exec, s[36:37]
	v_lshl_add_u64 v[196:197], v[192:193], 2, s[34:35]
	s_cbranch_vccnz .LBB0_927
	s_waitcnt vmcnt(7)
	v_mov_b32_e32 v162, v230
	v_mov_b32_e32 v163, v231
	v_mov_b32_e32 v164, v232
	v_mov_b32_e32 v165, v233
	v_mov_b32_e32 v166, v234
	v_mov_b32_e32 v167, v235
	v_mov_b32_e32 v168, v236
	v_mov_b32_e32 v169, v237
	v_lshlrev_b32_e32 v251, 1, v250
	v_add_u32_e32 v251, 0x30000, v251
	global_load_dwordx4 v[230:233], v251, s[34:35] offset:128
	global_load_dwordx4 v[234:237], v251, s[34:35] offset:144
	v_pk_mul_f32 v[164:165], v[164:165], s[86:87] op_sel_hi:[1,0]
	v_pk_mul_f32 v[162:163], v[162:163], s[86:87] op_sel_hi:[1,0]
	v_pk_fma_f32 v[164:165], v[104:105], v[160:161], v[164:165]
	v_pk_fma_f32 v[162:163], v[102:103], v[158:159], v[162:163]

; __device__ __forceinline__ u32x4 pack8(const f32x4 a, const f32x4 b) { u32x4 w; w.x = cvt_pk_bf16(a[0], a[1]); w.y = cvt_pk_bf16(a[2], a[3]); w.z = cvt_pk_bf16(b[0], b[1]); w.w = cvt_pk_bf16(b[2], b[3]); return w; }
;     __device__ __forceinline__ void operator()(const f32x4 (&acc)[2][2][4][2], const Unit& u, int wr, int wc, int fr, int fq) const {
;     ...
;                 for (int bj = 0; bj < 2; ++bj) { f32x4 o[2];
;                     if (lat && rinB) { const u32x4 w = *(const u32x4*)(rinB + off + bj * 32);
;                         const f32x4 b0 = {__builtin_bit_cast(float, w.x << 16), __builtin_bit_cast(float, w.x & 0xffff0000u), __builtin_bit_cast(float, w.y << 16), __builtin_bit_cast(float, w.y & 0xffff0000u)};
;                         const f32x4 b1 = {__builtin_bit_cast(float, w.z << 16), __builtin_bit_cast(float, w.z & 0xffff0000u), __builtin_bit_cast(float, w.w << 16), __builtin_bit_cast(float, w.w & 0xffff0000u)};
;                         o[0] = b0 * 1.6817928305074290f + gv[bj][0] * acc[ai][bj][m][0]; o[1] = b1 * 1.6817928305074290f + gv[bj][1] * acc[ai][bj][m][1]; }
;                     else {
; #pragma unroll
;                     for (int n = 0; n < 2; ++n) { const f32x4 bs = *(const f32x4*)(ib + off + bj * 32 + n * 4); o[n] = bs * 1.6817928305074290f + gv[bj][n] * acc[ai][bj][m][n]; } }
;                     if (tobf) *(u32x4*)(vout + off + bj * 32) = pack8(o[0], o[1]);
;                     else { *(f32x4*)(ob + off + bj * 32) = o[0]; *(f32x4*)(ob + off + bj * 32 + 4) = o[1]; } }
.LBB0_933:
	s_andn2_b64 vcc, exec, s[36:37]
	s_cbranch_vccnz .LBB0_935
	s_waitcnt vmcnt(7)
	v_mov_b32_e32 v162, v238
	v_mov_b32_e32 v163, v239
	v_mov_b32_e32 v164, v240
	v_mov_b32_e32 v165, v241
	v_mov_b32_e32 v174, v242
	v_mov_b32_e32 v175, v243
	v_mov_b32_e32 v176, v244
	v_mov_b32_e32 v177, v245
	v_lshlrev_b32_e32 v251, 1, v250
	v_add_u32_e32 v251, 0x80000, v251
	global_load_dwordx4 v[238:241], v251, s[34:35]
	global_load_dwordx4 v[242:245], v251, s[34:35] offset:16
	v_pk_mul_f32 v[164:165], v[164:165], s[86:87] op_sel_hi:[1,0]
	v_pk_mul_f32 v[162:163], v[162:163], s[86:87] op_sel_hi:[1,0]
	v_pk_fma_f32 v[168:169], v[84:85], v[152:153], v[164:165]
	v_pk_fma_f32 v[166:167], v[82:83], v[150:151], v[162:163]

; __device__ __forceinline__ u32x4 pack8(const f32x4 a, const f32x4 b) { u32x4 w; w.x = cvt_pk_bf16(a[0], a[1]); w.y = cvt_pk_bf16(a[2], a[3]); w.z = cvt_pk_bf16(b[0], b[1]); w.w = cvt_pk_bf16(b[2], b[3]); return w; }
;     __device__ __forceinline__ void operator()(const f32x4 (&acc)[2][2][4][2], const Unit& u, int wr, int wc, int fr, int fq) const {
;     ...
;                 for (int bj = 0; bj < 2; ++bj) { f32x4 o[2];
;                     if (lat && rinB) { const u32x4 w = *(const u32x4*)(rinB + off + bj * 32);
;                         const f32x4 b0 = {__builtin_bit_cast(float, w.x << 16), __builtin_bit_cast(float, w.x & 0xffff0000u), __builtin_bit_cast(float, w.y << 16), __builtin_bit_cast(float, w.y & 0xffff0000u)};
;                         const f32x4 b1 = {__builtin_bit_cast(float, w.z << 16), __builtin_bit_cast(float, w.z & 0xffff0000u), __builtin_bit_cast(float, w.w << 16), __builtin_bit_cast(float, w.w & 0xffff0000u)};
;                         o[0] = b0 * 1.6817928305074290f + gv[bj][0] * acc[ai][bj][m][0]; o[1] = b1 * 1.6817928305074290f + gv[bj][1] * acc[ai][bj][m][1]; }
;                     else {
; #pragma unroll
;                     for (int n = 0; n < 2; ++n) { const f32x4 bs = *(const f32x4*)(ib + off + bj * 32 + n * 4); o[n] = bs * 1.6817928305074290f + gv[bj][n] * acc[ai][bj][m][n]; } }
;                     if (tobf) *(u32x4*)(vout + off + bj * 32) = pack8(o[0], o[1]);
;                     else { *(f32x4*)(ob + off + bj * 32) = o[0]; *(f32x4*)(ob + off + bj * 32 + 4) = o[1]; } }
.LBB0_941:
	s_andn2_b64 vcc, exec, s[36:37]
	v_lshl_add_u64 v[196:197], v[192:193], 2, s[34:35]
	s_cbranch_vccnz .LBB0_943
	s_waitcnt vmcnt(7)
	v_mov_b32_e32 v162, v208
	v_mov_b32_e32 v163, v209
	v_mov_b32_e32 v164, v210
	v_mov_b32_e32 v165, v211
	v_mov_b32_e32 v166, v226
	v_mov_b32_e32 v167, v227
	v_mov_b32_e32 v168, v228
	v_mov_b32_e32 v169, v229
	v_lshlrev_b32_e32 v251, 1, v250
	v_add_u32_e32 v251, 0x80000, v251
	global_load_dwordx4 v[208:211], v251, s[34:35] offset:128
	global_load_dwordx4 v[226:229], v251, s[34:35] offset:144
	v_pk_mul_f32 v[164:165], v[164:165], s[86:87] op_sel_hi:[1,0]
	v_pk_mul_f32 v[162:163], v[162:163], s[86:87] op_sel_hi:[1,0]
	v_pk_fma_f32 v[164:165], v[88:89], v[160:161], v[164:165]
	v_pk_fma_f32 v[162:163], v[86:87], v[158:159], v[162:163]

; __device__ __forceinline__ u32x4 pack8(const f32x4 a, const f32x4 b) { u32x4 w; w.x = cvt_pk_bf16(a[0], a[1]); w.y = cvt_pk_bf16(a[2], a[3]); w.z = cvt_pk_bf16(b[0], b[1]); w.w = cvt_pk_bf16(b[2], b[3]); return w; }
;     __device__ __forceinline__ void operator()(const f32x4 (&acc)[2][2][4][2], const Unit& u, int wr, int wc, int fr, int fq) const {
;     ...
;                 for (int bj = 0; bj < 2; ++bj) { f32x4 o[2];
;                     if (lat && rinB) { const u32x4 w = *(const u32x4*)(rinB + off + bj * 32);
;                         const f32x4 b0 = {__builtin_bit_cast(float, w.x << 16), __builtin_bit_cast(float, w.x & 0xffff0000u), __builtin_bit_cast(float, w.y << 16), __builtin_bit_cast(float, w.y & 0xffff0000u)};
;                         const f32x4 b1 = {__builtin_bit_cast(float, w.z << 16), __builtin_bit_cast(float, w.z & 0xffff0000u), __builtin_bit_cast(float, w.w << 16), __builtin_bit_cast(float, w.w & 0xffff0000u)};
;                         o[0] = b0 * 1.6817928305074290f + gv[bj][0] * acc[ai][bj][m][0]; o[1] = b1 * 1.6817928305074290f + gv[bj][1] * acc[ai][bj][m][1]; }
;                     else {
; #pragma unroll
;                     for (int n = 0; n < 2; ++n) { const f32x4 bs = *(const f32x4*)(ib + off + bj * 32 + n * 4); o[n] = bs * 1.6817928305074290f + gv[bj][n] * acc[ai][bj][m][n]; } }
;                     if (tobf) *(u32x4*)(vout + off + bj * 32) = pack8(o[0], o[1]);
;                     else { *(f32x4*)(ob + off + bj * 32) = o[0]; *(f32x4*)(ob + off + bj * 32 + 4) = o[1]; } }
.LBB0_949:
	s_andn2_b64 vcc, exec, s[36:37]
	s_cbranch_vccnz .LBB0_951
	s_waitcnt vmcnt(7)
	v_mov_b32_e32 v162, v230
	v_mov_b32_e32 v163, v231
	v_mov_b32_e32 v164, v232
	v_mov_b32_e32 v165, v233
	v_mov_b32_e32 v174, v234
	v_mov_b32_e32 v175, v235
	v_mov_b32_e32 v176, v236
	v_mov_b32_e32 v177, v237
	v_lshlrev_b32_e32 v251, 1, v250
	v_add_u32_e32 v251, 0x90000, v251
	global_load_dwordx4 v[230:233], v251, s[34:35]
	global_load_dwordx4 v[234:237], v251, s[34:35] offset:16
	v_pk_mul_f32 v[164:165], v[164:165], s[86:87] op_sel_hi:[1,0]
	v_pk_mul_f32 v[162:163], v[162:163], s[86:87] op_sel_hi:[1,0]
	v_pk_fma_f32 v[168:169], v[72:73], v[152:153], v[164:165]
	v_pk_fma_f32 v[166:167], v[70:71], v[150:151], v[162:163]

; __device__ __forceinline__ u32x4 pack8(const f32x4 a, const f32x4 b) { u32x4 w; w.x = cvt_pk_bf16(a[0], a[1]); w.y = cvt_pk_bf16(a[2], a[3]); w.z = cvt_pk_bf16(b[0], b[1]); w.w = cvt_pk_bf16(b[2], b[3]); return w; }
;     __device__ __forceinline__ void operator()(const f32x4 (&acc)[2][2][4][2], const Unit& u, int wr, int wc, int fr, int fq) const {
;     ...
;                 for (int bj = 0; bj < 2; ++bj) { f32x4 o[2];
;                     if (lat && rinB) { const u32x4 w = *(const u32x4*)(rinB + off + bj * 32);
;                         const f32x4 b0 = {__builtin_bit_cast(float, w.x << 16), __builtin_bit_cast(float, w.x & 0xffff0000u), __builtin_bit_cast(float, w.y << 16), __builtin_bit_cast(float, w.y & 0xffff0000u)};
;                         const f32x4 b1 = {__builtin_bit_cast(float, w.z << 16), __builtin_bit_cast(float, w.z & 0xffff0000u), __builtin_bit_cast(float, w.w << 16), __builtin_bit_cast(float, w.w & 0xffff0000u)};
;                         o[0] = b0 * 1.6817928305074290f + gv[bj][0] * acc[ai][bj][m][0]; o[1] = b1 * 1.6817928305074290f + gv[bj][1] * acc[ai][bj][m][1]; }
;                     else {
; #pragma unroll
;                     for (int n = 0; n < 2; ++n) { const f32x4 bs = *(const f32x4*)(ib + off + bj * 32 + n * 4); o[n] = bs * 1.6817928305074290f + gv[bj][n] * acc[ai][bj][m][n]; } }
;                     if (tobf) *(u32x4*)(vout + off + bj * 32) = pack8(o[0], o[1]);
;                     else { *(f32x4*)(ob + off + bj * 32) = o[0]; *(f32x4*)(ob + off + bj * 32 + 4) = o[1]; } }
.LBB0_957:
	s_andn2_b64 vcc, exec, s[36:37]
	v_lshl_add_u64 v[196:197], v[192:193], 2, s[34:35]
	s_cbranch_vccnz .LBB0_959
	s_waitcnt vmcnt(7)
	v_mov_b32_e32 v162, v238
	v_mov_b32_e32 v163, v239
	v_mov_b32_e32 v164, v240
	v_mov_b32_e32 v165, v241
	v_mov_b32_e32 v166, v242
	v_mov_b32_e32 v167, v243
	v_mov_b32_e32 v168, v244
	v_mov_b32_e32 v169, v245
	v_lshlrev_b32_e32 v251, 1, v250
	v_add_u32_e32 v251, 0x90000, v251
	global_load_dwordx4 v[238:241], v251, s[34:35] offset:128
	global_load_dwordx4 v[242:245], v251, s[34:35] offset:144
	v_pk_mul_f32 v[164:165], v[164:165], s[86:87] op_sel_hi:[1,0]
	v_pk_mul_f32 v[162:163], v[162:163], s[86:87] op_sel_hi:[1,0]
	v_pk_fma_f32 v[164:165], v[64:65], v[160:161], v[164:165]
	v_pk_fma_f32 v[162:163], v[62:63], v[158:159], v[162:163]

; __device__ __forceinline__ u32x4 pack8(const f32x4 a, const f32x4 b) { u32x4 w; w.x = cvt_pk_bf16(a[0], a[1]); w.y = cvt_pk_bf16(a[2], a[3]); w.z = cvt_pk_bf16(b[0], b[1]); w.w = cvt_pk_bf16(b[2], b[3]); return w; }
;     __device__ __forceinline__ void operator()(const f32x4 (&acc)[2][2][4][2], const Unit& u, int wr, int wc, int fr, int fq) const {
;     ...
;                 for (int bj = 0; bj < 2; ++bj) { f32x4 o[2];
;                     if (lat && rinB) { const u32x4 w = *(const u32x4*)(rinB + off + bj * 32);
;                         const f32x4 b0 = {__builtin_bit_cast(float, w.x << 16), __builtin_bit_cast(float, w.x & 0xffff0000u), __builtin_bit_cast(float, w.y << 16), __builtin_bit_cast(float, w.y & 0xffff0000u)};
;                         const f32x4 b1 = {__builtin_bit_cast(float, w.z << 16), __builtin_bit_cast(float, w.z & 0xffff0000u), __builtin_bit_cast(float, w.w << 16), __builtin_bit_cast(float, w.w & 0xffff0000u)};
;                         o[0] = b0 * 1.6817928305074290f + gv[bj][0] * acc[ai][bj][m][0]; o[1] = b1 * 1.6817928305074290f + gv[bj][1] * acc[ai][bj][m][1]; }
;                     else {
; #pragma unroll
;                     for (int n = 0; n < 2; ++n) { const f32x4 bs = *(const f32x4*)(ib + off + bj * 32 + n * 4); o[n] = bs * 1.6817928305074290f + gv[bj][n] * acc[ai][bj][m][n]; } }
;                     if (tobf) *(u32x4*)(vout + off + bj * 32) = pack8(o[0], o[1]);
;                     else { *(f32x4*)(ob + off + bj * 32) = o[0]; *(f32x4*)(ob + off + bj * 32 + 4) = o[1]; } }
.LBB0_965:
	s_andn2_b64 vcc, exec, s[36:37]
	s_cbranch_vccnz .LBB0_967
	s_waitcnt vmcnt(7)
	v_mov_b32_e32 v162, v208
	v_mov_b32_e32 v163, v209
	v_mov_b32_e32 v164, v210
	v_mov_b32_e32 v165, v211
	v_mov_b32_e32 v174, v226
	v_mov_b32_e32 v175, v227
	v_mov_b32_e32 v176, v228
	v_mov_b32_e32 v177, v229
	v_lshlrev_b32_e32 v251, 1, v250
	v_add_u32_e32 v251, 0xa0000, v251
	global_load_dwordx4 v[208:211], v251, s[34:35]
	global_load_dwordx4 v[226:229], v251, s[34:35] offset:16
	v_pk_mul_f32 v[164:165], v[164:165], s[86:87] op_sel_hi:[1,0]
	v_pk_mul_f32 v[162:163], v[162:163], s[86:87] op_sel_hi:[1,0]
	v_pk_fma_f32 v[168:169], v[52:53], v[152:153], v[164:165]
	v_pk_fma_f32 v[166:167], v[50:51], v[150:151], v[162:163]

; __device__ __forceinline__ u32x4 pack8(const f32x4 a, const f32x4 b) { u32x4 w; w.x = cvt_pk_bf16(a[0], a[1]); w.y = cvt_pk_bf16(a[2], a[3]); w.z = cvt_pk_bf16(b[0], b[1]); w.w = cvt_pk_bf16(b[2], b[3]); return w; }
;     __device__ __forceinline__ void operator()(const f32x4 (&acc)[2][2][4][2], const Unit& u, int wr, int wc, int fr, int fq) const {
;     ...
;                 for (int bj = 0; bj < 2; ++bj) { f32x4 o[2];
;                     if (lat && rinB) { const u32x4 w = *(const u32x4*)(rinB + off + bj * 32);
;                         const f32x4 b0 = {__builtin_bit_cast(float, w.x << 16), __builtin_bit_cast(float, w.x & 0xffff0000u), __builtin_bit_cast(float, w.y << 16), __builtin_bit_cast(float, w.y & 0xffff0000u)};
;                         const f32x4 b1 = {__builtin_bit_cast(float, w.z << 16), __builtin_bit_cast(float, w.z & 0xffff0000u), __builtin_bit_cast(float, w.w << 16), __builtin_bit_cast(float, w.w & 0xffff0000u)};
;                         o[0] = b0 * 1.6817928305074290f + gv[bj][0] * acc[ai][bj][m][0]; o[1] = b1 * 1.6817928305074290f + gv[bj][1] * acc[ai][bj][m][1]; }
;                     else {
; #pragma unroll
;                     for (int n = 0; n < 2; ++n) { const f32x4 bs = *(const f32x4*)(ib + off + bj * 32 + n * 4); o[n] = bs * 1.6817928305074290f + gv[bj][n] * acc[ai][bj][m][n]; } }
;                     if (tobf) *(u32x4*)(vout + off + bj * 32) = pack8(o[0], o[1]);
;                     else { *(f32x4*)(ob + off + bj * 32) = o[0]; *(f32x4*)(ob + off + bj * 32 + 4) = o[1]; } }
.LBB0_973:
	s_andn2_b64 vcc, exec, s[36:37]
	v_lshl_add_u64 v[196:197], v[192:193], 2, s[34:35]
	s_cbranch_vccnz .LBB0_975
	s_waitcnt vmcnt(7)
	v_mov_b32_e32 v162, v230
	v_mov_b32_e32 v163, v231
	v_mov_b32_e32 v164, v232
	v_mov_b32_e32 v165, v233
	v_mov_b32_e32 v166, v234
	v_mov_b32_e32 v167, v235
	v_mov_b32_e32 v168, v236
	v_mov_b32_e32 v169, v237
	v_lshlrev_b32_e32 v251, 1, v250
	v_add_u32_e32 v251, 0xa0000, v251
	global_load_dwordx4 v[230:233], v251, s[34:35] offset:128
	global_load_dwordx4 v[234:237], v251, s[34:35] offset:144
	v_pk_mul_f32 v[164:165], v[164:165], s[86:87] op_sel_hi:[1,0]
	v_pk_mul_f32 v[162:163], v[162:163], s[86:87] op_sel_hi:[1,0]
	v_pk_fma_f32 v[164:165], v[56:57], v[160:161], v[164:165]
	v_pk_fma_f32 v[162:163], v[54:55], v[158:159], v[162:163]

; __device__ __forceinline__ u32x4 pack8(const f32x4 a, const f32x4 b) { u32x4 w; w.x = cvt_pk_bf16(a[0], a[1]); w.y = cvt_pk_bf16(a[2], a[3]); w.z = cvt_pk_bf16(b[0], b[1]); w.w = cvt_pk_bf16(b[2], b[3]); return w; }
;     __device__ __forceinline__ void operator()(const f32x4 (&acc)[2][2][4][2], const Unit& u, int wr, int wc, int fr, int fq) const {
;     ...
;                 for (int bj = 0; bj < 2; ++bj) { f32x4 o[2];
;                     if (lat && rinB) { const u32x4 w = *(const u32x4*)(rinB + off + bj * 32);
;                         const f32x4 b0 = {__builtin_bit_cast(float, w.x << 16), __builtin_bit_cast(float, w.x & 0xffff0000u), __builtin_bit_cast(float, w.y << 16), __builtin_bit_cast(float, w.y & 0xffff0000u)};
;                         const f32x4 b1 = {__builtin_bit_cast(float, w.z << 16), __builtin_bit_cast(float, w.z & 0xffff0000u), __builtin_bit_cast(float, w.w << 16), __builtin_bit_cast(float, w.w & 0xffff0000u)};
;                         o[0] = b0 * 1.6817928305074290f + gv[bj][0] * acc[ai][bj][m][0]; o[1] = b1 * 1.6817928305074290f + gv[bj][1] * acc[ai][bj][m][1]; }
;                     else {
; #pragma unroll
;                     for (int n = 0; n < 2; ++n) { const f32x4 bs = *(const f32x4*)(ib + off + bj * 32 + n * 4); o[n] = bs * 1.6817928305074290f + gv[bj][n] * acc[ai][bj][m][n]; } }
;                     if (tobf) *(u32x4*)(vout + off + bj * 32) = pack8(o[0], o[1]);
;                     else { *(f32x4*)(ob + off + bj * 32) = o[0]; *(f32x4*)(ob + off + bj * 32 + 4) = o[1]; } }
.LBB0_981:
	s_andn2_b64 vcc, exec, s[36:37]
	s_cbranch_vccnz .LBB0_983
	s_waitcnt vmcnt(7)
	v_mov_b32_e32 v162, v238
	v_mov_b32_e32 v163, v239
	v_mov_b32_e32 v164, v240
	v_mov_b32_e32 v165, v241
	v_mov_b32_e32 v174, v242
	v_mov_b32_e32 v175, v243
	v_mov_b32_e32 v176, v244
	v_mov_b32_e32 v177, v245
	v_lshlrev_b32_e32 v251, 1, v250
	v_add_u32_e32 v251, 0xb0000, v251
	global_load_dwordx4 v[238:241], v251, s[34:35]
	global_load_dwordx4 v[242:245], v251, s[34:35] offset:16
	v_pk_mul_f32 v[164:165], v[164:165], s[86:87] op_sel_hi:[1,0]
	v_pk_mul_f32 v[162:163], v[162:163], s[86:87] op_sel_hi:[1,0]
	v_pk_fma_f32 v[168:169], v[36:37], v[152:153], v[164:165]
	v_pk_fma_f32 v[166:167], v[34:35], v[150:151], v[162:163]

; __device__ __forceinline__ u32x4 pack8(const f32x4 a, const f32x4 b) { u32x4 w; w.x = cvt_pk_bf16(a[0], a[1]); w.y = cvt_pk_bf16(a[2], a[3]); w.z = cvt_pk_bf16(b[0], b[1]); w.w = cvt_pk_bf16(b[2], b[3]); return w; }
;     __device__ __forceinline__ void operator()(const f32x4 (&acc)[2][2][4][2], const Unit& u, int wr, int wc, int fr, int fq) const {
;     ...
;                 for (int bj = 0; bj < 2; ++bj) { f32x4 o[2];
;                     if (lat && rinB) { const u32x4 w = *(const u32x4*)(rinB + off + bj * 32);
;                         const f32x4 b0 = {__builtin_bit_cast(float, w.x << 16), __builtin_bit_cast(float, w.x & 0xffff0000u), __builtin_bit_cast(float, w.y << 16), __builtin_bit_cast(float, w.y & 0xffff0000u)};
;                         const f32x4 b1 = {__builtin_bit_cast(float, w.z << 16), __builtin_bit_cast(float, w.z & 0xffff0000u), __builtin_bit_cast(float, w.w << 16), __builtin_bit_cast(float, w.w & 0xffff0000u)};
;                         o[0] = b0 * 1.6817928305074290f + gv[bj][0] * acc[ai][bj][m][0]; o[1] = b1 * 1.6817928305074290f + gv[bj][1] * acc[ai][bj][m][1]; }
;                     else {
; #pragma unroll
;                     for (int n = 0; n < 2; ++n) { const f32x4 bs = *(const f32x4*)(ib + off + bj * 32 + n * 4); o[n] = bs * 1.6817928305074290f + gv[bj][n] * acc[ai][bj][m][n]; } }
;                     if (tobf) *(u32x4*)(vout + off + bj * 32) = pack8(o[0], o[1]);
;                     else { *(f32x4*)(ob + off + bj * 32) = o[0]; *(f32x4*)(ob + off + bj * 32 + 4) = o[1]; } }
.LBB0_989:
	s_andn2_b64 vcc, exec, s[36:37]
	v_lshl_add_u64 v[196:197], v[192:193], 2, s[34:35]
	s_cbranch_vccnz .LBB0_991
	s_waitcnt vmcnt(7)
	v_mov_b32_e32 v162, v208
	v_mov_b32_e32 v163, v209
	v_mov_b32_e32 v164, v210
	v_mov_b32_e32 v165, v211
	v_mov_b32_e32 v166, v226
	v_mov_b32_e32 v167, v227
	v_mov_b32_e32 v168, v228
	v_mov_b32_e32 v169, v229
	v_lshlrev_b32_e32 v251, 1, v250
	v_add_u32_e32 v251, 0xb0000, v251
	global_load_dwordx4 v[208:211], v251, s[34:35] offset:128
	global_load_dwordx4 v[226:229], v251, s[34:35] offset:144
	v_pk_mul_f32 v[164:165], v[164:165], s[86:87] op_sel_hi:[1,0]
	v_pk_mul_f32 v[162:163], v[162:163], s[86:87] op_sel_hi:[1,0]
	v_pk_fma_f32 v[164:165], v[40:41], v[160:161], v[164:165]
	v_pk_fma_f32 v[162:163], v[38:39], v[158:159], v[162:163]

; __device__ __forceinline__ u32x4 pack8(const f32x4 a, const f32x4 b) { u32x4 w; w.x = cvt_pk_bf16(a[0], a[1]); w.y = cvt_pk_bf16(a[2], a[3]); w.z = cvt_pk_bf16(b[0], b[1]); w.w = cvt_pk_bf16(b[2], b[3]); return w; }
;     __device__ __forceinline__ void operator()(const f32x4 (&acc)[2][2][4][2], const Unit& u, int wr, int wc, int fr, int fq) const {
;     ...
;                 for (int bj = 0; bj < 2; ++bj) { f32x4 o[2];
;                     if (lat && rinB) { const u32x4 w = *(const u32x4*)(rinB + off + bj * 32);
;                         const f32x4 b0 = {__builtin_bit_cast(float, w.x << 16), __builtin_bit_cast(float, w.x & 0xffff0000u), __builtin_bit_cast(float, w.y << 16), __builtin_bit_cast(float, w.y & 0xffff0000u)};
;                         const f32x4 b1 = {__builtin_bit_cast(float, w.z << 16), __builtin_bit_cast(float, w.z & 0xffff0000u), __builtin_bit_cast(float, w.w << 16), __builtin_bit_cast(float, w.w & 0xffff0000u)};
;                         o[0] = b0 * 1.6817928305074290f + gv[bj][0] * acc[ai][bj][m][0]; o[1] = b1 * 1.6817928305074290f + gv[bj][1] * acc[ai][bj][m][1]; }
;                     else {
; #pragma unroll
;                     for (int n = 0; n < 2; ++n) { const f32x4 bs = *(const f32x4*)(ib + off + bj * 32 + n * 4); o[n] = bs * 1.6817928305074290f + gv[bj][n] * acc[ai][bj][m][n]; } }
;                     if (tobf) *(u32x4*)(vout + off + bj * 32) = pack8(o[0], o[1]);
;                     else { *(f32x4*)(ob + off + bj * 32) = o[0]; *(f32x4*)(ob + off + bj * 32 + 4) = o[1]; } }
.LBB0_997:
	s_andn2_b64 vcc, exec, s[36:37]
	s_cbranch_vccnz .LBB0_999
	s_waitcnt vmcnt(7)
	v_mov_b32_e32 v162, v230
	v_mov_b32_e32 v163, v231
	v_mov_b32_e32 v164, v232
	v_mov_b32_e32 v165, v233
	v_mov_b32_e32 v174, v234
	v_mov_b32_e32 v175, v235
	v_mov_b32_e32 v176, v236
	v_mov_b32_e32 v177, v237
	v_pk_mul_f32 v[164:165], v[164:165], s[86:87] op_sel_hi:[1,0]
	v_pk_mul_f32 v[162:163], v[162:163], s[86:87] op_sel_hi:[1,0]
	v_pk_fma_f32 v[168:169], v[20:21], v[152:153], v[164:165]
	v_pk_fma_f32 v[166:167], v[18:19], v[150:151], v[162:163]

; __device__ __forceinline__ u32x4 pack8(const f32x4 a, const f32x4 b) { u32x4 w; w.x = cvt_pk_bf16(a[0], a[1]); w.y = cvt_pk_bf16(a[2], a[3]); w.z = cvt_pk_bf16(b[0], b[1]); w.w = cvt_pk_bf16(b[2], b[3]); return w; }
;     __device__ __forceinline__ void operator()(const f32x4 (&acc)[2][2][4][2], const Unit& u, int wr, int wc, int fr, int fq) const {
;     ...
;                 for (int bj = 0; bj < 2; ++bj) { f32x4 o[2];
;                     if (lat && rinB) { const u32x4 w = *(const u32x4*)(rinB + off + bj * 32);
;                         const f32x4 b0 = {__builtin_bit_cast(float, w.x << 16), __builtin_bit_cast(float, w.x & 0xffff0000u), __builtin_bit_cast(float, w.y << 16), __builtin_bit_cast(float, w.y & 0xffff0000u)};
;                         const f32x4 b1 = {__builtin_bit_cast(float, w.z << 16), __builtin_bit_cast(float, w.z & 0xffff0000u), __builtin_bit_cast(float, w.w << 16), __builtin_bit_cast(float, w.w & 0xffff0000u)};
;                         o[0] = b0 * 1.6817928305074290f + gv[bj][0] * acc[ai][bj][m][0]; o[1] = b1 * 1.6817928305074290f + gv[bj][1] * acc[ai][bj][m][1]; }
;                     else {
; #pragma unroll
;                     for (int n = 0; n < 2; ++n) { const f32x4 bs = *(const f32x4*)(ib + off + bj * 32 + n * 4); o[n] = bs * 1.6817928305074290f + gv[bj][n] * acc[ai][bj][m][n]; } }
;                     if (tobf) *(u32x4*)(vout + off + bj * 32) = pack8(o[0], o[1]);
;                     else { *(f32x4*)(ob + off + bj * 32) = o[0]; *(f32x4*)(ob + off + bj * 32 + 4) = o[1]; } }
.LBB0_1005:
	s_andn2_b64 vcc, exec, s[36:37]
	v_lshl_add_u64 v[174:175], v[170:171], 2, s[34:35]
	s_cbranch_vccnz .LBB0_1007
	s_waitcnt vmcnt(5)
	v_mov_b32_e32 v162, v238
	v_mov_b32_e32 v163, v239
	v_mov_b32_e32 v164, v240
	v_mov_b32_e32 v165, v241
	v_mov_b32_e32 v166, v242
	v_mov_b32_e32 v167, v243
	v_mov_b32_e32 v168, v244
	v_mov_b32_e32 v169, v245
	v_pk_mul_f32 v[164:165], v[164:165], s[86:87] op_sel_hi:[1,0]
	v_pk_mul_f32 v[162:163], v[162:163], s[86:87] op_sel_hi:[1,0]
	v_pk_fma_f32 v[164:165], v[24:25], v[160:161], v[164:165]
	v_pk_fma_f32 v[162:163], v[22:23], v[158:159], v[162:163]

; __device__ __forceinline__ u32x4 pack8(const f32x4 a, const f32x4 b) { u32x4 w; w.x = cvt_pk_bf16(a[0], a[1]); w.y = cvt_pk_bf16(a[2], a[3]); w.z = cvt_pk_bf16(b[0], b[1]); w.w = cvt_pk_bf16(b[2], b[3]); return w; }
;     __device__ __forceinline__ void operator()(const f32x4 (&acc)[2][2][4][2], const Unit& u, int wr, int wc, int fr, int fq) const {
;     ...
;                 for (int bj = 0; bj < 2; ++bj) { f32x4 o[2];
;                     if (lat && rinB) { const u32x4 w = *(const u32x4*)(rinB + off + bj * 32);
;                         const f32x4 b0 = {__builtin_bit_cast(float, w.x << 16), __builtin_bit_cast(float, w.x & 0xffff0000u), __builtin_bit_cast(float, w.y << 16), __builtin_bit_cast(float, w.y & 0xffff0000u)};
;                         const f32x4 b1 = {__builtin_bit_cast(float, w.z << 16), __builtin_bit_cast(float, w.z & 0xffff0000u), __builtin_bit_cast(float, w.w << 16), __builtin_bit_cast(float, w.w & 0xffff0000u)};
;                         o[0] = b0 * 1.6817928305074290f + gv[bj][0] * acc[ai][bj][m][0]; o[1] = b1 * 1.6817928305074290f + gv[bj][1] * acc[ai][bj][m][1]; }
;                     else {
; #pragma unroll
;                     for (int n = 0; n < 2; ++n) { const f32x4 bs = *(const f32x4*)(ib + off + bj * 32 + n * 4); o[n] = bs * 1.6817928305074290f + gv[bj][n] * acc[ai][bj][m][n]; } }
;                     if (tobf) *(u32x4*)(vout + off + bj * 32) = pack8(o[0], o[1]);
;                     else { *(f32x4*)(ob + off + bj * 32) = o[0]; *(f32x4*)(ob + off + bj * 32 + 4) = o[1]; } }
.LBB0_1013:
	s_andn2_b64 vcc, exec, s[34:35]
	s_cbranch_vccnz .LBB0_1015
	s_waitcnt vmcnt(3)
	v_mov_b32_e32 v154, v208
	v_mov_b32_e32 v155, v209
	v_mov_b32_e32 v156, v210
	v_mov_b32_e32 v157, v211
	v_mov_b32_e32 v166, v226
	v_mov_b32_e32 v167, v227
	v_mov_b32_e32 v168, v228
	v_mov_b32_e32 v169, v229
	v_pk_mul_f32 v[156:157], v[156:157], s[86:87] op_sel_hi:[1,0]
	v_pk_mul_f32 v[154:155], v[154:155], s[86:87] op_sel_hi:[1,0]
	v_pk_fma_f32 v[156:157], v[8:9], v[152:153], v[156:157]
	v_pk_fma_f32 v[154:155], v[6:7], v[150:151], v[154:155]

; __device__ __forceinline__ u32x4 pack8(const f32x4 a, const f32x4 b) { u32x4 w; w.x = cvt_pk_bf16(a[0], a[1]); w.y = cvt_pk_bf16(a[2], a[3]); w.z = cvt_pk_bf16(b[0], b[1]); w.w = cvt_pk_bf16(b[2], b[3]); return w; }
;     __device__ __forceinline__ void operator()(const f32x4 (&acc)[2][2][4][2], const Unit& u, int wr, int wc, int fr, int fq) const {
;     ...
;         const float* ib = lat ? rinL : rinC - (size_t)32768 * 1024; float* ob = lat ? routL : routC - (size_t)32768 * 1024;
;         const bool tobf = lat && vout != nullptr;
; #pragma unroll
;         for (int ai = 0; ai < 2; ++ai)
; #pragma unroll
;             for (int m = 0; m < 4; ++m) { const size_t off = (size_t)(rowb + ai * HALF + m * 16) * 1024 + col0;
; #pragma unroll
;                 for (int bj = 0; bj < 2; ++bj) { f32x4 o[2];
;                     if (lat && rinB) { const u32x4 w = *(const u32x4*)(rinB + off + bj * 32);
;                         const f32x4 b0 = {__builtin_bit_cast(float, w.x << 16), __builtin_bit_cast(float, w.x & 0xffff0000u), __builtin_bit_cast(float, w.y << 16), __builtin_bit_cast(float, w.y & 0xffff0000u)};
;                         const f32x4 b1 = {__builtin_bit_cast(float, w.z << 16), __builtin_bit_cast(float, w.z & 0xffff0000u), __builtin_bit_cast(float, w.w << 16), __builtin_bit_cast(float, w.w & 0xffff0000u)};
;                         o[0] = b0 * 1.6817928305074290f + gv[bj][0] * acc[ai][bj][m][0]; o[1] = b1 * 1.6817928305074290f + gv[bj][1] * acc[ai][bj][m][1]; }
;                     else {
; #pragma unroll
;                     for (int n = 0; n < 2; ++n) { const f32x4 bs = *(const f32x4*)(ib + off + bj * 32 + n * 4); o[n] = bs * 1.6817928305074290f + gv[bj][n] * acc[ai][bj][m][n]; } }
;                     if (tobf) *(u32x4*)(vout + off + bj * 32) = pack8(o[0], o[1]);
;                     else { *(f32x4*)(ob + off + bj * 32) = o[0]; *(f32x4*)(ob + off + bj * 32 + 4) = o[1]; } }
.LBB0_1046:
	s_andn2_b64 vcc, exec, s[30:31]
	v_lshl_add_u64 v[188:189], v[184:185], 2, s[28:29]
	s_cbranch_vccnz .LBB0_1048
	v_lshlrev_b32_e32 v251, 1, v250
	global_load_dwordx4 v[208:211], v251, s[28:29]
	global_load_dwordx4 v[226:229], v251, s[28:29] offset:16
	v_lshlrev_b32_e32 v251, 1, v250
	global_load_dwordx4 v[230:233], v251, s[28:29] offset:128
	global_load_dwordx4 v[234:237], v251, s[28:29] offset:144
	v_lshlrev_b32_e32 v251, 1, v250
	v_add_u32_e32 v251, 0x10000, v251
	global_load_dwordx4 v[238:241], v251, s[28:29]
	global_load_dwordx4 v[242:245], v251, s[28:29] offset:16
	s_waitcnt vmcnt(4)
	v_mov_b32_e32 v162, v208
	v_mov_b32_e32 v163, v209
	v_mov_b32_e32 v164, v210
	v_mov_b32_e32 v165, v211
	v_mov_b32_e32 v166, v226
	v_mov_b32_e32 v167, v227
	v_mov_b32_e32 v168, v228
	v_mov_b32_e32 v169, v229
	v_lshlrev_b32_e32 v251, 1, v250
	v_add_u32_e32 v251, 0x10000, v251
	global_load_dwordx4 v[208:211], v251, s[28:29] offset:128
	global_load_dwordx4 v[226:229], v251, s[28:29] offset:144
	v_pk_mul_f32 v[164:165], v[164:165], s[86:87] op_sel_hi:[1,0]
	v_pk_mul_f32 v[162:163], v[162:163], s[86:87] op_sel_hi:[1,0]
	v_pk_fma_f32 v[164:165], v[160:161], v[72:73], v[164:165]
	v_pk_fma_f32 v[162:163], v[158:159], v[70:71], v[162:163]

; __device__ __forceinline__ u32x4 pack8(const f32x4 a, const f32x4 b) { u32x4 w; w.x = cvt_pk_bf16(a[0], a[1]); w.y = cvt_pk_bf16(a[2], a[3]); w.z = cvt_pk_bf16(b[0], b[1]); w.w = cvt_pk_bf16(b[2], b[3]); return w; }
;     __device__ __forceinline__ void operator()(const f32x4 (&acc)[2][2][4][2], const Unit& u, int wr, int wc, int fr, int fq) const {
;     ...
;                 for (int bj = 0; bj < 2; ++bj) { f32x4 o[2];
;                     if (lat && rinB) { const u32x4 w = *(const u32x4*)(rinB + off + bj * 32);
;                         const f32x4 b0 = {__builtin_bit_cast(float, w.x << 16), __builtin_bit_cast(float, w.x & 0xffff0000u), __builtin_bit_cast(float, w.y << 16), __builtin_bit_cast(float, w.y & 0xffff0000u)};
;                         const f32x4 b1 = {__builtin_bit_cast(float, w.z << 16), __builtin_bit_cast(float, w.z & 0xffff0000u), __builtin_bit_cast(float, w.w << 16), __builtin_bit_cast(float, w.w & 0xffff0000u)};
;                         o[0] = b0 * 1.6817928305074290f + gv[bj][0] * acc[ai][bj][m][0]; o[1] = b1 * 1.6817928305074290f + gv[bj][1] * acc[ai][bj][m][1]; }
;                     else {
; #pragma unroll
;                     for (int n = 0; n < 2; ++n) { const f32x4 bs = *(const f32x4*)(ib + off + bj * 32 + n * 4); o[n] = bs * 1.6817928305074290f + gv[bj][n] * acc[ai][bj][m][n]; } }
;                     if (tobf) *(u32x4*)(vout + off + bj * 32) = pack8(o[0], o[1]);
;                     else { *(f32x4*)(ob + off + bj * 32) = o[0]; *(f32x4*)(ob + off + bj * 32 + 4) = o[1]; } }
.LBB0_1054:
	s_andn2_b64 vcc, exec, s[30:31]
	s_cbranch_vccnz .LBB0_1056
	s_waitcnt vmcnt(5)
	v_mov_b32_e32 v154, v230
	v_mov_b32_e32 v155, v231
	v_mov_b32_e32 v156, v232
	v_mov_b32_e32 v157, v233
	v_mov_b32_e32 v166, v234
	v_mov_b32_e32 v167, v235
	v_mov_b32_e32 v168, v236
	v_mov_b32_e32 v169, v237
	v_lshlrev_b32_e32 v251, 1, v250
	v_add_u32_e32 v251, 0x20000, v251
	global_load_dwordx4 v[230:233], v251, s[28:29]
	global_load_dwordx4 v[234:237], v251, s[28:29] offset:16
	v_pk_mul_f32 v[156:157], v[156:157], s[86:87] op_sel_hi:[1,0]
	v_pk_mul_f32 v[154:155], v[154:155], s[86:87] op_sel_hi:[1,0]
	v_pk_fma_f32 v[156:157], v[152:153], v[56:57], v[156:157]
	v_pk_fma_f32 v[154:155], v[150:151], v[54:55], v[154:155]

; __device__ __forceinline__ u32x4 pack8(const f32x4 a, const f32x4 b) { u32x4 w; w.x = cvt_pk_bf16(a[0], a[1]); w.y = cvt_pk_bf16(a[2], a[3]); w.z = cvt_pk_bf16(b[0], b[1]); w.w = cvt_pk_bf16(b[2], b[3]); return w; }
;     __device__ __forceinline__ void operator()(const f32x4 (&acc)[2][2][4][2], const Unit& u, int wr, int wc, int fr, int fq) const {
;     ...
;                 for (int bj = 0; bj < 2; ++bj) { f32x4 o[2];
;                     if (lat && rinB) { const u32x4 w = *(const u32x4*)(rinB + off + bj * 32);
;                         const f32x4 b0 = {__builtin_bit_cast(float, w.x << 16), __builtin_bit_cast(float, w.x & 0xffff0000u), __builtin_bit_cast(float, w.y << 16), __builtin_bit_cast(float, w.y & 0xffff0000u)};
;                         const f32x4 b1 = {__builtin_bit_cast(float, w.z << 16), __builtin_bit_cast(float, w.z & 0xffff0000u), __builtin_bit_cast(float, w.w << 16), __builtin_bit_cast(float, w.w & 0xffff0000u)};
;                         o[0] = b0 * 1.6817928305074290f + gv[bj][0] * acc[ai][bj][m][0]; o[1] = b1 * 1.6817928305074290f + gv[bj][1] * acc[ai][bj][m][1]; }
;                     else {
; #pragma unroll
;                     for (int n = 0; n < 2; ++n) { const f32x4 bs = *(const f32x4*)(ib + off + bj * 32 + n * 4); o[n] = bs * 1.6817928305074290f + gv[bj][n] * acc[ai][bj][m][n]; } }
;                     if (tobf) *(u32x4*)(vout + off + bj * 32) = pack8(o[0], o[1]);
;                     else { *(f32x4*)(ob + off + bj * 32) = o[0]; *(f32x4*)(ob + off + bj * 32 + 4) = o[1]; } }
.LBB0_1062:
	s_andn2_b64 vcc, exec, s[30:31]
	v_lshl_add_u64 v[158:159], v[154:155], 2, s[28:29]
	s_cbranch_vccnz .LBB0_1064
	s_waitcnt vmcnt(6)
	v_mov_b32_e32 v146, v238
	v_mov_b32_e32 v147, v239
	v_mov_b32_e32 v148, v240
	v_mov_b32_e32 v149, v241
	v_mov_b32_e32 v150, v242
	v_mov_b32_e32 v151, v243
	v_mov_b32_e32 v152, v244
	v_mov_b32_e32 v153, v245
	v_lshlrev_b32_e32 v251, 1, v250
	v_add_u32_e32 v251, 0x20000, v251
	global_load_dwordx4 v[238:241], v251, s[28:29] offset:128
	global_load_dwordx4 v[242:245], v251, s[28:29] offset:144
	v_pk_mul_f32 v[148:149], v[148:149], s[86:87] op_sel_hi:[1,0]
	v_pk_mul_f32 v[146:147], v[146:147], s[86:87] op_sel_hi:[1,0]
	v_pk_fma_f32 v[148:149], v[144:145], v[72:73], v[148:149]
	v_pk_fma_f32 v[146:147], v[142:143], v[70:71], v[146:147]

; __device__ __forceinline__ u32x4 pack8(const f32x4 a, const f32x4 b) { u32x4 w; w.x = cvt_pk_bf16(a[0], a[1]); w.y = cvt_pk_bf16(a[2], a[3]); w.z = cvt_pk_bf16(b[0], b[1]); w.w = cvt_pk_bf16(b[2], b[3]); return w; }
;     __device__ __forceinline__ void operator()(const f32x4 (&acc)[2][2][4][2], const Unit& u, int wr, int wc, int fr, int fq) const {
;     ...
;                 for (int bj = 0; bj < 2; ++bj) { f32x4 o[2];
;                     if (lat && rinB) { const u32x4 w = *(const u32x4*)(rinB + off + bj * 32);
;                         const f32x4 b0 = {__builtin_bit_cast(float, w.x << 16), __builtin_bit_cast(float, w.x & 0xffff0000u), __builtin_bit_cast(float, w.y << 16), __builtin_bit_cast(float, w.y & 0xffff0000u)};
;                         const f32x4 b1 = {__builtin_bit_cast(float, w.z << 16), __builtin_bit_cast(float, w.z & 0xffff0000u), __builtin_bit_cast(float, w.w << 16), __builtin_bit_cast(float, w.w & 0xffff0000u)};
;                         o[0] = b0 * 1.6817928305074290f + gv[bj][0] * acc[ai][bj][m][0]; o[1] = b1 * 1.6817928305074290f + gv[bj][1] * acc[ai][bj][m][1]; }
;                     else {
; #pragma unroll
;                     for (int n = 0; n < 2; ++n) { const f32x4 bs = *(const f32x4*)(ib + off + bj * 32 + n * 4); o[n] = bs * 1.6817928305074290f + gv[bj][n] * acc[ai][bj][m][n]; } }
;                     if (tobf) *(u32x4*)(vout + off + bj * 32) = pack8(o[0], o[1]);
;                     else { *(f32x4*)(ob + off + bj * 32) = o[0]; *(f32x4*)(ob + off + bj * 32 + 4) = o[1]; } }
.LBB0_1070:
	s_andn2_b64 vcc, exec, s[30:31]
	s_cbranch_vccnz .LBB0_1072
	s_waitcnt vmcnt(7)
	v_mov_b32_e32 v138, v208
	v_mov_b32_e32 v139, v209
	v_mov_b32_e32 v140, v210
	v_mov_b32_e32 v141, v211
	v_mov_b32_e32 v142, v226
	v_mov_b32_e32 v143, v227
	v_mov_b32_e32 v144, v228
	v_mov_b32_e32 v145, v229
	v_lshlrev_b32_e32 v251, 1, v250
	v_add_u32_e32 v251, 0x30000, v251
	global_load_dwordx4 v[208:211], v251, s[28:29]
	global_load_dwordx4 v[226:229], v251, s[28:29] offset:16
	v_pk_mul_f32 v[140:141], v[140:141], s[86:87] op_sel_hi:[1,0]
	v_pk_mul_f32 v[138:139], v[138:139], s[86:87] op_sel_hi:[1,0]
	v_pk_fma_f32 v[140:141], v[136:137], v[56:57], v[140:141]
	v_pk_fma_f32 v[138:139], v[134:135], v[54:55], v[138:139]

; __device__ __forceinline__ u32x4 pack8(const f32x4 a, const f32x4 b) { u32x4 w; w.x = cvt_pk_bf16(a[0], a[1]); w.y = cvt_pk_bf16(a[2], a[3]); w.z = cvt_pk_bf16(b[0], b[1]); w.w = cvt_pk_bf16(b[2], b[3]); return w; }
;     __device__ __forceinline__ void operator()(const f32x4 (&acc)[2][2][4][2], const Unit& u, int wr, int wc, int fr, int fq) const {
;     ...
;                 for (int bj = 0; bj < 2; ++bj) { f32x4 o[2];
;                     if (lat && rinB) { const u32x4 w = *(const u32x4*)(rinB + off + bj * 32);
;                         const f32x4 b0 = {__builtin_bit_cast(float, w.x << 16), __builtin_bit_cast(float, w.x & 0xffff0000u), __builtin_bit_cast(float, w.y << 16), __builtin_bit_cast(float, w.y & 0xffff0000u)};
;                         const f32x4 b1 = {__builtin_bit_cast(float, w.z << 16), __builtin_bit_cast(float, w.z & 0xffff0000u), __builtin_bit_cast(float, w.w << 16), __builtin_bit_cast(float, w.w & 0xffff0000u)};
;                         o[0] = b0 * 1.6817928305074290f + gv[bj][0] * acc[ai][bj][m][0]; o[1] = b1 * 1.6817928305074290f + gv[bj][1] * acc[ai][bj][m][1]; }
;                     else {
; #pragma unroll
;                     for (int n = 0; n < 2; ++n) { const f32x4 bs = *(const f32x4*)(ib + off + bj * 32 + n * 4); o[n] = bs * 1.6817928305074290f + gv[bj][n] * acc[ai][bj][m][n]; } }
;                     if (tobf) *(u32x4*)(vout + off + bj * 32) = pack8(o[0], o[1]);
;                     else { *(f32x4*)(ob + off + bj * 32) = o[0]; *(f32x4*)(ob + off + bj * 32 + 4) = o[1]; } }
.LBB0_1078:
	s_andn2_b64 vcc, exec, s[30:31]
	v_lshl_add_u64 v[142:143], v[138:139], 2, s[28:29]
	s_cbranch_vccnz .LBB0_1080
	s_waitcnt vmcnt(7)
	v_mov_b32_e32 v130, v230
	v_mov_b32_e32 v131, v231
	v_mov_b32_e32 v132, v232
	v_mov_b32_e32 v133, v233
	v_mov_b32_e32 v134, v234
	v_mov_b32_e32 v135, v235
	v_mov_b32_e32 v136, v236
	v_mov_b32_e32 v137, v237
	v_lshlrev_b32_e32 v251, 1, v250
	v_add_u32_e32 v251, 0x30000, v251
	global_load_dwordx4 v[230:233], v251, s[28:29] offset:128
	global_load_dwordx4 v[234:237], v251, s[28:29] offset:144
	v_pk_mul_f32 v[132:133], v[132:133], s[86:87] op_sel_hi:[1,0]
	v_pk_mul_f32 v[130:131], v[130:131], s[86:87] op_sel_hi:[1,0]
	v_pk_fma_f32 v[132:133], v[112:113], v[72:73], v[132:133]
	v_pk_fma_f32 v[130:131], v[110:111], v[70:71], v[130:131]

; __device__ __forceinline__ u32x4 pack8(const f32x4 a, const f32x4 b) { u32x4 w; w.x = cvt_pk_bf16(a[0], a[1]); w.y = cvt_pk_bf16(a[2], a[3]); w.z = cvt_pk_bf16(b[0], b[1]); w.w = cvt_pk_bf16(b[2], b[3]); return w; }
;     __device__ __forceinline__ void operator()(const f32x4 (&acc)[2][2][4][2], const Unit& u, int wr, int wc, int fr, int fq) const {
;     ...
;                 for (int bj = 0; bj < 2; ++bj) { f32x4 o[2];
;                     if (lat && rinB) { const u32x4 w = *(const u32x4*)(rinB + off + bj * 32);
;                         const f32x4 b0 = {__builtin_bit_cast(float, w.x << 16), __builtin_bit_cast(float, w.x & 0xffff0000u), __builtin_bit_cast(float, w.y << 16), __builtin_bit_cast(float, w.y & 0xffff0000u)};
;                         const f32x4 b1 = {__builtin_bit_cast(float, w.z << 16), __builtin_bit_cast(float, w.z & 0xffff0000u), __builtin_bit_cast(float, w.w << 16), __builtin_bit_cast(float, w.w & 0xffff0000u)};
;                         o[0] = b0 * 1.6817928305074290f + gv[bj][0] * acc[ai][bj][m][0]; o[1] = b1 * 1.6817928305074290f + gv[bj][1] * acc[ai][bj][m][1]; }
;                     else {
; #pragma unroll
;                     for (int n = 0; n < 2; ++n) { const f32x4 bs = *(const f32x4*)(ib + off + bj * 32 + n * 4); o[n] = bs * 1.6817928305074290f + gv[bj][n] * acc[ai][bj][m][n]; } }
;                     if (tobf) *(u32x4*)(vout + off + bj * 32) = pack8(o[0], o[1]);
;                     else { *(f32x4*)(ob + off + bj * 32) = o[0]; *(f32x4*)(ob + off + bj * 32 + 4) = o[1]; } }
.LBB0_1086:
	s_andn2_b64 vcc, exec, s[30:31]
	s_cbranch_vccnz .LBB0_1088
	s_waitcnt vmcnt(7)
	v_mov_b32_e32 v106, v238
	v_mov_b32_e32 v107, v239
	v_mov_b32_e32 v108, v240
	v_mov_b32_e32 v109, v241
	v_mov_b32_e32 v134, v242
	v_mov_b32_e32 v135, v243
	v_mov_b32_e32 v136, v244
	v_mov_b32_e32 v137, v245
	v_lshlrev_b32_e32 v251, 1, v250
	v_add_u32_e32 v251, 0x80000, v251
	global_load_dwordx4 v[238:241], v251, s[28:29]
	global_load_dwordx4 v[242:245], v251, s[28:29] offset:16
	v_pk_mul_f32 v[108:109], v[108:109], s[86:87] op_sel_hi:[1,0]
	v_pk_mul_f32 v[106:107], v[106:107], s[86:87] op_sel_hi:[1,0]
	v_pk_fma_f32 v[108:109], v[104:105], v[56:57], v[108:109]
	v_pk_fma_f32 v[106:107], v[102:103], v[54:55], v[106:107]

; __device__ __forceinline__ u32x4 pack8(const f32x4 a, const f32x4 b) { u32x4 w; w.x = cvt_pk_bf16(a[0], a[1]); w.y = cvt_pk_bf16(a[2], a[3]); w.z = cvt_pk_bf16(b[0], b[1]); w.w = cvt_pk_bf16(b[2], b[3]); return w; }
;     __device__ __forceinline__ void operator()(const f32x4 (&acc)[2][2][4][2], const Unit& u, int wr, int wc, int fr, int fq) const {
;     ...
;                 for (int bj = 0; bj < 2; ++bj) { f32x4 o[2];
;                     if (lat && rinB) { const u32x4 w = *(const u32x4*)(rinB + off + bj * 32);
;                         const f32x4 b0 = {__builtin_bit_cast(float, w.x << 16), __builtin_bit_cast(float, w.x & 0xffff0000u), __builtin_bit_cast(float, w.y << 16), __builtin_bit_cast(float, w.y & 0xffff0000u)};
;                         const f32x4 b1 = {__builtin_bit_cast(float, w.z << 16), __builtin_bit_cast(float, w.z & 0xffff0000u), __builtin_bit_cast(float, w.w << 16), __builtin_bit_cast(float, w.w & 0xffff0000u)};
;                         o[0] = b0 * 1.6817928305074290f + gv[bj][0] * acc[ai][bj][m][0]; o[1] = b1 * 1.6817928305074290f + gv[bj][1] * acc[ai][bj][m][1]; }
;                     else {
; #pragma unroll
;                     for (int n = 0; n < 2; ++n) { const f32x4 bs = *(const f32x4*)(ib + off + bj * 32 + n * 4); o[n] = bs * 1.6817928305074290f + gv[bj][n] * acc[ai][bj][m][n]; } }
;                     if (tobf) *(u32x4*)(vout + off + bj * 32) = pack8(o[0], o[1]);
;                     else { *(f32x4*)(ob + off + bj * 32) = o[0]; *(f32x4*)(ob + off + bj * 32 + 4) = o[1]; } }
.LBB0_1094:
	s_andn2_b64 vcc, exec, s[30:31]
	v_lshl_add_u64 v[110:111], v[106:107], 2, s[28:29]
	s_cbranch_vccnz .LBB0_1096
	s_waitcnt vmcnt(7)
	v_mov_b32_e32 v98, v208
	v_mov_b32_e32 v99, v209
	v_mov_b32_e32 v100, v210
	v_mov_b32_e32 v101, v211
	v_mov_b32_e32 v102, v226
	v_mov_b32_e32 v103, v227
	v_mov_b32_e32 v104, v228
	v_mov_b32_e32 v105, v229
	v_lshlrev_b32_e32 v251, 1, v250
	v_add_u32_e32 v251, 0x80000, v251
	global_load_dwordx4 v[208:211], v251, s[28:29] offset:128
	global_load_dwordx4 v[226:229], v251, s[28:29] offset:144
	v_pk_mul_f32 v[100:101], v[100:101], s[86:87] op_sel_hi:[1,0]
	v_pk_mul_f32 v[98:99], v[98:99], s[86:87] op_sel_hi:[1,0]
	v_pk_fma_f32 v[100:101], v[96:97], v[72:73], v[100:101]
	v_pk_fma_f32 v[98:99], v[94:95], v[70:71], v[98:99]

; __device__ __forceinline__ u32x4 pack8(const f32x4 a, const f32x4 b) { u32x4 w; w.x = cvt_pk_bf16(a[0], a[1]); w.y = cvt_pk_bf16(a[2], a[3]); w.z = cvt_pk_bf16(b[0], b[1]); w.w = cvt_pk_bf16(b[2], b[3]); return w; }
;     __device__ __forceinline__ void operator()(const f32x4 (&acc)[2][2][4][2], const Unit& u, int wr, int wc, int fr, int fq) const {
;     ...
;                 for (int bj = 0; bj < 2; ++bj) { f32x4 o[2];
;                     if (lat && rinB) { const u32x4 w = *(const u32x4*)(rinB + off + bj * 32);
;                         const f32x4 b0 = {__builtin_bit_cast(float, w.x << 16), __builtin_bit_cast(float, w.x & 0xffff0000u), __builtin_bit_cast(float, w.y << 16), __builtin_bit_cast(float, w.y & 0xffff0000u)};
;                         const f32x4 b1 = {__builtin_bit_cast(float, w.z << 16), __builtin_bit_cast(float, w.z & 0xffff0000u), __builtin_bit_cast(float, w.w << 16), __builtin_bit_cast(float, w.w & 0xffff0000u)};
;                         o[0] = b0 * 1.6817928305074290f + gv[bj][0] * acc[ai][bj][m][0]; o[1] = b1 * 1.6817928305074290f + gv[bj][1] * acc[ai][bj][m][1]; }
;                     else {
; #pragma unroll
;                     for (int n = 0; n < 2; ++n) { const f32x4 bs = *(const f32x4*)(ib + off + bj * 32 + n * 4); o[n] = bs * 1.6817928305074290f + gv[bj][n] * acc[ai][bj][m][n]; } }
;                     if (tobf) *(u32x4*)(vout + off + bj * 32) = pack8(o[0], o[1]);
;                     else { *(f32x4*)(ob + off + bj * 32) = o[0]; *(f32x4*)(ob + off + bj * 32 + 4) = o[1]; } }
.LBB0_1102:
	s_andn2_b64 vcc, exec, s[30:31]
	s_cbranch_vccnz .LBB0_1104
	s_waitcnt vmcnt(7)
	v_mov_b32_e32 v90, v230
	v_mov_b32_e32 v91, v231
	v_mov_b32_e32 v92, v232
	v_mov_b32_e32 v93, v233
	v_mov_b32_e32 v102, v234
	v_mov_b32_e32 v103, v235
	v_mov_b32_e32 v104, v236
	v_mov_b32_e32 v105, v237
	v_lshlrev_b32_e32 v251, 1, v250
	v_add_u32_e32 v251, 0x90000, v251
	global_load_dwordx4 v[230:233], v251, s[28:29]
	global_load_dwordx4 v[234:237], v251, s[28:29] offset:16
	v_pk_mul_f32 v[92:93], v[92:93], s[86:87] op_sel_hi:[1,0]
	v_pk_mul_f32 v[90:91], v[90:91], s[86:87] op_sel_hi:[1,0]
	v_pk_fma_f32 v[92:93], v[88:89], v[56:57], v[92:93]
	v_pk_fma_f32 v[90:91], v[86:87], v[54:55], v[90:91]

; __device__ __forceinline__ u32x4 pack8(const f32x4 a, const f32x4 b) { u32x4 w; w.x = cvt_pk_bf16(a[0], a[1]); w.y = cvt_pk_bf16(a[2], a[3]); w.z = cvt_pk_bf16(b[0], b[1]); w.w = cvt_pk_bf16(b[2], b[3]); return w; }
;     __device__ __forceinline__ void operator()(const f32x4 (&acc)[2][2][4][2], const Unit& u, int wr, int wc, int fr, int fq) const {
;     ...
;                 for (int bj = 0; bj < 2; ++bj) { f32x4 o[2];
;                     if (lat && rinB) { const u32x4 w = *(const u32x4*)(rinB + off + bj * 32);
;                         const f32x4 b0 = {__builtin_bit_cast(float, w.x << 16), __builtin_bit_cast(float, w.x & 0xffff0000u), __builtin_bit_cast(float, w.y << 16), __builtin_bit_cast(float, w.y & 0xffff0000u)};
;                         const f32x4 b1 = {__builtin_bit_cast(float, w.z << 16), __builtin_bit_cast(float, w.z & 0xffff0000u), __builtin_bit_cast(float, w.w << 16), __builtin_bit_cast(float, w.w & 0xffff0000u)};
;                         o[0] = b0 * 1.6817928305074290f + gv[bj][0] * acc[ai][bj][m][0]; o[1] = b1 * 1.6817928305074290f + gv[bj][1] * acc[ai][bj][m][1]; }
;                     else {
; #pragma unroll
;                     for (int n = 0; n < 2; ++n) { const f32x4 bs = *(const f32x4*)(ib + off + bj * 32 + n * 4); o[n] = bs * 1.6817928305074290f + gv[bj][n] * acc[ai][bj][m][n]; } }
;                     if (tobf) *(u32x4*)(vout + off + bj * 32) = pack8(o[0], o[1]);
;                     else { *(f32x4*)(ob + off + bj * 32) = o[0]; *(f32x4*)(ob + off + bj * 32 + 4) = o[1]; } }
.LBB0_1110:
	s_andn2_b64 vcc, exec, s[30:31]
	v_lshl_add_u64 v[94:95], v[90:91], 2, s[28:29]
	s_cbranch_vccnz .LBB0_1112
	s_waitcnt vmcnt(7)
	v_mov_b32_e32 v82, v238
	v_mov_b32_e32 v83, v239
	v_mov_b32_e32 v84, v240
	v_mov_b32_e32 v85, v241
	v_mov_b32_e32 v86, v242
	v_mov_b32_e32 v87, v243
	v_mov_b32_e32 v88, v244
	v_mov_b32_e32 v89, v245
	v_lshlrev_b32_e32 v251, 1, v250
	v_add_u32_e32 v251, 0x90000, v251
	global_load_dwordx4 v[238:241], v251, s[28:29] offset:128
	global_load_dwordx4 v[242:245], v251, s[28:29] offset:144
	v_pk_mul_f32 v[84:85], v[84:85], s[86:87] op_sel_hi:[1,0]
	v_pk_mul_f32 v[82:83], v[82:83], s[86:87] op_sel_hi:[1,0]
	v_pk_fma_f32 v[84:85], v[80:81], v[72:73], v[84:85]
	v_pk_fma_f32 v[82:83], v[78:79], v[70:71], v[82:83]

; __device__ __forceinline__ u32x4 pack8(const f32x4 a, const f32x4 b) { u32x4 w; w.x = cvt_pk_bf16(a[0], a[1]); w.y = cvt_pk_bf16(a[2], a[3]); w.z = cvt_pk_bf16(b[0], b[1]); w.w = cvt_pk_bf16(b[2], b[3]); return w; }
;     __device__ __forceinline__ void operator()(const f32x4 (&acc)[2][2][4][2], const Unit& u, int wr, int wc, int fr, int fq) const {
;     ...
;                 for (int bj = 0; bj < 2; ++bj) { f32x4 o[2];
;                     if (lat && rinB) { const u32x4 w = *(const u32x4*)(rinB + off + bj * 32);
;                         const f32x4 b0 = {__builtin_bit_cast(float, w.x << 16), __builtin_bit_cast(float, w.x & 0xffff0000u), __builtin_bit_cast(float, w.y << 16), __builtin_bit_cast(float, w.y & 0xffff0000u)};
;                         const f32x4 b1 = {__builtin_bit_cast(float, w.z << 16), __builtin_bit_cast(float, w.z & 0xffff0000u), __builtin_bit_cast(float, w.w << 16), __builtin_bit_cast(float, w.w & 0xffff0000u)};
;                         o[0] = b0 * 1.6817928305074290f + gv[bj][0] * acc[ai][bj][m][0]; o[1] = b1 * 1.6817928305074290f + gv[bj][1] * acc[ai][bj][m][1]; }
;                     else {
; #pragma unroll
;                     for (int n = 0; n < 2; ++n) { const f32x4 bs = *(const f32x4*)(ib + off + bj * 32 + n * 4); o[n] = bs * 1.6817928305074290f + gv[bj][n] * acc[ai][bj][m][n]; } }
;                     if (tobf) *(u32x4*)(vout + off + bj * 32) = pack8(o[0], o[1]);
;                     else { *(f32x4*)(ob + off + bj * 32) = o[0]; *(f32x4*)(ob + off + bj * 32 + 4) = o[1]; } }
.LBB0_1118:
	s_andn2_b64 vcc, exec, s[30:31]
	s_cbranch_vccnz .LBB0_1120
	s_waitcnt vmcnt(7)
	v_mov_b32_e32 v74, v208
	v_mov_b32_e32 v75, v209
	v_mov_b32_e32 v76, v210
	v_mov_b32_e32 v77, v211
	v_mov_b32_e32 v86, v226
	v_mov_b32_e32 v87, v227
	v_mov_b32_e32 v88, v228
	v_mov_b32_e32 v89, v229
	v_lshlrev_b32_e32 v251, 1, v250
	v_add_u32_e32 v251, 0xa0000, v251
	global_load_dwordx4 v[208:211], v251, s[28:29]
	global_load_dwordx4 v[226:229], v251, s[28:29] offset:16
	v_pk_mul_f32 v[76:77], v[76:77], s[86:87] op_sel_hi:[1,0]
	v_pk_mul_f32 v[74:75], v[74:75], s[86:87] op_sel_hi:[1,0]
	v_pk_fma_f32 v[76:77], v[64:65], v[56:57], v[76:77]
	v_pk_fma_f32 v[74:75], v[62:63], v[54:55], v[74:75]

; __device__ __forceinline__ u32x4 pack8(const f32x4 a, const f32x4 b) { u32x4 w; w.x = cvt_pk_bf16(a[0], a[1]); w.y = cvt_pk_bf16(a[2], a[3]); w.z = cvt_pk_bf16(b[0], b[1]); w.w = cvt_pk_bf16(b[2], b[3]); return w; }
;     __device__ __forceinline__ void operator()(const f32x4 (&acc)[2][2][4][2], const Unit& u, int wr, int wc, int fr, int fq) const {
;     ...
;                 for (int bj = 0; bj < 2; ++bj) { f32x4 o[2];
;                     if (lat && rinB) { const u32x4 w = *(const u32x4*)(rinB + off + bj * 32);
;                         const f32x4 b0 = {__builtin_bit_cast(float, w.x << 16), __builtin_bit_cast(float, w.x & 0xffff0000u), __builtin_bit_cast(float, w.y << 16), __builtin_bit_cast(float, w.y & 0xffff0000u)};
;                         const f32x4 b1 = {__builtin_bit_cast(float, w.z << 16), __builtin_bit_cast(float, w.z & 0xffff0000u), __builtin_bit_cast(float, w.w << 16), __builtin_bit_cast(float, w.w & 0xffff0000u)};
;                         o[0] = b0 * 1.6817928305074290f + gv[bj][0] * acc[ai][bj][m][0]; o[1] = b1 * 1.6817928305074290f + gv[bj][1] * acc[ai][bj][m][1]; }
;                     else {
; #pragma unroll
;                     for (int n = 0; n < 2; ++n) { const f32x4 bs = *(const f32x4*)(ib + off + bj * 32 + n * 4); o[n] = bs * 1.6817928305074290f + gv[bj][n] * acc[ai][bj][m][n]; } }
;                     if (tobf) *(u32x4*)(vout + off + bj * 32) = pack8(o[0], o[1]);
;                     else { *(f32x4*)(ob + off + bj * 32) = o[0]; *(f32x4*)(ob + off + bj * 32 + 4) = o[1]; } }
.LBB0_1126:
	s_andn2_b64 vcc, exec, s[30:31]
	v_lshl_add_u64 v[78:79], v[74:75], 2, s[28:29]
	s_cbranch_vccnz .LBB0_1128
	s_waitcnt vmcnt(7)
	v_mov_b32_e32 v58, v230
	v_mov_b32_e32 v59, v231
	v_mov_b32_e32 v60, v232
	v_mov_b32_e32 v61, v233
	v_mov_b32_e32 v62, v234
	v_mov_b32_e32 v63, v235
	v_mov_b32_e32 v64, v236
	v_mov_b32_e32 v65, v237
	v_lshlrev_b32_e32 v251, 1, v250
	v_add_u32_e32 v251, 0xa0000, v251
	global_load_dwordx4 v[230:233], v251, s[28:29] offset:128
	global_load_dwordx4 v[234:237], v251, s[28:29] offset:144
	v_pk_mul_f32 v[60:61], v[60:61], s[86:87] op_sel_hi:[1,0]
	v_pk_mul_f32 v[58:59], v[58:59], s[86:87] op_sel_hi:[1,0]
	v_pk_fma_f32 v[60:61], v[48:49], v[72:73], v[60:61]
	v_pk_fma_f32 v[58:59], v[46:47], v[70:71], v[58:59]

; __device__ __forceinline__ u32x4 pack8(const f32x4 a, const f32x4 b) { u32x4 w; w.x = cvt_pk_bf16(a[0], a[1]); w.y = cvt_pk_bf16(a[2], a[3]); w.z = cvt_pk_bf16(b[0], b[1]); w.w = cvt_pk_bf16(b[2], b[3]); return w; }
;     __device__ __forceinline__ void operator()(const f32x4 (&acc)[2][2][4][2], const Unit& u, int wr, int wc, int fr, int fq) const {
;     ...
;                 for (int bj = 0; bj < 2; ++bj) { f32x4 o[2];
;                     if (lat && rinB) { const u32x4 w = *(const u32x4*)(rinB + off + bj * 32);
;                         const f32x4 b0 = {__builtin_bit_cast(float, w.x << 16), __builtin_bit_cast(float, w.x & 0xffff0000u), __builtin_bit_cast(float, w.y << 16), __builtin_bit_cast(float, w.y & 0xffff0000u)};
;                         const f32x4 b1 = {__builtin_bit_cast(float, w.z << 16), __builtin_bit_cast(float, w.z & 0xffff0000u), __builtin_bit_cast(float, w.w << 16), __builtin_bit_cast(float, w.w & 0xffff0000u)};
;                         o[0] = b0 * 1.6817928305074290f + gv[bj][0] * acc[ai][bj][m][0]; o[1] = b1 * 1.6817928305074290f + gv[bj][1] * acc[ai][bj][m][1]; }
;                     else {
; #pragma unroll
;                     for (int n = 0; n < 2; ++n) { const f32x4 bs = *(const f32x4*)(ib + off + bj * 32 + n * 4); o[n] = bs * 1.6817928305074290f + gv[bj][n] * acc[ai][bj][m][n]; } }
;                     if (tobf) *(u32x4*)(vout + off + bj * 32) = pack8(o[0], o[1]);
;                     else { *(f32x4*)(ob + off + bj * 32) = o[0]; *(f32x4*)(ob + off + bj * 32 + 4) = o[1]; } }
.LBB0_1134:
	s_andn2_b64 vcc, exec, s[30:31]
	s_cbranch_vccnz .LBB0_1136
	s_waitcnt vmcnt(7)
	v_mov_b32_e32 v42, v238
	v_mov_b32_e32 v43, v239
	v_mov_b32_e32 v44, v240
	v_mov_b32_e32 v45, v241
	v_mov_b32_e32 v62, v242
	v_mov_b32_e32 v63, v243
	v_mov_b32_e32 v64, v244
	v_mov_b32_e32 v65, v245
	v_lshlrev_b32_e32 v251, 1, v250
	v_add_u32_e32 v251, 0xb0000, v251
	global_load_dwordx4 v[238:241], v251, s[28:29]
	global_load_dwordx4 v[242:245], v251, s[28:29] offset:16
	v_pk_mul_f32 v[44:45], v[44:45], s[86:87] op_sel_hi:[1,0]
	v_pk_mul_f32 v[42:43], v[42:43], s[86:87] op_sel_hi:[1,0]
	v_pk_fma_f32 v[44:45], v[40:41], v[56:57], v[44:45]
	v_pk_fma_f32 v[42:43], v[38:39], v[54:55], v[42:43]

; __device__ __forceinline__ u32x4 pack8(const f32x4 a, const f32x4 b) { u32x4 w; w.x = cvt_pk_bf16(a[0], a[1]); w.y = cvt_pk_bf16(a[2], a[3]); w.z = cvt_pk_bf16(b[0], b[1]); w.w = cvt_pk_bf16(b[2], b[3]); return w; }
;     __device__ __forceinline__ void operator()(const f32x4 (&acc)[2][2][4][2], const Unit& u, int wr, int wc, int fr, int fq) const {
;     ...
;                 for (int bj = 0; bj < 2; ++bj) { f32x4 o[2];
;                     if (lat && rinB) { const u32x4 w = *(const u32x4*)(rinB + off + bj * 32);
;                         const f32x4 b0 = {__builtin_bit_cast(float, w.x << 16), __builtin_bit_cast(float, w.x & 0xffff0000u), __builtin_bit_cast(float, w.y << 16), __builtin_bit_cast(float, w.y & 0xffff0000u)};
;                         const f32x4 b1 = {__builtin_bit_cast(float, w.z << 16), __builtin_bit_cast(float, w.z & 0xffff0000u), __builtin_bit_cast(float, w.w << 16), __builtin_bit_cast(float, w.w & 0xffff0000u)};
;                         o[0] = b0 * 1.6817928305074290f + gv[bj][0] * acc[ai][bj][m][0]; o[1] = b1 * 1.6817928305074290f + gv[bj][1] * acc[ai][bj][m][1]; }
;                     else {
; #pragma unroll
;                     for (int n = 0; n < 2; ++n) { const f32x4 bs = *(const f32x4*)(ib + off + bj * 32 + n * 4); o[n] = bs * 1.6817928305074290f + gv[bj][n] * acc[ai][bj][m][n]; } }
;                     if (tobf) *(u32x4*)(vout + off + bj * 32) = pack8(o[0], o[1]);
;                     else { *(f32x4*)(ob + off + bj * 32) = o[0]; *(f32x4*)(ob + off + bj * 32 + 4) = o[1]; } }
.LBB0_1142:
	s_andn2_b64 vcc, exec, s[30:31]
	v_lshl_add_u64 v[46:47], v[42:43], 2, s[28:29]
	s_cbranch_vccnz .LBB0_1144
	s_waitcnt vmcnt(7)
	v_mov_b32_e32 v34, v208
	v_mov_b32_e32 v35, v209
	v_mov_b32_e32 v36, v210
	v_mov_b32_e32 v37, v211
	v_mov_b32_e32 v38, v226
	v_mov_b32_e32 v39, v227
	v_mov_b32_e32 v40, v228
	v_mov_b32_e32 v41, v229
	v_lshlrev_b32_e32 v251, 1, v250
	v_add_u32_e32 v251, 0xb0000, v251
	global_load_dwordx4 v[208:211], v251, s[28:29] offset:128
	global_load_dwordx4 v[226:229], v251, s[28:29] offset:144
	v_pk_mul_f32 v[36:37], v[36:37], s[86:87] op_sel_hi:[1,0]
	v_pk_mul_f32 v[34:35], v[34:35], s[86:87] op_sel_hi:[1,0]
	v_pk_fma_f32 v[36:37], v[32:33], v[72:73], v[36:37]
	v_pk_fma_f32 v[34:35], v[30:31], v[70:71], v[34:35]

; __device__ __forceinline__ u32x4 pack8(const f32x4 a, const f32x4 b) { u32x4 w; w.x = cvt_pk_bf16(a[0], a[1]); w.y = cvt_pk_bf16(a[2], a[3]); w.z = cvt_pk_bf16(b[0], b[1]); w.w = cvt_pk_bf16(b[2], b[3]); return w; }
;     __device__ __forceinline__ void operator()(const f32x4 (&acc)[2][2][4][2], const Unit& u, int wr, int wc, int fr, int fq) const {
;     ...
;                 for (int bj = 0; bj < 2; ++bj) { f32x4 o[2];
;                     if (lat && rinB) { const u32x4 w = *(const u32x4*)(rinB + off + bj * 32);
;                         const f32x4 b0 = {__builtin_bit_cast(float, w.x << 16), __builtin_bit_cast(float, w.x & 0xffff0000u), __builtin_bit_cast(float, w.y << 16), __builtin_bit_cast(float, w.y & 0xffff0000u)};
;                         const f32x4 b1 = {__builtin_bit_cast(float, w.z << 16), __builtin_bit_cast(float, w.z & 0xffff0000u), __builtin_bit_cast(float, w.w << 16), __builtin_bit_cast(float, w.w & 0xffff0000u)};
;                         o[0] = b0 * 1.6817928305074290f + gv[bj][0] * acc[ai][bj][m][0]; o[1] = b1 * 1.6817928305074290f + gv[bj][1] * acc[ai][bj][m][1]; }
;                     else {
; #pragma unroll
;                     for (int n = 0; n < 2; ++n) { const f32x4 bs = *(const f32x4*)(ib + off + bj * 32 + n * 4); o[n] = bs * 1.6817928305074290f + gv[bj][n] * acc[ai][bj][m][n]; } }
;                     if (tobf) *(u32x4*)(vout + off + bj * 32) = pack8(o[0], o[1]);
;                     else { *(f32x4*)(ob + off + bj * 32) = o[0]; *(f32x4*)(ob + off + bj * 32 + 4) = o[1]; } }
.LBB0_1150:
	s_andn2_b64 vcc, exec, s[30:31]
	s_cbranch_vccnz .LBB0_1152
	s_waitcnt vmcnt(7)
	v_mov_b32_e32 v26, v230
	v_mov_b32_e32 v27, v231
	v_mov_b32_e32 v28, v232
	v_mov_b32_e32 v29, v233
	v_mov_b32_e32 v38, v234
	v_mov_b32_e32 v39, v235
	v_mov_b32_e32 v40, v236
	v_mov_b32_e32 v41, v237
	v_pk_mul_f32 v[28:29], v[28:29], s[86:87] op_sel_hi:[1,0]
	v_pk_mul_f32 v[26:27], v[26:27], s[86:87] op_sel_hi:[1,0]
	v_pk_fma_f32 v[28:29], v[24:25], v[56:57], v[28:29]
	v_pk_fma_f32 v[26:27], v[22:23], v[54:55], v[26:27]

; __device__ __forceinline__ u32x4 pack8(const f32x4 a, const f32x4 b) { u32x4 w; w.x = cvt_pk_bf16(a[0], a[1]); w.y = cvt_pk_bf16(a[2], a[3]); w.z = cvt_pk_bf16(b[0], b[1]); w.w = cvt_pk_bf16(b[2], b[3]); return w; }
;     __device__ __forceinline__ void operator()(const f32x4 (&acc)[2][2][4][2], const Unit& u, int wr, int wc, int fr, int fq) const {
;     ...
;                 for (int bj = 0; bj < 2; ++bj) { f32x4 o[2];
;                     if (lat && rinB) { const u32x4 w = *(const u32x4*)(rinB + off + bj * 32);
;                         const f32x4 b0 = {__builtin_bit_cast(float, w.x << 16), __builtin_bit_cast(float, w.x & 0xffff0000u), __builtin_bit_cast(float, w.y << 16), __builtin_bit_cast(float, w.y & 0xffff0000u)};
;                         const f32x4 b1 = {__builtin_bit_cast(float, w.z << 16), __builtin_bit_cast(float, w.z & 0xffff0000u), __builtin_bit_cast(float, w.w << 16), __builtin_bit_cast(float, w.w & 0xffff0000u)};
;                         o[0] = b0 * 1.6817928305074290f + gv[bj][0] * acc[ai][bj][m][0]; o[1] = b1 * 1.6817928305074290f + gv[bj][1] * acc[ai][bj][m][1]; }
;                     else {
; #pragma unroll
;                     for (int n = 0; n < 2; ++n) { const f32x4 bs = *(const f32x4*)(ib + off + bj * 32 + n * 4); o[n] = bs * 1.6817928305074290f + gv[bj][n] * acc[ai][bj][m][n]; } }
;                     if (tobf) *(u32x4*)(vout + off + bj * 32) = pack8(o[0], o[1]);
;                     else { *(f32x4*)(ob + off + bj * 32) = o[0]; *(f32x4*)(ob + off + bj * 32 + 4) = o[1]; } }
.LBB0_1158:
	s_andn2_b64 vcc, exec, s[30:31]
	v_lshl_add_u64 v[30:31], v[26:27], 2, s[28:29]
	s_cbranch_vccnz .LBB0_1160
	s_waitcnt vmcnt(5)
	v_mov_b32_e32 v18, v238
	v_mov_b32_e32 v19, v239
	v_mov_b32_e32 v20, v240
	v_mov_b32_e32 v21, v241
	v_mov_b32_e32 v22, v242
	v_mov_b32_e32 v23, v243
	v_mov_b32_e32 v24, v244
	v_mov_b32_e32 v25, v245
	v_pk_mul_f32 v[20:21], v[20:21], s[86:87] op_sel_hi:[1,0]
	v_pk_mul_f32 v[18:19], v[18:19], s[86:87] op_sel_hi:[1,0]
	v_pk_fma_f32 v[20:21], v[16:17], v[72:73], v[20:21]
	v_pk_fma_f32 v[18:19], v[14:15], v[70:71], v[18:19]

; __device__ __forceinline__ u32x4 pack8(const f32x4 a, const f32x4 b) { u32x4 w; w.x = cvt_pk_bf16(a[0], a[1]); w.y = cvt_pk_bf16(a[2], a[3]); w.z = cvt_pk_bf16(b[0], b[1]); w.w = cvt_pk_bf16(b[2], b[3]); return w; }
;     __device__ __forceinline__ void operator()(const f32x4 (&acc)[2][2][4][2], const Unit& u, int wr, int wc, int fr, int fq) const {
;     ...
;                 for (int bj = 0; bj < 2; ++bj) { f32x4 o[2];
;                     if (lat && rinB) { const u32x4 w = *(const u32x4*)(rinB + off + bj * 32);
;                         const f32x4 b0 = {__builtin_bit_cast(float, w.x << 16), __builtin_bit_cast(float, w.x & 0xffff0000u), __builtin_bit_cast(float, w.y << 16), __builtin_bit_cast(float, w.y & 0xffff0000u)};
;                         const f32x4 b1 = {__builtin_bit_cast(float, w.z << 16), __builtin_bit_cast(float, w.z & 0xffff0000u), __builtin_bit_cast(float, w.w << 16), __builtin_bit_cast(float, w.w & 0xffff0000u)};
;                         o[0] = b0 * 1.6817928305074290f + gv[bj][0] * acc[ai][bj][m][0]; o[1] = b1 * 1.6817928305074290f + gv[bj][1] * acc[ai][bj][m][1]; }
;                     else {
; #pragma unroll
;                     for (int n = 0; n < 2; ++n) { const f32x4 bs = *(const f32x4*)(ib + off + bj * 32 + n * 4); o[n] = bs * 1.6817928305074290f + gv[bj][n] * acc[ai][bj][m][n]; } }
;                     if (tobf) *(u32x4*)(vout + off + bj * 32) = pack8(o[0], o[1]);
;                     else { *(f32x4*)(ob + off + bj * 32) = o[0]; *(f32x4*)(ob + off + bj * 32 + 4) = o[1]; } }
.LBB0_1166:
	s_andn2_b64 vcc, exec, s[28:29]
	s_cbranch_vccnz .LBB0_1168
	s_waitcnt vmcnt(3)
	v_mov_b32_e32 v10, v208
	v_mov_b32_e32 v11, v209
	v_mov_b32_e32 v12, v210
	v_mov_b32_e32 v13, v211
	v_mov_b32_e32 v22, v226
	v_mov_b32_e32 v23, v227
	v_mov_b32_e32 v24, v228
	v_mov_b32_e32 v25, v229
	v_pk_mul_f32 v[12:13], v[12:13], s[86:87] op_sel_hi:[1,0]
	v_pk_mul_f32 v[10:11], v[10:11], s[86:87] op_sel_hi:[1,0]
	v_pk_fma_f32 v[12:13], v[8:9], v[56:57], v[12:13]
	v_pk_fma_f32 v[10:11], v[6:7], v[54:55], v[10:11]

; __device__ __forceinline__ u32x4 pack8(const f32x4 a, const f32x4 b) { u32x4 w; w.x = cvt_pk_bf16(a[0], a[1]); w.y = cvt_pk_bf16(a[2], a[3]); w.z = cvt_pk_bf16(b[0], b[1]); w.w = cvt_pk_bf16(b[2], b[3]); return w; }
;     __device__ __forceinline__ void operator()(const f32x4 (&acc)[2][2][4][2], const Unit& u, int wr, int wc, int fr, int fq) const {
;     ...
;         const float* ib = lat ? rinL : rinC - (size_t)32768 * 1024; float* ob = lat ? routL : routC - (size_t)32768 * 1024;
;         const bool tobf = lat && vout != nullptr;
; #pragma unroll
;         for (int ai = 0; ai < 2; ++ai)
; #pragma unroll
;             for (int m = 0; m < 4; ++m) { const size_t off = (size_t)(rowb + ai * HALF + m * 16) * 1024 + col0;
; #pragma unroll
;                 for (int bj = 0; bj < 2; ++bj) { f32x4 o[2];
;                     if (lat && rinB) { const u32x4 w = *(const u32x4*)(rinB + off + bj * 32);
;                         const f32x4 b0 = {__builtin_bit_cast(float, w.x << 16), __builtin_bit_cast(float, w.x & 0xffff0000u), __builtin_bit_cast(float, w.y << 16), __builtin_bit_cast(float, w.y & 0xffff0000u)};
;                         const f32x4 b1 = {__builtin_bit_cast(float, w.z << 16), __builtin_bit_cast(float, w.z & 0xffff0000u), __builtin_bit_cast(float, w.w << 16), __builtin_bit_cast(float, w.w & 0xffff0000u)};
;                         o[0] = b0 * 1.6817928305074290f + gv[bj][0] * acc[ai][bj][m][0]; o[1] = b1 * 1.6817928305074290f + gv[bj][1] * acc[ai][bj][m][1]; }
;                     else {
; #pragma unroll
;                     for (int n = 0; n < 2; ++n) { const f32x4 bs = *(const f32x4*)(ib + off + bj * 32 + n * 4); o[n] = bs * 1.6817928305074290f + gv[bj][n] * acc[ai][bj][m][n]; } }
;                     if (tobf) *(u32x4*)(vout + off + bj * 32) = pack8(o[0], o[1]);
;                     else { *(f32x4*)(ob + off + bj * 32) = o[0]; *(f32x4*)(ob + off + bj * 32 + 4) = o[1]; } }
.LBB0_1433:
	s_andn2_b64 vcc, exec, s[30:31]
	v_lshl_add_u64 v[192:193], v[196:197], 2, s[28:29]
	s_cbranch_vccnz .LBB0_1435
	v_lshlrev_b32_e32 v251, 1, v250
	global_load_dwordx4 v[208:211], v251, s[28:29]
	global_load_dwordx4 v[226:229], v251, s[28:29] offset:16
	v_lshlrev_b32_e32 v251, 1, v250
	global_load_dwordx4 v[230:233], v251, s[28:29] offset:128
	global_load_dwordx4 v[234:237], v251, s[28:29] offset:144
	v_lshlrev_b32_e32 v251, 1, v250
	v_add_u32_e32 v251, 0x10000, v251
	global_load_dwordx4 v[238:241], v251, s[28:29]
	global_load_dwordx4 v[242:245], v251, s[28:29] offset:16
	s_waitcnt vmcnt(4)
	v_mov_b32_e32 v162, v208
	v_mov_b32_e32 v163, v209
	v_mov_b32_e32 v164, v210
	v_mov_b32_e32 v165, v211
	v_mov_b32_e32 v166, v226
	v_mov_b32_e32 v167, v227
	v_mov_b32_e32 v168, v228
	v_mov_b32_e32 v169, v229
	v_lshlrev_b32_e32 v251, 1, v250
	v_add_u32_e32 v251, 0x10000, v251
	global_load_dwordx4 v[208:211], v251, s[28:29] offset:128
	global_load_dwordx4 v[226:229], v251, s[28:29] offset:144
	v_pk_mul_f32 v[164:165], v[164:165], s[86:87] op_sel_hi:[1,0]
	v_pk_mul_f32 v[162:163], v[162:163], s[86:87] op_sel_hi:[1,0]
	v_pk_fma_f32 v[164:165], v[144:145], v[160:161], v[164:165]
	v_pk_fma_f32 v[162:163], v[142:143], v[158:159], v[162:163]

; __device__ __forceinline__ u32x4 pack8(const f32x4 a, const f32x4 b) { u32x4 w; w.x = cvt_pk_bf16(a[0], a[1]); w.y = cvt_pk_bf16(a[2], a[3]); w.z = cvt_pk_bf16(b[0], b[1]); w.w = cvt_pk_bf16(b[2], b[3]); return w; }
;     __device__ __forceinline__ void operator()(const f32x4 (&acc)[2][2][4][2], const Unit& u, int wr, int wc, int fr, int fq) const {
;     ...
;                 for (int bj = 0; bj < 2; ++bj) { f32x4 o[2];
;                     if (lat && rinB) { const u32x4 w = *(const u32x4*)(rinB + off + bj * 32);
;                         const f32x4 b0 = {__builtin_bit_cast(float, w.x << 16), __builtin_bit_cast(float, w.x & 0xffff0000u), __builtin_bit_cast(float, w.y << 16), __builtin_bit_cast(float, w.y & 0xffff0000u)};
;                         const f32x4 b1 = {__builtin_bit_cast(float, w.z << 16), __builtin_bit_cast(float, w.z & 0xffff0000u), __builtin_bit_cast(float, w.w << 16), __builtin_bit_cast(float, w.w & 0xffff0000u)};
;                         o[0] = b0 * 1.6817928305074290f + gv[bj][0] * acc[ai][bj][m][0]; o[1] = b1 * 1.6817928305074290f + gv[bj][1] * acc[ai][bj][m][1]; }
;                     else {
; #pragma unroll
;                     for (int n = 0; n < 2; ++n) { const f32x4 bs = *(const f32x4*)(ib + off + bj * 32 + n * 4); o[n] = bs * 1.6817928305074290f + gv[bj][n] * acc[ai][bj][m][n]; } }
;                     if (tobf) *(u32x4*)(vout + off + bj * 32) = pack8(o[0], o[1]);
;                     else { *(f32x4*)(ob + off + bj * 32) = o[0]; *(f32x4*)(ob + off + bj * 32 + 4) = o[1]; } }
.LBB0_1443:
	s_andn2_b64 vcc, exec, s[30:31]
	s_cbranch_vccnz .LBB0_1445
	s_waitcnt vmcnt(5)
	v_mov_b32_e32 v162, v230
	v_mov_b32_e32 v163, v231
	v_mov_b32_e32 v164, v232
	v_mov_b32_e32 v165, v233
	v_mov_b32_e32 v174, v234
	v_mov_b32_e32 v175, v235
	v_mov_b32_e32 v176, v236
	v_mov_b32_e32 v177, v237
	v_lshlrev_b32_e32 v251, 1, v250
	v_add_u32_e32 v251, 0x20000, v251
	global_load_dwordx4 v[230:233], v251, s[28:29]
	global_load_dwordx4 v[234:237], v251, s[28:29] offset:16
	v_pk_mul_f32 v[164:165], v[164:165], s[86:87] op_sel_hi:[1,0]
	v_pk_mul_f32 v[162:163], v[162:163], s[86:87] op_sel_hi:[1,0]
	v_pk_fma_f32 v[168:169], v[132:133], v[152:153], v[164:165]
	v_pk_fma_f32 v[166:167], v[130:131], v[150:151], v[162:163]

; __device__ __forceinline__ u32x4 pack8(const f32x4 a, const f32x4 b) { u32x4 w; w.x = cvt_pk_bf16(a[0], a[1]); w.y = cvt_pk_bf16(a[2], a[3]); w.z = cvt_pk_bf16(b[0], b[1]); w.w = cvt_pk_bf16(b[2], b[3]); return w; }
;     __device__ __forceinline__ void operator()(const f32x4 (&acc)[2][2][4][2], const Unit& u, int wr, int wc, int fr, int fq) const {
;     ...
;                 for (int bj = 0; bj < 2; ++bj) { f32x4 o[2];
;                     if (lat && rinB) { const u32x4 w = *(const u32x4*)(rinB + off + bj * 32);
;                         const f32x4 b0 = {__builtin_bit_cast(float, w.x << 16), __builtin_bit_cast(float, w.x & 0xffff0000u), __builtin_bit_cast(float, w.y << 16), __builtin_bit_cast(float, w.y & 0xffff0000u)};
;                         const f32x4 b1 = {__builtin_bit_cast(float, w.z << 16), __builtin_bit_cast(float, w.z & 0xffff0000u), __builtin_bit_cast(float, w.w << 16), __builtin_bit_cast(float, w.w & 0xffff0000u)};
;                         o[0] = b0 * 1.6817928305074290f + gv[bj][0] * acc[ai][bj][m][0]; o[1] = b1 * 1.6817928305074290f + gv[bj][1] * acc[ai][bj][m][1]; }
;                     else {
; #pragma unroll
;                     for (int n = 0; n < 2; ++n) { const f32x4 bs = *(const f32x4*)(ib + off + bj * 32 + n * 4); o[n] = bs * 1.6817928305074290f + gv[bj][n] * acc[ai][bj][m][n]; } }
;                     if (tobf) *(u32x4*)(vout + off + bj * 32) = pack8(o[0], o[1]);
;                     else { *(f32x4*)(ob + off + bj * 32) = o[0]; *(f32x4*)(ob + off + bj * 32 + 4) = o[1]; } }
.LBB0_1451:
	s_andn2_b64 vcc, exec, s[30:31]
	v_lshl_add_u64 v[192:193], v[196:197], 2, s[28:29]
	s_cbranch_vccnz .LBB0_1453
	s_waitcnt vmcnt(6)
	v_mov_b32_e32 v162, v238
	v_mov_b32_e32 v163, v239
	v_mov_b32_e32 v164, v240
	v_mov_b32_e32 v165, v241
	v_mov_b32_e32 v166, v242
	v_mov_b32_e32 v167, v243
	v_mov_b32_e32 v168, v244
	v_mov_b32_e32 v169, v245
	v_lshlrev_b32_e32 v251, 1, v250
	v_add_u32_e32 v251, 0x20000, v251
	global_load_dwordx4 v[238:241], v251, s[28:29] offset:128
	global_load_dwordx4 v[242:245], v251, s[28:29] offset:144
	v_pk_mul_f32 v[164:165], v[164:165], s[86:87] op_sel_hi:[1,0]
	v_pk_mul_f32 v[162:163], v[162:163], s[86:87] op_sel_hi:[1,0]
	v_pk_fma_f32 v[164:165], v[136:137], v[160:161], v[164:165]
	v_pk_fma_f32 v[162:163], v[134:135], v[158:159], v[162:163]

; __device__ __forceinline__ u32x4 pack8(const f32x4 a, const f32x4 b) { u32x4 w; w.x = cvt_pk_bf16(a[0], a[1]); w.y = cvt_pk_bf16(a[2], a[3]); w.z = cvt_pk_bf16(b[0], b[1]); w.w = cvt_pk_bf16(b[2], b[3]); return w; }
;     __device__ __forceinline__ void operator()(const f32x4 (&acc)[2][2][4][2], const Unit& u, int wr, int wc, int fr, int fq) const {
;     ...
;                 for (int bj = 0; bj < 2; ++bj) { f32x4 o[2];
;                     if (lat && rinB) { const u32x4 w = *(const u32x4*)(rinB + off + bj * 32);
;                         const f32x4 b0 = {__builtin_bit_cast(float, w.x << 16), __builtin_bit_cast(float, w.x & 0xffff0000u), __builtin_bit_cast(float, w.y << 16), __builtin_bit_cast(float, w.y & 0xffff0000u)};
;                         const f32x4 b1 = {__builtin_bit_cast(float, w.z << 16), __builtin_bit_cast(float, w.z & 0xffff0000u), __builtin_bit_cast(float, w.w << 16), __builtin_bit_cast(float, w.w & 0xffff0000u)};
;                         o[0] = b0 * 1.6817928305074290f + gv[bj][0] * acc[ai][bj][m][0]; o[1] = b1 * 1.6817928305074290f + gv[bj][1] * acc[ai][bj][m][1]; }
;                     else {
; #pragma unroll
;                     for (int n = 0; n < 2; ++n) { const f32x4 bs = *(const f32x4*)(ib + off + bj * 32 + n * 4); o[n] = bs * 1.6817928305074290f + gv[bj][n] * acc[ai][bj][m][n]; } }
;                     if (tobf) *(u32x4*)(vout + off + bj * 32) = pack8(o[0], o[1]);
;                     else { *(f32x4*)(ob + off + bj * 32) = o[0]; *(f32x4*)(ob + off + bj * 32 + 4) = o[1]; } }
.LBB0_1459:
	s_andn2_b64 vcc, exec, s[30:31]
	s_cbranch_vccnz .LBB0_1461
	s_waitcnt vmcnt(7)
	v_mov_b32_e32 v162, v208
	v_mov_b32_e32 v163, v209
	v_mov_b32_e32 v164, v210
	v_mov_b32_e32 v165, v211
	v_mov_b32_e32 v170, v226
	v_mov_b32_e32 v171, v227
	v_mov_b32_e32 v172, v228
	v_mov_b32_e32 v173, v229
	v_lshlrev_b32_e32 v251, 1, v250
	v_add_u32_e32 v251, 0x30000, v251
	global_load_dwordx4 v[208:211], v251, s[28:29]
	global_load_dwordx4 v[226:229], v251, s[28:29] offset:16
	v_pk_mul_f32 v[164:165], v[164:165], s[86:87] op_sel_hi:[1,0]
	v_pk_mul_f32 v[162:163], v[162:163], s[86:87] op_sel_hi:[1,0]
	v_pk_fma_f32 v[168:169], v[100:101], v[152:153], v[164:165]
	v_pk_fma_f32 v[166:167], v[98:99], v[150:151], v[162:163]

; __device__ __forceinline__ u32x4 pack8(const f32x4 a, const f32x4 b) { u32x4 w; w.x = cvt_pk_bf16(a[0], a[1]); w.y = cvt_pk_bf16(a[2], a[3]); w.z = cvt_pk_bf16(b[0], b[1]); w.w = cvt_pk_bf16(b[2], b[3]); return w; }
;     __device__ __forceinline__ void operator()(const f32x4 (&acc)[2][2][4][2], const Unit& u, int wr, int wc, int fr, int fq) const {
;     ...
;                 for (int bj = 0; bj < 2; ++bj) { f32x4 o[2];
;                     if (lat && rinB) { const u32x4 w = *(const u32x4*)(rinB + off + bj * 32);
;                         const f32x4 b0 = {__builtin_bit_cast(float, w.x << 16), __builtin_bit_cast(float, w.x & 0xffff0000u), __builtin_bit_cast(float, w.y << 16), __builtin_bit_cast(float, w.y & 0xffff0000u)};
;                         const f32x4 b1 = {__builtin_bit_cast(float, w.z << 16), __builtin_bit_cast(float, w.z & 0xffff0000u), __builtin_bit_cast(float, w.w << 16), __builtin_bit_cast(float, w.w & 0xffff0000u)};
;                         o[0] = b0 * 1.6817928305074290f + gv[bj][0] * acc[ai][bj][m][0]; o[1] = b1 * 1.6817928305074290f + gv[bj][1] * acc[ai][bj][m][1]; }
;                     else {
; #pragma unroll
;                     for (int n = 0; n < 2; ++n) { const f32x4 bs = *(const f32x4*)(ib + off + bj * 32 + n * 4); o[n] = bs * 1.6817928305074290f + gv[bj][n] * acc[ai][bj][m][n]; } }
;                     if (tobf) *(u32x4*)(vout + off + bj * 32) = pack8(o[0], o[1]);
;                     else { *(f32x4*)(ob + off + bj * 32) = o[0]; *(f32x4*)(ob + off + bj * 32 + 4) = o[1]; } }
.LBB0_1467:
	s_andn2_b64 vcc, exec, s[30:31]
	v_lshl_add_u64 v[192:193], v[196:197], 2, s[28:29]
	s_cbranch_vccnz .LBB0_1469
	s_waitcnt vmcnt(7)
	v_mov_b32_e32 v162, v230
	v_mov_b32_e32 v163, v231
	v_mov_b32_e32 v164, v232
	v_mov_b32_e32 v165, v233
	v_mov_b32_e32 v166, v234
	v_mov_b32_e32 v167, v235
	v_mov_b32_e32 v168, v236
	v_mov_b32_e32 v169, v237
	v_lshlrev_b32_e32 v251, 1, v250
	v_add_u32_e32 v251, 0x30000, v251
	global_load_dwordx4 v[230:233], v251, s[28:29] offset:128
	global_load_dwordx4 v[234:237], v251, s[28:29] offset:144
	v_pk_mul_f32 v[164:165], v[164:165], s[86:87] op_sel_hi:[1,0]
	v_pk_mul_f32 v[162:163], v[162:163], s[86:87] op_sel_hi:[1,0]
	v_pk_fma_f32 v[164:165], v[104:105], v[160:161], v[164:165]
	v_pk_fma_f32 v[162:163], v[102:103], v[158:159], v[162:163]

; __device__ __forceinline__ u32x4 pack8(const f32x4 a, const f32x4 b) { u32x4 w; w.x = cvt_pk_bf16(a[0], a[1]); w.y = cvt_pk_bf16(a[2], a[3]); w.z = cvt_pk_bf16(b[0], b[1]); w.w = cvt_pk_bf16(b[2], b[3]); return w; }
;     __device__ __forceinline__ void operator()(const f32x4 (&acc)[2][2][4][2], const Unit& u, int wr, int wc, int fr, int fq) const {
;     ...
;                 for (int bj = 0; bj < 2; ++bj) { f32x4 o[2];
;                     if (lat && rinB) { const u32x4 w = *(const u32x4*)(rinB + off + bj * 32);
;                         const f32x4 b0 = {__builtin_bit_cast(float, w.x << 16), __builtin_bit_cast(float, w.x & 0xffff0000u), __builtin_bit_cast(float, w.y << 16), __builtin_bit_cast(float, w.y & 0xffff0000u)};
;                         const f32x4 b1 = {__builtin_bit_cast(float, w.z << 16), __builtin_bit_cast(float, w.z & 0xffff0000u), __builtin_bit_cast(float, w.w << 16), __builtin_bit_cast(float, w.w & 0xffff0000u)};
;                         o[0] = b0 * 1.6817928305074290f + gv[bj][0] * acc[ai][bj][m][0]; o[1] = b1 * 1.6817928305074290f + gv[bj][1] * acc[ai][bj][m][1]; }
;                     else {
; #pragma unroll
;                     for (int n = 0; n < 2; ++n) { const f32x4 bs = *(const f32x4*)(ib + off + bj * 32 + n * 4); o[n] = bs * 1.6817928305074290f + gv[bj][n] * acc[ai][bj][m][n]; } }
;                     if (tobf) *(u32x4*)(vout + off + bj * 32) = pack8(o[0], o[1]);
;                     else { *(f32x4*)(ob + off + bj * 32) = o[0]; *(f32x4*)(ob + off + bj * 32 + 4) = o[1]; } }
.LBB0_1475:
	s_andn2_b64 vcc, exec, s[30:31]
	s_cbranch_vccnz .LBB0_1477
	s_waitcnt vmcnt(7)
	v_mov_b32_e32 v162, v238
	v_mov_b32_e32 v163, v239
	v_mov_b32_e32 v164, v240
	v_mov_b32_e32 v165, v241
	v_mov_b32_e32 v174, v242
	v_mov_b32_e32 v175, v243
	v_mov_b32_e32 v176, v244
	v_mov_b32_e32 v177, v245
	v_lshlrev_b32_e32 v251, 1, v250
	v_add_u32_e32 v251, 0x80000, v251
	global_load_dwordx4 v[238:241], v251, s[28:29]
	global_load_dwordx4 v[242:245], v251, s[28:29] offset:16
	v_pk_mul_f32 v[164:165], v[164:165], s[86:87] op_sel_hi:[1,0]
	v_pk_mul_f32 v[162:163], v[162:163], s[86:87] op_sel_hi:[1,0]
	v_pk_fma_f32 v[168:169], v[84:85], v[152:153], v[164:165]
	v_pk_fma_f32 v[166:167], v[82:83], v[150:151], v[162:163]

; __device__ __forceinline__ u32x4 pack8(const f32x4 a, const f32x4 b) { u32x4 w; w.x = cvt_pk_bf16(a[0], a[1]); w.y = cvt_pk_bf16(a[2], a[3]); w.z = cvt_pk_bf16(b[0], b[1]); w.w = cvt_pk_bf16(b[2], b[3]); return w; }
;     __device__ __forceinline__ void operator()(const f32x4 (&acc)[2][2][4][2], const Unit& u, int wr, int wc, int fr, int fq) const {
;     ...
;                 for (int bj = 0; bj < 2; ++bj) { f32x4 o[2];
;                     if (lat && rinB) { const u32x4 w = *(const u32x4*)(rinB + off + bj * 32);
;                         const f32x4 b0 = {__builtin_bit_cast(float, w.x << 16), __builtin_bit_cast(float, w.x & 0xffff0000u), __builtin_bit_cast(float, w.y << 16), __builtin_bit_cast(float, w.y & 0xffff0000u)};
;                         const f32x4 b1 = {__builtin_bit_cast(float, w.z << 16), __builtin_bit_cast(float, w.z & 0xffff0000u), __builtin_bit_cast(float, w.w << 16), __builtin_bit_cast(float, w.w & 0xffff0000u)};
;                         o[0] = b0 * 1.6817928305074290f + gv[bj][0] * acc[ai][bj][m][0]; o[1] = b1 * 1.6817928305074290f + gv[bj][1] * acc[ai][bj][m][1]; }
;                     else {
; #pragma unroll
;                     for (int n = 0; n < 2; ++n) { const f32x4 bs = *(const f32x4*)(ib + off + bj * 32 + n * 4); o[n] = bs * 1.6817928305074290f + gv[bj][n] * acc[ai][bj][m][n]; } }
;                     if (tobf) *(u32x4*)(vout + off + bj * 32) = pack8(o[0], o[1]);
;                     else { *(f32x4*)(ob + off + bj * 32) = o[0]; *(f32x4*)(ob + off + bj * 32 + 4) = o[1]; } }
.LBB0_1483:
	s_andn2_b64 vcc, exec, s[30:31]
	v_lshl_add_u64 v[192:193], v[196:197], 2, s[28:29]
	s_cbranch_vccnz .LBB0_1485
	s_waitcnt vmcnt(7)
	v_mov_b32_e32 v162, v208
	v_mov_b32_e32 v163, v209
	v_mov_b32_e32 v164, v210
	v_mov_b32_e32 v165, v211
	v_mov_b32_e32 v166, v226
	v_mov_b32_e32 v167, v227
	v_mov_b32_e32 v168, v228
	v_mov_b32_e32 v169, v229
	v_lshlrev_b32_e32 v251, 1, v250
	v_add_u32_e32 v251, 0x80000, v251
	global_load_dwordx4 v[208:211], v251, s[28:29] offset:128
	global_load_dwordx4 v[226:229], v251, s[28:29] offset:144
	v_pk_mul_f32 v[164:165], v[164:165], s[86:87] op_sel_hi:[1,0]
	v_pk_mul_f32 v[162:163], v[162:163], s[86:87] op_sel_hi:[1,0]
	v_pk_fma_f32 v[164:165], v[88:89], v[160:161], v[164:165]
	v_pk_fma_f32 v[162:163], v[86:87], v[158:159], v[162:163]

; __device__ __forceinline__ u32x4 pack8(const f32x4 a, const f32x4 b) { u32x4 w; w.x = cvt_pk_bf16(a[0], a[1]); w.y = cvt_pk_bf16(a[2], a[3]); w.z = cvt_pk_bf16(b[0], b[1]); w.w = cvt_pk_bf16(b[2], b[3]); return w; }
;     __device__ __forceinline__ void operator()(const f32x4 (&acc)[2][2][4][2], const Unit& u, int wr, int wc, int fr, int fq) const {
;     ...
;                 for (int bj = 0; bj < 2; ++bj) { f32x4 o[2];
;                     if (lat && rinB) { const u32x4 w = *(const u32x4*)(rinB + off + bj * 32);
;                         const f32x4 b0 = {__builtin_bit_cast(float, w.x << 16), __builtin_bit_cast(float, w.x & 0xffff0000u), __builtin_bit_cast(float, w.y << 16), __builtin_bit_cast(float, w.y & 0xffff0000u)};
;                         const f32x4 b1 = {__builtin_bit_cast(float, w.z << 16), __builtin_bit_cast(float, w.z & 0xffff0000u), __builtin_bit_cast(float, w.w << 16), __builtin_bit_cast(float, w.w & 0xffff0000u)};
;                         o[0] = b0 * 1.6817928305074290f + gv[bj][0] * acc[ai][bj][m][0]; o[1] = b1 * 1.6817928305074290f + gv[bj][1] * acc[ai][bj][m][1]; }
;                     else {
; #pragma unroll
;                     for (int n = 0; n < 2; ++n) { const f32x4 bs = *(const f32x4*)(ib + off + bj * 32 + n * 4); o[n] = bs * 1.6817928305074290f + gv[bj][n] * acc[ai][bj][m][n]; } }
;                     if (tobf) *(u32x4*)(vout + off + bj * 32) = pack8(o[0], o[1]);
;                     else { *(f32x4*)(ob + off + bj * 32) = o[0]; *(f32x4*)(ob + off + bj * 32 + 4) = o[1]; } }
.LBB0_1491:
	s_andn2_b64 vcc, exec, s[30:31]
	s_cbranch_vccnz .LBB0_1493
	s_waitcnt vmcnt(7)
	v_mov_b32_e32 v162, v230
	v_mov_b32_e32 v163, v231
	v_mov_b32_e32 v164, v232
	v_mov_b32_e32 v165, v233
	v_mov_b32_e32 v174, v234
	v_mov_b32_e32 v175, v235
	v_mov_b32_e32 v176, v236
	v_mov_b32_e32 v177, v237
	v_lshlrev_b32_e32 v251, 1, v250
	v_add_u32_e32 v251, 0x90000, v251
	global_load_dwordx4 v[230:233], v251, s[28:29]
	global_load_dwordx4 v[234:237], v251, s[28:29] offset:16
	v_pk_mul_f32 v[164:165], v[164:165], s[86:87] op_sel_hi:[1,0]
	v_pk_mul_f32 v[162:163], v[162:163], s[86:87] op_sel_hi:[1,0]
	v_pk_fma_f32 v[168:169], v[72:73], v[152:153], v[164:165]
	v_pk_fma_f32 v[166:167], v[70:71], v[150:151], v[162:163]

; __device__ __forceinline__ u32x4 pack8(const f32x4 a, const f32x4 b) { u32x4 w; w.x = cvt_pk_bf16(a[0], a[1]); w.y = cvt_pk_bf16(a[2], a[3]); w.z = cvt_pk_bf16(b[0], b[1]); w.w = cvt_pk_bf16(b[2], b[3]); return w; }
;     __device__ __forceinline__ void operator()(const f32x4 (&acc)[2][2][4][2], const Unit& u, int wr, int wc, int fr, int fq) const {
;     ...
;                 for (int bj = 0; bj < 2; ++bj) { f32x4 o[2];
;                     if (lat && rinB) { const u32x4 w = *(const u32x4*)(rinB + off + bj * 32);
;                         const f32x4 b0 = {__builtin_bit_cast(float, w.x << 16), __builtin_bit_cast(float, w.x & 0xffff0000u), __builtin_bit_cast(float, w.y << 16), __builtin_bit_cast(float, w.y & 0xffff0000u)};
;                         const f32x4 b1 = {__builtin_bit_cast(float, w.z << 16), __builtin_bit_cast(float, w.z & 0xffff0000u), __builtin_bit_cast(float, w.w << 16), __builtin_bit_cast(float, w.w & 0xffff0000u)};
;                         o[0] = b0 * 1.6817928305074290f + gv[bj][0] * acc[ai][bj][m][0]; o[1] = b1 * 1.6817928305074290f + gv[bj][1] * acc[ai][bj][m][1]; }
;                     else {
; #pragma unroll
;                     for (int n = 0; n < 2; ++n) { const f32x4 bs = *(const f32x4*)(ib + off + bj * 32 + n * 4); o[n] = bs * 1.6817928305074290f + gv[bj][n] * acc[ai][bj][m][n]; } }
;                     if (tobf) *(u32x4*)(vout + off + bj * 32) = pack8(o[0], o[1]);
;                     else { *(f32x4*)(ob + off + bj * 32) = o[0]; *(f32x4*)(ob + off + bj * 32 + 4) = o[1]; } }
.LBB0_1499:
	s_andn2_b64 vcc, exec, s[30:31]
	v_lshl_add_u64 v[192:193], v[196:197], 2, s[28:29]
	s_cbranch_vccnz .LBB0_1501
	s_waitcnt vmcnt(7)
	v_mov_b32_e32 v162, v238
	v_mov_b32_e32 v163, v239
	v_mov_b32_e32 v164, v240
	v_mov_b32_e32 v165, v241
	v_mov_b32_e32 v166, v242
	v_mov_b32_e32 v167, v243
	v_mov_b32_e32 v168, v244
	v_mov_b32_e32 v169, v245
	v_lshlrev_b32_e32 v251, 1, v250
	v_add_u32_e32 v251, 0x90000, v251
	global_load_dwordx4 v[238:241], v251, s[28:29] offset:128
	global_load_dwordx4 v[242:245], v251, s[28:29] offset:144
	v_pk_mul_f32 v[164:165], v[164:165], s[86:87] op_sel_hi:[1,0]
	v_pk_mul_f32 v[162:163], v[162:163], s[86:87] op_sel_hi:[1,0]
	v_pk_fma_f32 v[164:165], v[64:65], v[160:161], v[164:165]
	v_pk_fma_f32 v[162:163], v[62:63], v[158:159], v[162:163]

; __device__ __forceinline__ u32x4 pack8(const f32x4 a, const f32x4 b) { u32x4 w; w.x = cvt_pk_bf16(a[0], a[1]); w.y = cvt_pk_bf16(a[2], a[3]); w.z = cvt_pk_bf16(b[0], b[1]); w.w = cvt_pk_bf16(b[2], b[3]); return w; }
;     __device__ __forceinline__ void operator()(const f32x4 (&acc)[2][2][4][2], const Unit& u, int wr, int wc, int fr, int fq) const {
;     ...
;                 for (int bj = 0; bj < 2; ++bj) { f32x4 o[2];
;                     if (lat && rinB) { const u32x4 w = *(const u32x4*)(rinB + off + bj * 32);
;                         const f32x4 b0 = {__builtin_bit_cast(float, w.x << 16), __builtin_bit_cast(float, w.x & 0xffff0000u), __builtin_bit_cast(float, w.y << 16), __builtin_bit_cast(float, w.y & 0xffff0000u)};
;                         const f32x4 b1 = {__builtin_bit_cast(float, w.z << 16), __builtin_bit_cast(float, w.z & 0xffff0000u), __builtin_bit_cast(float, w.w << 16), __builtin_bit_cast(float, w.w & 0xffff0000u)};
;                         o[0] = b0 * 1.6817928305074290f + gv[bj][0] * acc[ai][bj][m][0]; o[1] = b1 * 1.6817928305074290f + gv[bj][1] * acc[ai][bj][m][1]; }
;                     else {
; #pragma unroll
;                     for (int n = 0; n < 2; ++n) { const f32x4 bs = *(const f32x4*)(ib + off + bj * 32 + n * 4); o[n] = bs * 1.6817928305074290f + gv[bj][n] * acc[ai][bj][m][n]; } }
;                     if (tobf) *(u32x4*)(vout + off + bj * 32) = pack8(o[0], o[1]);
;                     else { *(f32x4*)(ob + off + bj * 32) = o[0]; *(f32x4*)(ob + off + bj * 32 + 4) = o[1]; } }
.LBB0_1507:
	s_andn2_b64 vcc, exec, s[30:31]
	s_cbranch_vccnz .LBB0_1509
	s_waitcnt vmcnt(7)
	v_mov_b32_e32 v162, v208
	v_mov_b32_e32 v163, v209
	v_mov_b32_e32 v164, v210
	v_mov_b32_e32 v165, v211
	v_mov_b32_e32 v174, v226
	v_mov_b32_e32 v175, v227
	v_mov_b32_e32 v176, v228
	v_mov_b32_e32 v177, v229
	v_lshlrev_b32_e32 v251, 1, v250
	v_add_u32_e32 v251, 0xa0000, v251
	global_load_dwordx4 v[208:211], v251, s[28:29]
	global_load_dwordx4 v[226:229], v251, s[28:29] offset:16
	v_pk_mul_f32 v[164:165], v[164:165], s[86:87] op_sel_hi:[1,0]
	v_pk_mul_f32 v[162:163], v[162:163], s[86:87] op_sel_hi:[1,0]
	v_pk_fma_f32 v[168:169], v[52:53], v[152:153], v[164:165]
	v_pk_fma_f32 v[166:167], v[50:51], v[150:151], v[162:163]

; __device__ __forceinline__ u32x4 pack8(const f32x4 a, const f32x4 b) { u32x4 w; w.x = cvt_pk_bf16(a[0], a[1]); w.y = cvt_pk_bf16(a[2], a[3]); w.z = cvt_pk_bf16(b[0], b[1]); w.w = cvt_pk_bf16(b[2], b[3]); return w; }
;     __device__ __forceinline__ void operator()(const f32x4 (&acc)[2][2][4][2], const Unit& u, int wr, int wc, int fr, int fq) const {
;     ...
;                 for (int bj = 0; bj < 2; ++bj) { f32x4 o[2];
;                     if (lat && rinB) { const u32x4 w = *(const u32x4*)(rinB + off + bj * 32);
;                         const f32x4 b0 = {__builtin_bit_cast(float, w.x << 16), __builtin_bit_cast(float, w.x & 0xffff0000u), __builtin_bit_cast(float, w.y << 16), __builtin_bit_cast(float, w.y & 0xffff0000u)};
;                         const f32x4 b1 = {__builtin_bit_cast(float, w.z << 16), __builtin_bit_cast(float, w.z & 0xffff0000u), __builtin_bit_cast(float, w.w << 16), __builtin_bit_cast(float, w.w & 0xffff0000u)};
;                         o[0] = b0 * 1.6817928305074290f + gv[bj][0] * acc[ai][bj][m][0]; o[1] = b1 * 1.6817928305074290f + gv[bj][1] * acc[ai][bj][m][1]; }
;                     else {
; #pragma unroll
;                     for (int n = 0; n < 2; ++n) { const f32x4 bs = *(const f32x4*)(ib + off + bj * 32 + n * 4); o[n] = bs * 1.6817928305074290f + gv[bj][n] * acc[ai][bj][m][n]; } }
;                     if (tobf) *(u32x4*)(vout + off + bj * 32) = pack8(o[0], o[1]);
;                     else { *(f32x4*)(ob + off + bj * 32) = o[0]; *(f32x4*)(ob + off + bj * 32 + 4) = o[1]; } }
.LBB0_1515:
	s_andn2_b64 vcc, exec, s[30:31]
	v_lshl_add_u64 v[192:193], v[196:197], 2, s[28:29]
	s_cbranch_vccnz .LBB0_1517
	s_waitcnt vmcnt(7)
	v_mov_b32_e32 v162, v230
	v_mov_b32_e32 v163, v231
	v_mov_b32_e32 v164, v232
	v_mov_b32_e32 v165, v233
	v_mov_b32_e32 v166, v234
	v_mov_b32_e32 v167, v235
	v_mov_b32_e32 v168, v236
	v_mov_b32_e32 v169, v237
	v_lshlrev_b32_e32 v251, 1, v250
	v_add_u32_e32 v251, 0xa0000, v251
	global_load_dwordx4 v[230:233], v251, s[28:29] offset:128
	global_load_dwordx4 v[234:237], v251, s[28:29] offset:144
	v_pk_mul_f32 v[164:165], v[164:165], s[86:87] op_sel_hi:[1,0]
	v_pk_mul_f32 v[162:163], v[162:163], s[86:87] op_sel_hi:[1,0]
	v_pk_fma_f32 v[164:165], v[56:57], v[160:161], v[164:165]
	v_pk_fma_f32 v[162:163], v[54:55], v[158:159], v[162:163]

; __device__ __forceinline__ u32x4 pack8(const f32x4 a, const f32x4 b) { u32x4 w; w.x = cvt_pk_bf16(a[0], a[1]); w.y = cvt_pk_bf16(a[2], a[3]); w.z = cvt_pk_bf16(b[0], b[1]); w.w = cvt_pk_bf16(b[2], b[3]); return w; }
;     __device__ __forceinline__ void operator()(const f32x4 (&acc)[2][2][4][2], const Unit& u, int wr, int wc, int fr, int fq) const {
;     ...
;             for (int m = 0; m < 4; ++m) { const size_t off = (size_t)(rowb + ai * HALF + m * 16) * 1024 + col0;
; #pragma unroll
;                 for (int bj = 0; bj < 2; ++bj) { f32x4 o[2];
;                     if (lat && rinB) { const u32x4 w = *(const u32x4*)(rinB + off + bj * 32);
;                         const f32x4 b0 = {__builtin_bit_cast(float, w.x << 16), __builtin_bit_cast(float, w.x & 0xffff0000u), __builtin_bit_cast(float, w.y << 16), __builtin_bit_cast(float, w.y & 0xffff0000u)};
;                         const f32x4 b1 = {__builtin_bit_cast(float, w.z << 16), __builtin_bit_cast(float, w.z & 0xffff0000u), __builtin_bit_cast(float, w.w << 16), __builtin_bit_cast(float, w.w & 0xffff0000u)};
;                         o[0] = b0 * 1.6817928305074290f + gv[bj][0] * acc[ai][bj][m][0]; o[1] = b1 * 1.6817928305074290f + gv[bj][1] * acc[ai][bj][m][1]; }
;                     else {
; #pragma unroll
;                     for (int n = 0; n < 2; ++n) { const f32x4 bs = *(const f32x4*)(ib + off + bj * 32 + n * 4); o[n] = bs * 1.6817928305074290f + gv[bj][n] * acc[ai][bj][m][n]; } }
;                     if (tobf) *(u32x4*)(vout + off + bj * 32) = pack8(o[0], o[1]);
;                     else { *(f32x4*)(ob + off + bj * 32) = o[0]; *(f32x4*)(ob + off + bj * 32 + 4) = o[1]; } }
.LBB0_1523:
	s_andn2_b64 vcc, exec, s[30:31]
	s_cbranch_vccnz .LBB0_1525
	s_waitcnt vmcnt(7)
	v_mov_b32_e32 v162, v238
	v_mov_b32_e32 v163, v239
	v_mov_b32_e32 v164, v240
	v_mov_b32_e32 v165, v241
	v_mov_b32_e32 v174, v242
	v_mov_b32_e32 v175, v243
	v_mov_b32_e32 v176, v244
	v_mov_b32_e32 v177, v245
	v_lshlrev_b32_e32 v251, 1, v250
	v_add_u32_e32 v251, 0xb0000, v251
	global_load_dwordx4 v[238:241], v251, s[28:29]
	global_load_dwordx4 v[242:245], v251, s[28:29] offset:16
	v_pk_mul_f32 v[164:165], v[164:165], s[86:87] op_sel_hi:[1,0]
	v_pk_mul_f32 v[162:163], v[162:163], s[86:87] op_sel_hi:[1,0]
	v_pk_fma_f32 v[168:169], v[36:37], v[152:153], v[164:165]
	v_pk_fma_f32 v[166:167], v[34:35], v[150:151], v[162:163]

; __device__ __forceinline__ u32x4 pack8(const f32x4 a, const f32x4 b) { u32x4 w; w.x = cvt_pk_bf16(a[0], a[1]); w.y = cvt_pk_bf16(a[2], a[3]); w.z = cvt_pk_bf16(b[0], b[1]); w.w = cvt_pk_bf16(b[2], b[3]); return w; }
;     __device__ __forceinline__ void operator()(const f32x4 (&acc)[2][2][4][2], const Unit& u, int wr, int wc, int fr, int fq) const {
;     ...
;             for (int m = 0; m < 4; ++m) { const size_t off = (size_t)(rowb + ai * HALF + m * 16) * 1024 + col0;
; #pragma unroll
;                 for (int bj = 0; bj < 2; ++bj) { f32x4 o[2];
;                     if (lat && rinB) { const u32x4 w = *(const u32x4*)(rinB + off + bj * 32);
;                         const f32x4 b0 = {__builtin_bit_cast(float, w.x << 16), __builtin_bit_cast(float, w.x & 0xffff0000u), __builtin_bit_cast(float, w.y << 16), __builtin_bit_cast(float, w.y & 0xffff0000u)};
;                         const f32x4 b1 = {__builtin_bit_cast(float, w.z << 16), __builtin_bit_cast(float, w.z & 0xffff0000u), __builtin_bit_cast(float, w.w << 16), __builtin_bit_cast(float, w.w & 0xffff0000u)};
;                         o[0] = b0 * 1.6817928305074290f + gv[bj][0] * acc[ai][bj][m][0]; o[1] = b1 * 1.6817928305074290f + gv[bj][1] * acc[ai][bj][m][1]; }
;                     else {
; #pragma unroll
;                     for (int n = 0; n < 2; ++n) { const f32x4 bs = *(const f32x4*)(ib + off + bj * 32 + n * 4); o[n] = bs * 1.6817928305074290f + gv[bj][n] * acc[ai][bj][m][n]; } }
;                     if (tobf) *(u32x4*)(vout + off + bj * 32) = pack8(o[0], o[1]);
;                     else { *(f32x4*)(ob + off + bj * 32) = o[0]; *(f32x4*)(ob + off + bj * 32 + 4) = o[1]; } }
.LBB0_1531:
	s_andn2_b64 vcc, exec, s[30:31]
	v_lshl_add_u64 v[192:193], v[196:197], 2, s[28:29]
	s_cbranch_vccnz .LBB0_1533
	s_waitcnt vmcnt(7)
	v_mov_b32_e32 v162, v208
	v_mov_b32_e32 v163, v209
	v_mov_b32_e32 v164, v210
	v_mov_b32_e32 v165, v211
	v_mov_b32_e32 v166, v226
	v_mov_b32_e32 v167, v227
	v_mov_b32_e32 v168, v228
	v_mov_b32_e32 v169, v229
	v_lshlrev_b32_e32 v251, 1, v250
	v_add_u32_e32 v251, 0xb0000, v251
	global_load_dwordx4 v[208:211], v251, s[28:29] offset:128
	global_load_dwordx4 v[226:229], v251, s[28:29] offset:144
	v_pk_mul_f32 v[164:165], v[164:165], s[86:87] op_sel_hi:[1,0]
	v_pk_mul_f32 v[162:163], v[162:163], s[86:87] op_sel_hi:[1,0]
	v_pk_fma_f32 v[164:165], v[40:41], v[160:161], v[164:165]
	v_pk_fma_f32 v[162:163], v[38:39], v[158:159], v[162:163]

; __device__ __forceinline__ u32x4 pack8(const f32x4 a, const f32x4 b) { u32x4 w; w.x = cvt_pk_bf16(a[0], a[1]); w.y = cvt_pk_bf16(a[2], a[3]); w.z = cvt_pk_bf16(b[0], b[1]); w.w = cvt_pk_bf16(b[2], b[3]); return w; }
;     __device__ __forceinline__ void operator()(const f32x4 (&acc)[2][2][4][2], const Unit& u, int wr, int wc, int fr, int fq) const {
;     ...
;             for (int m = 0; m < 4; ++m) { const size_t off = (size_t)(rowb + ai * HALF + m * 16) * 1024 + col0;
; #pragma unroll
;                 for (int bj = 0; bj < 2; ++bj) { f32x4 o[2];
;                     if (lat && rinB) { const u32x4 w = *(const u32x4*)(rinB + off + bj * 32);
;                         const f32x4 b0 = {__builtin_bit_cast(float, w.x << 16), __builtin_bit_cast(float, w.x & 0xffff0000u), __builtin_bit_cast(float, w.y << 16), __builtin_bit_cast(float, w.y & 0xffff0000u)};
;                         const f32x4 b1 = {__builtin_bit_cast(float, w.z << 16), __builtin_bit_cast(float, w.z & 0xffff0000u), __builtin_bit_cast(float, w.w << 16), __builtin_bit_cast(float, w.w & 0xffff0000u)};
;                         o[0] = b0 * 1.6817928305074290f + gv[bj][0] * acc[ai][bj][m][0]; o[1] = b1 * 1.6817928305074290f + gv[bj][1] * acc[ai][bj][m][1]; }
;                     else {
; #pragma unroll
;                     for (int n = 0; n < 2; ++n) { const f32x4 bs = *(const f32x4*)(ib + off + bj * 32 + n * 4); o[n] = bs * 1.6817928305074290f + gv[bj][n] * acc[ai][bj][m][n]; } }
;                     if (tobf) *(u32x4*)(vout + off + bj * 32) = pack8(o[0], o[1]);
;                     else { *(f32x4*)(ob + off + bj * 32) = o[0]; *(f32x4*)(ob + off + bj * 32 + 4) = o[1]; } }
.LBB0_1539:
	s_andn2_b64 vcc, exec, s[30:31]
	s_cbranch_vccnz .LBB0_1541
	s_waitcnt vmcnt(7)
	v_mov_b32_e32 v162, v230
	v_mov_b32_e32 v163, v231
	v_mov_b32_e32 v164, v232
	v_mov_b32_e32 v165, v233
	v_mov_b32_e32 v174, v234
	v_mov_b32_e32 v175, v235
	v_mov_b32_e32 v176, v236
	v_mov_b32_e32 v177, v237
	v_pk_mul_f32 v[164:165], v[164:165], s[86:87] op_sel_hi:[1,0]
	v_pk_mul_f32 v[162:163], v[162:163], s[86:87] op_sel_hi:[1,0]
	v_pk_fma_f32 v[168:169], v[20:21], v[152:153], v[164:165]
	v_pk_fma_f32 v[166:167], v[18:19], v[150:151], v[162:163]

; __device__ __forceinline__ u32x4 pack8(const f32x4 a, const f32x4 b) { u32x4 w; w.x = cvt_pk_bf16(a[0], a[1]); w.y = cvt_pk_bf16(a[2], a[3]); w.z = cvt_pk_bf16(b[0], b[1]); w.w = cvt_pk_bf16(b[2], b[3]); return w; }
;     __device__ __forceinline__ void operator()(const f32x4 (&acc)[2][2][4][2], const Unit& u, int wr, int wc, int fr, int fq) const {
;     ...
;             for (int m = 0; m < 4; ++m) { const size_t off = (size_t)(rowb + ai * HALF + m * 16) * 1024 + col0;
; #pragma unroll
;                 for (int bj = 0; bj < 2; ++bj) { f32x4 o[2];
;                     if (lat && rinB) { const u32x4 w = *(const u32x4*)(rinB + off + bj * 32);
;                         const f32x4 b0 = {__builtin_bit_cast(float, w.x << 16), __builtin_bit_cast(float, w.x & 0xffff0000u), __builtin_bit_cast(float, w.y << 16), __builtin_bit_cast(float, w.y & 0xffff0000u)};
;                         const f32x4 b1 = {__builtin_bit_cast(float, w.z << 16), __builtin_bit_cast(float, w.z & 0xffff0000u), __builtin_bit_cast(float, w.w << 16), __builtin_bit_cast(float, w.w & 0xffff0000u)};
;                         o[0] = b0 * 1.6817928305074290f + gv[bj][0] * acc[ai][bj][m][0]; o[1] = b1 * 1.6817928305074290f + gv[bj][1] * acc[ai][bj][m][1]; }
;                     else {
; #pragma unroll
;                     for (int n = 0; n < 2; ++n) { const f32x4 bs = *(const f32x4*)(ib + off + bj * 32 + n * 4); o[n] = bs * 1.6817928305074290f + gv[bj][n] * acc[ai][bj][m][n]; } }
;                     if (tobf) *(u32x4*)(vout + off + bj * 32) = pack8(o[0], o[1]);
;                     else { *(f32x4*)(ob + off + bj * 32) = o[0]; *(f32x4*)(ob + off + bj * 32 + 4) = o[1]; } }
.LBB0_1547:
	s_andn2_b64 vcc, exec, s[30:31]
	v_lshl_add_u64 v[170:171], v[174:175], 2, s[28:29]
	s_cbranch_vccnz .LBB0_1549
	s_waitcnt vmcnt(5)
	v_mov_b32_e32 v162, v238
	v_mov_b32_e32 v163, v239
	v_mov_b32_e32 v164, v240
	v_mov_b32_e32 v165, v241
	v_mov_b32_e32 v166, v242
	v_mov_b32_e32 v167, v243
	v_mov_b32_e32 v168, v244
	v_mov_b32_e32 v169, v245
	v_pk_mul_f32 v[164:165], v[164:165], s[86:87] op_sel_hi:[1,0]
	v_pk_mul_f32 v[162:163], v[162:163], s[86:87] op_sel_hi:[1,0]
	v_pk_fma_f32 v[164:165], v[24:25], v[160:161], v[164:165]
	v_pk_fma_f32 v[162:163], v[22:23], v[158:159], v[162:163]

; __device__ __forceinline__ u32x4 pack8(const f32x4 a, const f32x4 b) { u32x4 w; w.x = cvt_pk_bf16(a[0], a[1]); w.y = cvt_pk_bf16(a[2], a[3]); w.z = cvt_pk_bf16(b[0], b[1]); w.w = cvt_pk_bf16(b[2], b[3]); return w; }
;     __device__ __forceinline__ void operator()(const f32x4 (&acc)[2][2][4][2], const Unit& u, int wr, int wc, int fr, int fq) const {
;     ...
;             for (int m = 0; m < 4; ++m) { const size_t off = (size_t)(rowb + ai * HALF + m * 16) * 1024 + col0;
; #pragma unroll
;                 for (int bj = 0; bj < 2; ++bj) { f32x4 o[2];
;                     if (lat && rinB) { const u32x4 w = *(const u32x4*)(rinB + off + bj * 32);
;                         const f32x4 b0 = {__builtin_bit_cast(float, w.x << 16), __builtin_bit_cast(float, w.x & 0xffff0000u), __builtin_bit_cast(float, w.y << 16), __builtin_bit_cast(float, w.y & 0xffff0000u)};
;                         const f32x4 b1 = {__builtin_bit_cast(float, w.z << 16), __builtin_bit_cast(float, w.z & 0xffff0000u), __builtin_bit_cast(float, w.w << 16), __builtin_bit_cast(float, w.w & 0xffff0000u)};
;                         o[0] = b0 * 1.6817928305074290f + gv[bj][0] * acc[ai][bj][m][0]; o[1] = b1 * 1.6817928305074290f + gv[bj][1] * acc[ai][bj][m][1]; }
;                     else {
; #pragma unroll
;                     for (int n = 0; n < 2; ++n) { const f32x4 bs = *(const f32x4*)(ib + off + bj * 32 + n * 4); o[n] = bs * 1.6817928305074290f + gv[bj][n] * acc[ai][bj][m][n]; } }
;                     if (tobf) *(u32x4*)(vout + off + bj * 32) = pack8(o[0], o[1]);
;                     else { *(f32x4*)(ob + off + bj * 32) = o[0]; *(f32x4*)(ob + off + bj * 32 + 4) = o[1]; } }
.LBB0_1555:
	s_andn2_b64 vcc, exec, s[28:29]
	s_cbranch_vccnz .LBB0_1557
	s_waitcnt vmcnt(3)
	v_mov_b32_e32 v154, v208
	v_mov_b32_e32 v155, v209
	v_mov_b32_e32 v156, v210
	v_mov_b32_e32 v157, v211
	v_mov_b32_e32 v166, v226
	v_mov_b32_e32 v167, v227
	v_mov_b32_e32 v168, v228
	v_mov_b32_e32 v169, v229
	v_pk_mul_f32 v[156:157], v[156:157], s[86:87] op_sel_hi:[1,0]
	v_pk_mul_f32 v[154:155], v[154:155], s[86:87] op_sel_hi:[1,0]
	v_pk_fma_f32 v[156:157], v[8:9], v[152:153], v[156:157]
	v_pk_fma_f32 v[154:155], v[6:7], v[150:151], v[154:155]

; __device__ __forceinline__ u32x4 pack8(const f32x4 a, const f32x4 b) { u32x4 w; w.x = cvt_pk_bf16(a[0], a[1]); w.y = cvt_pk_bf16(a[2], a[3]); w.z = cvt_pk_bf16(b[0], b[1]); w.w = cvt_pk_bf16(b[2], b[3]); return w; }
;     __device__ __forceinline__ void operator()(const f32x4 (&acc)[2][2][4][2], const Unit& u, int wr, int wc, int fr, int fq) const {
;     ...
;             for (int m = 0; m < 4; ++m) { const size_t off = (size_t)(rowb + ai * HALF + m * 16) * 1024 + col0;
; #pragma unroll
;                 for (int bj = 0; bj < 2; ++bj) { f32x4 o[2];
;                     if (lat && rinB) { const u32x4 w = *(const u32x4*)(rinB + off + bj * 32);
;                         const f32x4 b0 = {__builtin_bit_cast(float, w.x << 16), __builtin_bit_cast(float, w.x & 0xffff0000u), __builtin_bit_cast(float, w.y << 16), __builtin_bit_cast(float, w.y & 0xffff0000u)};
;                         const f32x4 b1 = {__builtin_bit_cast(float, w.z << 16), __builtin_bit_cast(float, w.z & 0xffff0000u), __builtin_bit_cast(float, w.w << 16), __builtin_bit_cast(float, w.w & 0xffff0000u)};
;                         o[0] = b0 * 1.6817928305074290f + gv[bj][0] * acc[ai][bj][m][0]; o[1] = b1 * 1.6817928305074290f + gv[bj][1] * acc[ai][bj][m][1]; }
;                     else {
; #pragma unroll
;                     for (int n = 0; n < 2; ++n) { const f32x4 bs = *(const f32x4*)(ib + off + bj * 32 + n * 4); o[n] = bs * 1.6817928305074290f + gv[bj][n] * acc[ai][bj][m][n]; } }
;                     if (tobf) *(u32x4*)(vout + off + bj * 32) = pack8(o[0], o[1]);
;                     else { *(f32x4*)(ob + off + bj * 32) = o[0]; *(f32x4*)(ob + off + bj * 32 + 4) = o[1]; } }
.LBB0_1588:
	v_readlane_b32 s52, v255, 58
	s_andn2_b64 vcc, exec, s[26:27]
	v_lshl_add_u64 v[184:185], v[188:189], 2, s[24:25]
	v_readlane_b32 s53, v255, 59
	s_cbranch_vccnz .LBB0_1590
	v_lshlrev_b32_e32 v251, 1, v250
	global_load_dwordx4 v[208:211], v251, s[24:25]
	global_load_dwordx4 v[226:229], v251, s[24:25] offset:16
	v_lshlrev_b32_e32 v251, 1, v250
	global_load_dwordx4 v[230:233], v251, s[24:25] offset:128
	global_load_dwordx4 v[234:237], v251, s[24:25] offset:144
	v_lshlrev_b32_e32 v251, 1, v250
	v_add_u32_e32 v251, 0x10000, v251
	global_load_dwordx4 v[238:241], v251, s[24:25]
	global_load_dwordx4 v[242:245], v251, s[24:25] offset:16
	s_waitcnt vmcnt(4)
	v_mov_b32_e32 v162, v208
	v_mov_b32_e32 v163, v209
	v_mov_b32_e32 v164, v210
	v_mov_b32_e32 v165, v211
	v_mov_b32_e32 v166, v226
	v_mov_b32_e32 v167, v227
	v_mov_b32_e32 v168, v228
	v_mov_b32_e32 v169, v229
	v_lshlrev_b32_e32 v251, 1, v250
	v_add_u32_e32 v251, 0x10000, v251
	global_load_dwordx4 v[208:211], v251, s[24:25] offset:128
	global_load_dwordx4 v[226:229], v251, s[24:25] offset:144
	v_pk_mul_f32 v[164:165], v[164:165], s[86:87] op_sel_hi:[1,0]
	v_pk_mul_f32 v[162:163], v[162:163], s[86:87] op_sel_hi:[1,0]
	v_pk_fma_f32 v[164:165], v[160:161], v[72:73], v[164:165]
	v_pk_fma_f32 v[162:163], v[158:159], v[70:71], v[162:163]

; __device__ __forceinline__ u32x4 pack8(const f32x4 a, const f32x4 b) { u32x4 w; w.x = cvt_pk_bf16(a[0], a[1]); w.y = cvt_pk_bf16(a[2], a[3]); w.z = cvt_pk_bf16(b[0], b[1]); w.w = cvt_pk_bf16(b[2], b[3]); return w; }
;     __device__ __forceinline__ void operator()(const f32x4 (&acc)[2][2][4][2], const Unit& u, int wr, int wc, int fr, int fq) const {
;     ...
;             for (int m = 0; m < 4; ++m) { const size_t off = (size_t)(rowb + ai * HALF + m * 16) * 1024 + col0;
; #pragma unroll
;                 for (int bj = 0; bj < 2; ++bj) { f32x4 o[2];
;                     if (lat && rinB) { const u32x4 w = *(const u32x4*)(rinB + off + bj * 32);
;                         const f32x4 b0 = {__builtin_bit_cast(float, w.x << 16), __builtin_bit_cast(float, w.x & 0xffff0000u), __builtin_bit_cast(float, w.y << 16), __builtin_bit_cast(float, w.y & 0xffff0000u)};
;                         const f32x4 b1 = {__builtin_bit_cast(float, w.z << 16), __builtin_bit_cast(float, w.z & 0xffff0000u), __builtin_bit_cast(float, w.w << 16), __builtin_bit_cast(float, w.w & 0xffff0000u)};
;                         o[0] = b0 * 1.6817928305074290f + gv[bj][0] * acc[ai][bj][m][0]; o[1] = b1 * 1.6817928305074290f + gv[bj][1] * acc[ai][bj][m][1]; }
;                     else {
; #pragma unroll
;                     for (int n = 0; n < 2; ++n) { const f32x4 bs = *(const f32x4*)(ib + off + bj * 32 + n * 4); o[n] = bs * 1.6817928305074290f + gv[bj][n] * acc[ai][bj][m][n]; } }
;                     if (tobf) *(u32x4*)(vout + off + bj * 32) = pack8(o[0], o[1]);
;                     else { *(f32x4*)(ob + off + bj * 32) = o[0]; *(f32x4*)(ob + off + bj * 32 + 4) = o[1]; } }
.LBB0_1596:
	s_andn2_b64 vcc, exec, s[26:27]
	s_cbranch_vccnz .LBB0_1598
	s_waitcnt vmcnt(5)
	v_mov_b32_e32 v154, v230
	v_mov_b32_e32 v155, v231
	v_mov_b32_e32 v156, v232
	v_mov_b32_e32 v157, v233
	v_mov_b32_e32 v166, v234
	v_mov_b32_e32 v167, v235
	v_mov_b32_e32 v168, v236
	v_mov_b32_e32 v169, v237
	v_lshlrev_b32_e32 v251, 1, v250
	v_add_u32_e32 v251, 0x20000, v251
	global_load_dwordx4 v[230:233], v251, s[24:25]
	global_load_dwordx4 v[234:237], v251, s[24:25] offset:16
	v_pk_mul_f32 v[156:157], v[156:157], s[86:87] op_sel_hi:[1,0]
	v_pk_mul_f32 v[154:155], v[154:155], s[86:87] op_sel_hi:[1,0]
	v_pk_fma_f32 v[156:157], v[152:153], v[56:57], v[156:157]
	v_pk_fma_f32 v[154:155], v[150:151], v[54:55], v[154:155]

; __device__ __forceinline__ u32x4 pack8(const f32x4 a, const f32x4 b) { u32x4 w; w.x = cvt_pk_bf16(a[0], a[1]); w.y = cvt_pk_bf16(a[2], a[3]); w.z = cvt_pk_bf16(b[0], b[1]); w.w = cvt_pk_bf16(b[2], b[3]); return w; }
;     __device__ __forceinline__ void operator()(const f32x4 (&acc)[2][2][4][2], const Unit& u, int wr, int wc, int fr, int fq) const {
;     ...
;             for (int m = 0; m < 4; ++m) { const size_t off = (size_t)(rowb + ai * HALF + m * 16) * 1024 + col0;
; #pragma unroll
;                 for (int bj = 0; bj < 2; ++bj) { f32x4 o[2];
;                     if (lat && rinB) { const u32x4 w = *(const u32x4*)(rinB + off + bj * 32);
;                         const f32x4 b0 = {__builtin_bit_cast(float, w.x << 16), __builtin_bit_cast(float, w.x & 0xffff0000u), __builtin_bit_cast(float, w.y << 16), __builtin_bit_cast(float, w.y & 0xffff0000u)};
;                         const f32x4 b1 = {__builtin_bit_cast(float, w.z << 16), __builtin_bit_cast(float, w.z & 0xffff0000u), __builtin_bit_cast(float, w.w << 16), __builtin_bit_cast(float, w.w & 0xffff0000u)};
;                         o[0] = b0 * 1.6817928305074290f + gv[bj][0] * acc[ai][bj][m][0]; o[1] = b1 * 1.6817928305074290f + gv[bj][1] * acc[ai][bj][m][1]; }
;                     else {
; #pragma unroll
;                     for (int n = 0; n < 2; ++n) { const f32x4 bs = *(const f32x4*)(ib + off + bj * 32 + n * 4); o[n] = bs * 1.6817928305074290f + gv[bj][n] * acc[ai][bj][m][n]; } }
;                     if (tobf) *(u32x4*)(vout + off + bj * 32) = pack8(o[0], o[1]);
;                     else { *(f32x4*)(ob + off + bj * 32) = o[0]; *(f32x4*)(ob + off + bj * 32 + 4) = o[1]; } }
.LBB0_1604:
	s_andn2_b64 vcc, exec, s[26:27]
	v_lshl_add_u64 v[154:155], v[158:159], 2, s[24:25]
	s_cbranch_vccnz .LBB0_1606
	s_waitcnt vmcnt(6)
	v_mov_b32_e32 v146, v238
	v_mov_b32_e32 v147, v239
	v_mov_b32_e32 v148, v240
	v_mov_b32_e32 v149, v241
	v_mov_b32_e32 v150, v242
	v_mov_b32_e32 v151, v243
	v_mov_b32_e32 v152, v244
	v_mov_b32_e32 v153, v245
	v_lshlrev_b32_e32 v251, 1, v250
	v_add_u32_e32 v251, 0x20000, v251
	global_load_dwordx4 v[238:241], v251, s[24:25] offset:128
	global_load_dwordx4 v[242:245], v251, s[24:25] offset:144
	v_pk_mul_f32 v[148:149], v[148:149], s[86:87] op_sel_hi:[1,0]
	v_pk_mul_f32 v[146:147], v[146:147], s[86:87] op_sel_hi:[1,0]
	v_pk_fma_f32 v[148:149], v[144:145], v[72:73], v[148:149]
	v_pk_fma_f32 v[146:147], v[142:143], v[70:71], v[146:147]

; __device__ __forceinline__ u32x4 pack8(const f32x4 a, const f32x4 b) { u32x4 w; w.x = cvt_pk_bf16(a[0], a[1]); w.y = cvt_pk_bf16(a[2], a[3]); w.z = cvt_pk_bf16(b[0], b[1]); w.w = cvt_pk_bf16(b[2], b[3]); return w; }
;     __device__ __forceinline__ void operator()(const f32x4 (&acc)[2][2][4][2], const Unit& u, int wr, int wc, int fr, int fq) const {
;     ...
;             for (int m = 0; m < 4; ++m) { const size_t off = (size_t)(rowb + ai * HALF + m * 16) * 1024 + col0;
; #pragma unroll
;                 for (int bj = 0; bj < 2; ++bj) { f32x4 o[2];
;                     if (lat && rinB) { const u32x4 w = *(const u32x4*)(rinB + off + bj * 32);
;                         const f32x4 b0 = {__builtin_bit_cast(float, w.x << 16), __builtin_bit_cast(float, w.x & 0xffff0000u), __builtin_bit_cast(float, w.y << 16), __builtin_bit_cast(float, w.y & 0xffff0000u)};
;                         const f32x4 b1 = {__builtin_bit_cast(float, w.z << 16), __builtin_bit_cast(float, w.z & 0xffff0000u), __builtin_bit_cast(float, w.w << 16), __builtin_bit_cast(float, w.w & 0xffff0000u)};
;                         o[0] = b0 * 1.6817928305074290f + gv[bj][0] * acc[ai][bj][m][0]; o[1] = b1 * 1.6817928305074290f + gv[bj][1] * acc[ai][bj][m][1]; }
;                     else {
; #pragma unroll
;                     for (int n = 0; n < 2; ++n) { const f32x4 bs = *(const f32x4*)(ib + off + bj * 32 + n * 4); o[n] = bs * 1.6817928305074290f + gv[bj][n] * acc[ai][bj][m][n]; } }
;                     if (tobf) *(u32x4*)(vout + off + bj * 32) = pack8(o[0], o[1]);
;                     else { *(f32x4*)(ob + off + bj * 32) = o[0]; *(f32x4*)(ob + off + bj * 32 + 4) = o[1]; } }
.LBB0_1612:
	s_andn2_b64 vcc, exec, s[26:27]
	s_cbranch_vccnz .LBB0_1614
	s_waitcnt vmcnt(7)
	v_mov_b32_e32 v138, v208
	v_mov_b32_e32 v139, v209
	v_mov_b32_e32 v140, v210
	v_mov_b32_e32 v141, v211
	v_mov_b32_e32 v142, v226
	v_mov_b32_e32 v143, v227
	v_mov_b32_e32 v144, v228
	v_mov_b32_e32 v145, v229
	v_lshlrev_b32_e32 v251, 1, v250
	v_add_u32_e32 v251, 0x30000, v251
	global_load_dwordx4 v[208:211], v251, s[24:25]
	global_load_dwordx4 v[226:229], v251, s[24:25] offset:16
	v_pk_mul_f32 v[140:141], v[140:141], s[86:87] op_sel_hi:[1,0]
	v_pk_mul_f32 v[138:139], v[138:139], s[86:87] op_sel_hi:[1,0]
	v_pk_fma_f32 v[140:141], v[136:137], v[56:57], v[140:141]
	v_pk_fma_f32 v[138:139], v[134:135], v[54:55], v[138:139]

; __device__ __forceinline__ u32x4 pack8(const f32x4 a, const f32x4 b) { u32x4 w; w.x = cvt_pk_bf16(a[0], a[1]); w.y = cvt_pk_bf16(a[2], a[3]); w.z = cvt_pk_bf16(b[0], b[1]); w.w = cvt_pk_bf16(b[2], b[3]); return w; }
;     __device__ __forceinline__ void operator()(const f32x4 (&acc)[2][2][4][2], const Unit& u, int wr, int wc, int fr, int fq) const {
;     ...
;             for (int m = 0; m < 4; ++m) { const size_t off = (size_t)(rowb + ai * HALF + m * 16) * 1024 + col0;
; #pragma unroll
;                 for (int bj = 0; bj < 2; ++bj) { f32x4 o[2];
;                     if (lat && rinB) { const u32x4 w = *(const u32x4*)(rinB + off + bj * 32);
;                         const f32x4 b0 = {__builtin_bit_cast(float, w.x << 16), __builtin_bit_cast(float, w.x & 0xffff0000u), __builtin_bit_cast(float, w.y << 16), __builtin_bit_cast(float, w.y & 0xffff0000u)};
;                         const f32x4 b1 = {__builtin_bit_cast(float, w.z << 16), __builtin_bit_cast(float, w.z & 0xffff0000u), __builtin_bit_cast(float, w.w << 16), __builtin_bit_cast(float, w.w & 0xffff0000u)};
;                         o[0] = b0 * 1.6817928305074290f + gv[bj][0] * acc[ai][bj][m][0]; o[1] = b1 * 1.6817928305074290f + gv[bj][1] * acc[ai][bj][m][1]; }
;                     else {
; #pragma unroll
;                     for (int n = 0; n < 2; ++n) { const f32x4 bs = *(const f32x4*)(ib + off + bj * 32 + n * 4); o[n] = bs * 1.6817928305074290f + gv[bj][n] * acc[ai][bj][m][n]; } }
;                     if (tobf) *(u32x4*)(vout + off + bj * 32) = pack8(o[0], o[1]);
;                     else { *(f32x4*)(ob + off + bj * 32) = o[0]; *(f32x4*)(ob + off + bj * 32 + 4) = o[1]; } }
.LBB0_1620:
	s_andn2_b64 vcc, exec, s[26:27]
	v_lshl_add_u64 v[138:139], v[142:143], 2, s[24:25]
	s_cbranch_vccnz .LBB0_1622
	s_waitcnt vmcnt(7)
	v_mov_b32_e32 v130, v230
	v_mov_b32_e32 v131, v231
	v_mov_b32_e32 v132, v232
	v_mov_b32_e32 v133, v233
	v_mov_b32_e32 v134, v234
	v_mov_b32_e32 v135, v235
	v_mov_b32_e32 v136, v236
	v_mov_b32_e32 v137, v237
	v_lshlrev_b32_e32 v251, 1, v250
	v_add_u32_e32 v251, 0x30000, v251
	global_load_dwordx4 v[230:233], v251, s[24:25] offset:128
	global_load_dwordx4 v[234:237], v251, s[24:25] offset:144
	v_pk_mul_f32 v[132:133], v[132:133], s[86:87] op_sel_hi:[1,0]
	v_pk_mul_f32 v[130:131], v[130:131], s[86:87] op_sel_hi:[1,0]
	v_pk_fma_f32 v[132:133], v[112:113], v[72:73], v[132:133]
	v_pk_fma_f32 v[130:131], v[110:111], v[70:71], v[130:131]

; __device__ __forceinline__ u32x4 pack8(const f32x4 a, const f32x4 b) { u32x4 w; w.x = cvt_pk_bf16(a[0], a[1]); w.y = cvt_pk_bf16(a[2], a[3]); w.z = cvt_pk_bf16(b[0], b[1]); w.w = cvt_pk_bf16(b[2], b[3]); return w; }
;     __device__ __forceinline__ void operator()(const f32x4 (&acc)[2][2][4][2], const Unit& u, int wr, int wc, int fr, int fq) const {
;     ...
;             for (int m = 0; m < 4; ++m) { const size_t off = (size_t)(rowb + ai * HALF + m * 16) * 1024 + col0;
; #pragma unroll
;                 for (int bj = 0; bj < 2; ++bj) { f32x4 o[2];
;                     if (lat && rinB) { const u32x4 w = *(const u32x4*)(rinB + off + bj * 32);
;                         const f32x4 b0 = {__builtin_bit_cast(float, w.x << 16), __builtin_bit_cast(float, w.x & 0xffff0000u), __builtin_bit_cast(float, w.y << 16), __builtin_bit_cast(float, w.y & 0xffff0000u)};
;                         const f32x4 b1 = {__builtin_bit_cast(float, w.z << 16), __builtin_bit_cast(float, w.z & 0xffff0000u), __builtin_bit_cast(float, w.w << 16), __builtin_bit_cast(float, w.w & 0xffff0000u)};
;                         o[0] = b0 * 1.6817928305074290f + gv[bj][0] * acc[ai][bj][m][0]; o[1] = b1 * 1.6817928305074290f + gv[bj][1] * acc[ai][bj][m][1]; }
;                     else {
; #pragma unroll
;                     for (int n = 0; n < 2; ++n) { const f32x4 bs = *(const f32x4*)(ib + off + bj * 32 + n * 4); o[n] = bs * 1.6817928305074290f + gv[bj][n] * acc[ai][bj][m][n]; } }
;                     if (tobf) *(u32x4*)(vout + off + bj * 32) = pack8(o[0], o[1]);
;                     else { *(f32x4*)(ob + off + bj * 32) = o[0]; *(f32x4*)(ob + off + bj * 32 + 4) = o[1]; } }
.LBB0_1628:
	s_andn2_b64 vcc, exec, s[26:27]
	s_cbranch_vccnz .LBB0_1630
	s_waitcnt vmcnt(7)
	v_mov_b32_e32 v106, v238
	v_mov_b32_e32 v107, v239
	v_mov_b32_e32 v108, v240
	v_mov_b32_e32 v109, v241
	v_mov_b32_e32 v134, v242
	v_mov_b32_e32 v135, v243
	v_mov_b32_e32 v136, v244
	v_mov_b32_e32 v137, v245
	v_lshlrev_b32_e32 v251, 1, v250
	v_add_u32_e32 v251, 0x80000, v251
	global_load_dwordx4 v[238:241], v251, s[24:25]
	global_load_dwordx4 v[242:245], v251, s[24:25] offset:16
	v_pk_mul_f32 v[108:109], v[108:109], s[86:87] op_sel_hi:[1,0]
	v_pk_mul_f32 v[106:107], v[106:107], s[86:87] op_sel_hi:[1,0]
	v_pk_fma_f32 v[108:109], v[104:105], v[56:57], v[108:109]
	v_pk_fma_f32 v[106:107], v[102:103], v[54:55], v[106:107]

; __device__ __forceinline__ u32x4 pack8(const f32x4 a, const f32x4 b) { u32x4 w; w.x = cvt_pk_bf16(a[0], a[1]); w.y = cvt_pk_bf16(a[2], a[3]); w.z = cvt_pk_bf16(b[0], b[1]); w.w = cvt_pk_bf16(b[2], b[3]); return w; }
;     __device__ __forceinline__ void operator()(const f32x4 (&acc)[2][2][4][2], const Unit& u, int wr, int wc, int fr, int fq) const {
;     ...
;             for (int m = 0; m < 4; ++m) { const size_t off = (size_t)(rowb + ai * HALF + m * 16) * 1024 + col0;
; #pragma unroll
;                 for (int bj = 0; bj < 2; ++bj) { f32x4 o[2];
;                     if (lat && rinB) { const u32x4 w = *(const u32x4*)(rinB + off + bj * 32);
;                         const f32x4 b0 = {__builtin_bit_cast(float, w.x << 16), __builtin_bit_cast(float, w.x & 0xffff0000u), __builtin_bit_cast(float, w.y << 16), __builtin_bit_cast(float, w.y & 0xffff0000u)};
;                         const f32x4 b1 = {__builtin_bit_cast(float, w.z << 16), __builtin_bit_cast(float, w.z & 0xffff0000u), __builtin_bit_cast(float, w.w << 16), __builtin_bit_cast(float, w.w & 0xffff0000u)};
;                         o[0] = b0 * 1.6817928305074290f + gv[bj][0] * acc[ai][bj][m][0]; o[1] = b1 * 1.6817928305074290f + gv[bj][1] * acc[ai][bj][m][1]; }
;                     else {
; #pragma unroll
;                     for (int n = 0; n < 2; ++n) { const f32x4 bs = *(const f32x4*)(ib + off + bj * 32 + n * 4); o[n] = bs * 1.6817928305074290f + gv[bj][n] * acc[ai][bj][m][n]; } }
;                     if (tobf) *(u32x4*)(vout + off + bj * 32) = pack8(o[0], o[1]);
;                     else { *(f32x4*)(ob + off + bj * 32) = o[0]; *(f32x4*)(ob + off + bj * 32 + 4) = o[1]; } }
.LBB0_1636:
	s_andn2_b64 vcc, exec, s[26:27]
	v_lshl_add_u64 v[106:107], v[110:111], 2, s[24:25]
	s_cbranch_vccnz .LBB0_1638
	s_waitcnt vmcnt(7)
	v_mov_b32_e32 v98, v208
	v_mov_b32_e32 v99, v209
	v_mov_b32_e32 v100, v210
	v_mov_b32_e32 v101, v211
	v_mov_b32_e32 v102, v226
	v_mov_b32_e32 v103, v227
	v_mov_b32_e32 v104, v228
	v_mov_b32_e32 v105, v229
	v_lshlrev_b32_e32 v251, 1, v250
	v_add_u32_e32 v251, 0x80000, v251
	global_load_dwordx4 v[208:211], v251, s[24:25] offset:128
	global_load_dwordx4 v[226:229], v251, s[24:25] offset:144
	v_pk_mul_f32 v[100:101], v[100:101], s[86:87] op_sel_hi:[1,0]
	v_pk_mul_f32 v[98:99], v[98:99], s[86:87] op_sel_hi:[1,0]
	v_pk_fma_f32 v[100:101], v[96:97], v[72:73], v[100:101]
	v_pk_fma_f32 v[98:99], v[94:95], v[70:71], v[98:99]

; __device__ __forceinline__ u32x4 pack8(const f32x4 a, const f32x4 b) { u32x4 w; w.x = cvt_pk_bf16(a[0], a[1]); w.y = cvt_pk_bf16(a[2], a[3]); w.z = cvt_pk_bf16(b[0], b[1]); w.w = cvt_pk_bf16(b[2], b[3]); return w; }
;     __device__ __forceinline__ void operator()(const f32x4 (&acc)[2][2][4][2], const Unit& u, int wr, int wc, int fr, int fq) const {
;     ...
;             for (int m = 0; m < 4; ++m) { const size_t off = (size_t)(rowb + ai * HALF + m * 16) * 1024 + col0;
; #pragma unroll
;                 for (int bj = 0; bj < 2; ++bj) { f32x4 o[2];
;                     if (lat && rinB) { const u32x4 w = *(const u32x4*)(rinB + off + bj * 32);
;                         const f32x4 b0 = {__builtin_bit_cast(float, w.x << 16), __builtin_bit_cast(float, w.x & 0xffff0000u), __builtin_bit_cast(float, w.y << 16), __builtin_bit_cast(float, w.y & 0xffff0000u)};
;                         const f32x4 b1 = {__builtin_bit_cast(float, w.z << 16), __builtin_bit_cast(float, w.z & 0xffff0000u), __builtin_bit_cast(float, w.w << 16), __builtin_bit_cast(float, w.w & 0xffff0000u)};
;                         o[0] = b0 * 1.6817928305074290f + gv[bj][0] * acc[ai][bj][m][0]; o[1] = b1 * 1.6817928305074290f + gv[bj][1] * acc[ai][bj][m][1]; }
;                     else {
; #pragma unroll
;                     for (int n = 0; n < 2; ++n) { const f32x4 bs = *(const f32x4*)(ib + off + bj * 32 + n * 4); o[n] = bs * 1.6817928305074290f + gv[bj][n] * acc[ai][bj][m][n]; } }
;                     if (tobf) *(u32x4*)(vout + off + bj * 32) = pack8(o[0], o[1]);
;                     else { *(f32x4*)(ob + off + bj * 32) = o[0]; *(f32x4*)(ob + off + bj * 32 + 4) = o[1]; } }
.LBB0_1644:
	s_andn2_b64 vcc, exec, s[26:27]
	s_cbranch_vccnz .LBB0_1646
	s_waitcnt vmcnt(7)
	v_mov_b32_e32 v90, v230
	v_mov_b32_e32 v91, v231
	v_mov_b32_e32 v92, v232
	v_mov_b32_e32 v93, v233
	v_mov_b32_e32 v102, v234
	v_mov_b32_e32 v103, v235
	v_mov_b32_e32 v104, v236
	v_mov_b32_e32 v105, v237
	v_lshlrev_b32_e32 v251, 1, v250
	v_add_u32_e32 v251, 0x90000, v251
	global_load_dwordx4 v[230:233], v251, s[24:25]
	global_load_dwordx4 v[234:237], v251, s[24:25] offset:16
	v_pk_mul_f32 v[92:93], v[92:93], s[86:87] op_sel_hi:[1,0]
	v_pk_mul_f32 v[90:91], v[90:91], s[86:87] op_sel_hi:[1,0]
	v_pk_fma_f32 v[92:93], v[88:89], v[56:57], v[92:93]
	v_pk_fma_f32 v[90:91], v[86:87], v[54:55], v[90:91]

; __device__ __forceinline__ u32x4 pack8(const f32x4 a, const f32x4 b) { u32x4 w; w.x = cvt_pk_bf16(a[0], a[1]); w.y = cvt_pk_bf16(a[2], a[3]); w.z = cvt_pk_bf16(b[0], b[1]); w.w = cvt_pk_bf16(b[2], b[3]); return w; }
;     __device__ __forceinline__ void operator()(const f32x4 (&acc)[2][2][4][2], const Unit& u, int wr, int wc, int fr, int fq) const {
;     ...
;             for (int m = 0; m < 4; ++m) { const size_t off = (size_t)(rowb + ai * HALF + m * 16) * 1024 + col0;
; #pragma unroll
;                 for (int bj = 0; bj < 2; ++bj) { f32x4 o[2];
;                     if (lat && rinB) { const u32x4 w = *(const u32x4*)(rinB + off + bj * 32);
;                         const f32x4 b0 = {__builtin_bit_cast(float, w.x << 16), __builtin_bit_cast(float, w.x & 0xffff0000u), __builtin_bit_cast(float, w.y << 16), __builtin_bit_cast(float, w.y & 0xffff0000u)};
;                         const f32x4 b1 = {__builtin_bit_cast(float, w.z << 16), __builtin_bit_cast(float, w.z & 0xffff0000u), __builtin_bit_cast(float, w.w << 16), __builtin_bit_cast(float, w.w & 0xffff0000u)};
;                         o[0] = b0 * 1.6817928305074290f + gv[bj][0] * acc[ai][bj][m][0]; o[1] = b1 * 1.6817928305074290f + gv[bj][1] * acc[ai][bj][m][1]; }
;                     else {
; #pragma unroll
;                     for (int n = 0; n < 2; ++n) { const f32x4 bs = *(const f32x4*)(ib + off + bj * 32 + n * 4); o[n] = bs * 1.6817928305074290f + gv[bj][n] * acc[ai][bj][m][n]; } }
;                     if (tobf) *(u32x4*)(vout + off + bj * 32) = pack8(o[0], o[1]);
;                     else { *(f32x4*)(ob + off + bj * 32) = o[0]; *(f32x4*)(ob + off + bj * 32 + 4) = o[1]; } }
.LBB0_1652:
	s_andn2_b64 vcc, exec, s[26:27]
	v_lshl_add_u64 v[90:91], v[94:95], 2, s[24:25]
	s_cbranch_vccnz .LBB0_1654
	s_waitcnt vmcnt(7)
	v_mov_b32_e32 v82, v238
	v_mov_b32_e32 v83, v239
	v_mov_b32_e32 v84, v240
	v_mov_b32_e32 v85, v241
	v_mov_b32_e32 v86, v242
	v_mov_b32_e32 v87, v243
	v_mov_b32_e32 v88, v244
	v_mov_b32_e32 v89, v245
	v_lshlrev_b32_e32 v251, 1, v250
	v_add_u32_e32 v251, 0x90000, v251
	global_load_dwordx4 v[238:241], v251, s[24:25] offset:128
	global_load_dwordx4 v[242:245], v251, s[24:25] offset:144
	v_pk_mul_f32 v[84:85], v[84:85], s[86:87] op_sel_hi:[1,0]
	v_pk_mul_f32 v[82:83], v[82:83], s[86:87] op_sel_hi:[1,0]
	v_pk_fma_f32 v[84:85], v[80:81], v[72:73], v[84:85]
	v_pk_fma_f32 v[82:83], v[78:79], v[70:71], v[82:83]

; __device__ __forceinline__ u32x4 pack8(const f32x4 a, const f32x4 b) { u32x4 w; w.x = cvt_pk_bf16(a[0], a[1]); w.y = cvt_pk_bf16(a[2], a[3]); w.z = cvt_pk_bf16(b[0], b[1]); w.w = cvt_pk_bf16(b[2], b[3]); return w; }
;     __device__ __forceinline__ void operator()(const f32x4 (&acc)[2][2][4][2], const Unit& u, int wr, int wc, int fr, int fq) const {
;     ...
;             for (int m = 0; m < 4; ++m) { const size_t off = (size_t)(rowb + ai * HALF + m * 16) * 1024 + col0;
; #pragma unroll
;                 for (int bj = 0; bj < 2; ++bj) { f32x4 o[2];
;                     if (lat && rinB) { const u32x4 w = *(const u32x4*)(rinB + off + bj * 32);
;                         const f32x4 b0 = {__builtin_bit_cast(float, w.x << 16), __builtin_bit_cast(float, w.x & 0xffff0000u), __builtin_bit_cast(float, w.y << 16), __builtin_bit_cast(float, w.y & 0xffff0000u)};
;                         const f32x4 b1 = {__builtin_bit_cast(float, w.z << 16), __builtin_bit_cast(float, w.z & 0xffff0000u), __builtin_bit_cast(float, w.w << 16), __builtin_bit_cast(float, w.w & 0xffff0000u)};
;                         o[0] = b0 * 1.6817928305074290f + gv[bj][0] * acc[ai][bj][m][0]; o[1] = b1 * 1.6817928305074290f + gv[bj][1] * acc[ai][bj][m][1]; }
;                     else {
; #pragma unroll
;                     for (int n = 0; n < 2; ++n) { const f32x4 bs = *(const f32x4*)(ib + off + bj * 32 + n * 4); o[n] = bs * 1.6817928305074290f + gv[bj][n] * acc[ai][bj][m][n]; } }
;                     if (tobf) *(u32x4*)(vout + off + bj * 32) = pack8(o[0], o[1]);
;                     else { *(f32x4*)(ob + off + bj * 32) = o[0]; *(f32x4*)(ob + off + bj * 32 + 4) = o[1]; } }
.LBB0_1660:
	s_andn2_b64 vcc, exec, s[26:27]
	s_cbranch_vccnz .LBB0_1662
	s_waitcnt vmcnt(7)
	v_mov_b32_e32 v74, v208
	v_mov_b32_e32 v75, v209
	v_mov_b32_e32 v76, v210
	v_mov_b32_e32 v77, v211
	v_mov_b32_e32 v86, v226
	v_mov_b32_e32 v87, v227
	v_mov_b32_e32 v88, v228
	v_mov_b32_e32 v89, v229
	v_lshlrev_b32_e32 v251, 1, v250
	v_add_u32_e32 v251, 0xa0000, v251
	global_load_dwordx4 v[208:211], v251, s[24:25]
	global_load_dwordx4 v[226:229], v251, s[24:25] offset:16
	v_pk_mul_f32 v[76:77], v[76:77], s[86:87] op_sel_hi:[1,0]
	v_pk_mul_f32 v[74:75], v[74:75], s[86:87] op_sel_hi:[1,0]
	v_pk_fma_f32 v[76:77], v[64:65], v[56:57], v[76:77]
	v_pk_fma_f32 v[74:75], v[62:63], v[54:55], v[74:75]

; __device__ __forceinline__ u32x4 pack8(const f32x4 a, const f32x4 b) { u32x4 w; w.x = cvt_pk_bf16(a[0], a[1]); w.y = cvt_pk_bf16(a[2], a[3]); w.z = cvt_pk_bf16(b[0], b[1]); w.w = cvt_pk_bf16(b[2], b[3]); return w; }
;     __device__ __forceinline__ void operator()(const f32x4 (&acc)[2][2][4][2], const Unit& u, int wr, int wc, int fr, int fq) const {
;     ...
;             for (int m = 0; m < 4; ++m) { const size_t off = (size_t)(rowb + ai * HALF + m * 16) * 1024 + col0;
; #pragma unroll
;                 for (int bj = 0; bj < 2; ++bj) { f32x4 o[2];
;                     if (lat && rinB) { const u32x4 w = *(const u32x4*)(rinB + off + bj * 32);
;                         const f32x4 b0 = {__builtin_bit_cast(float, w.x << 16), __builtin_bit_cast(float, w.x & 0xffff0000u), __builtin_bit_cast(float, w.y << 16), __builtin_bit_cast(float, w.y & 0xffff0000u)};
;                         const f32x4 b1 = {__builtin_bit_cast(float, w.z << 16), __builtin_bit_cast(float, w.z & 0xffff0000u), __builtin_bit_cast(float, w.w << 16), __builtin_bit_cast(float, w.w & 0xffff0000u)};
;                         o[0] = b0 * 1.6817928305074290f + gv[bj][0] * acc[ai][bj][m][0]; o[1] = b1 * 1.6817928305074290f + gv[bj][1] * acc[ai][bj][m][1]; }
;                     else {
; #pragma unroll
;                     for (int n = 0; n < 2; ++n) { const f32x4 bs = *(const f32x4*)(ib + off + bj * 32 + n * 4); o[n] = bs * 1.6817928305074290f + gv[bj][n] * acc[ai][bj][m][n]; } }
;                     if (tobf) *(u32x4*)(vout + off + bj * 32) = pack8(o[0], o[1]);
;                     else { *(f32x4*)(ob + off + bj * 32) = o[0]; *(f32x4*)(ob + off + bj * 32 + 4) = o[1]; } }
.LBB0_1668:
	s_andn2_b64 vcc, exec, s[26:27]
	v_lshl_add_u64 v[74:75], v[78:79], 2, s[24:25]
	s_cbranch_vccnz .LBB0_1670
	s_waitcnt vmcnt(7)
	v_mov_b32_e32 v58, v230
	v_mov_b32_e32 v59, v231
	v_mov_b32_e32 v60, v232
	v_mov_b32_e32 v61, v233
	v_mov_b32_e32 v62, v234
	v_mov_b32_e32 v63, v235
	v_mov_b32_e32 v64, v236
	v_mov_b32_e32 v65, v237
	v_lshlrev_b32_e32 v251, 1, v250
	v_add_u32_e32 v251, 0xa0000, v251
	global_load_dwordx4 v[230:233], v251, s[24:25] offset:128
	global_load_dwordx4 v[234:237], v251, s[24:25] offset:144
	v_pk_mul_f32 v[60:61], v[60:61], s[86:87] op_sel_hi:[1,0]
	v_pk_mul_f32 v[58:59], v[58:59], s[86:87] op_sel_hi:[1,0]
	v_pk_fma_f32 v[60:61], v[48:49], v[72:73], v[60:61]
	v_pk_fma_f32 v[58:59], v[46:47], v[70:71], v[58:59]

; __device__ __forceinline__ u32x4 pack8(const f32x4 a, const f32x4 b) { u32x4 w; w.x = cvt_pk_bf16(a[0], a[1]); w.y = cvt_pk_bf16(a[2], a[3]); w.z = cvt_pk_bf16(b[0], b[1]); w.w = cvt_pk_bf16(b[2], b[3]); return w; }
;     __device__ __forceinline__ void operator()(const f32x4 (&acc)[2][2][4][2], const Unit& u, int wr, int wc, int fr, int fq) const {
;     ...
;             for (int m = 0; m < 4; ++m) { const size_t off = (size_t)(rowb + ai * HALF + m * 16) * 1024 + col0;
; #pragma unroll
;                 for (int bj = 0; bj < 2; ++bj) { f32x4 o[2];
;                     if (lat && rinB) { const u32x4 w = *(const u32x4*)(rinB + off + bj * 32);
;                         const f32x4 b0 = {__builtin_bit_cast(float, w.x << 16), __builtin_bit_cast(float, w.x & 0xffff0000u), __builtin_bit_cast(float, w.y << 16), __builtin_bit_cast(float, w.y & 0xffff0000u)};
;                         const f32x4 b1 = {__builtin_bit_cast(float, w.z << 16), __builtin_bit_cast(float, w.z & 0xffff0000u), __builtin_bit_cast(float, w.w << 16), __builtin_bit_cast(float, w.w & 0xffff0000u)};
;                         o[0] = b0 * 1.6817928305074290f + gv[bj][0] * acc[ai][bj][m][0]; o[1] = b1 * 1.6817928305074290f + gv[bj][1] * acc[ai][bj][m][1]; }
;                     else {
; #pragma unroll
;                     for (int n = 0; n < 2; ++n) { const f32x4 bs = *(const f32x4*)(ib + off + bj * 32 + n * 4); o[n] = bs * 1.6817928305074290f + gv[bj][n] * acc[ai][bj][m][n]; } }
;                     if (tobf) *(u32x4*)(vout + off + bj * 32) = pack8(o[0], o[1]);
;                     else { *(f32x4*)(ob + off + bj * 32) = o[0]; *(f32x4*)(ob + off + bj * 32 + 4) = o[1]; } }
.LBB0_1676:
	s_andn2_b64 vcc, exec, s[26:27]
	s_cbranch_vccnz .LBB0_1678
	s_waitcnt vmcnt(7)
	v_mov_b32_e32 v42, v238
	v_mov_b32_e32 v43, v239
	v_mov_b32_e32 v44, v240
	v_mov_b32_e32 v45, v241
	v_mov_b32_e32 v62, v242
	v_mov_b32_e32 v63, v243
	v_mov_b32_e32 v64, v244
	v_mov_b32_e32 v65, v245
	v_lshlrev_b32_e32 v251, 1, v250
	v_add_u32_e32 v251, 0xb0000, v251
	global_load_dwordx4 v[238:241], v251, s[24:25]
	global_load_dwordx4 v[242:245], v251, s[24:25] offset:16
	v_pk_mul_f32 v[44:45], v[44:45], s[86:87] op_sel_hi:[1,0]
	v_pk_mul_f32 v[42:43], v[42:43], s[86:87] op_sel_hi:[1,0]
	v_pk_fma_f32 v[44:45], v[40:41], v[56:57], v[44:45]
	v_pk_fma_f32 v[42:43], v[38:39], v[54:55], v[42:43]

; __device__ __forceinline__ u32x4 pack8(const f32x4 a, const f32x4 b) { u32x4 w; w.x = cvt_pk_bf16(a[0], a[1]); w.y = cvt_pk_bf16(a[2], a[3]); w.z = cvt_pk_bf16(b[0], b[1]); w.w = cvt_pk_bf16(b[2], b[3]); return w; }
;     __device__ __forceinline__ void operator()(const f32x4 (&acc)[2][2][4][2], const Unit& u, int wr, int wc, int fr, int fq) const {
;     ...
;             for (int m = 0; m < 4; ++m) { const size_t off = (size_t)(rowb + ai * HALF + m * 16) * 1024 + col0;
; #pragma unroll
;                 for (int bj = 0; bj < 2; ++bj) { f32x4 o[2];
;                     if (lat && rinB) { const u32x4 w = *(const u32x4*)(rinB + off + bj * 32);
;                         const f32x4 b0 = {__builtin_bit_cast(float, w.x << 16), __builtin_bit_cast(float, w.x & 0xffff0000u), __builtin_bit_cast(float, w.y << 16), __builtin_bit_cast(float, w.y & 0xffff0000u)};
;                         const f32x4 b1 = {__builtin_bit_cast(float, w.z << 16), __builtin_bit_cast(float, w.z & 0xffff0000u), __builtin_bit_cast(float, w.w << 16), __builtin_bit_cast(float, w.w & 0xffff0000u)};
;                         o[0] = b0 * 1.6817928305074290f + gv[bj][0] * acc[ai][bj][m][0]; o[1] = b1 * 1.6817928305074290f + gv[bj][1] * acc[ai][bj][m][1]; }
;                     else {
; #pragma unroll
;                     for (int n = 0; n < 2; ++n) { const f32x4 bs = *(const f32x4*)(ib + off + bj * 32 + n * 4); o[n] = bs * 1.6817928305074290f + gv[bj][n] * acc[ai][bj][m][n]; } }
;                     if (tobf) *(u32x4*)(vout + off + bj * 32) = pack8(o[0], o[1]);
;                     else { *(f32x4*)(ob + off + bj * 32) = o[0]; *(f32x4*)(ob + off + bj * 32 + 4) = o[1]; } }
.LBB0_1684:
	s_andn2_b64 vcc, exec, s[26:27]
	v_lshl_add_u64 v[42:43], v[46:47], 2, s[24:25]
	s_cbranch_vccnz .LBB0_1686
	s_waitcnt vmcnt(7)
	v_mov_b32_e32 v34, v208
	v_mov_b32_e32 v35, v209
	v_mov_b32_e32 v36, v210
	v_mov_b32_e32 v37, v211
	v_mov_b32_e32 v38, v226
	v_mov_b32_e32 v39, v227
	v_mov_b32_e32 v40, v228
	v_mov_b32_e32 v41, v229
	v_lshlrev_b32_e32 v251, 1, v250
	v_add_u32_e32 v251, 0xb0000, v251
	global_load_dwordx4 v[208:211], v251, s[24:25] offset:128
	global_load_dwordx4 v[226:229], v251, s[24:25] offset:144
	v_pk_mul_f32 v[36:37], v[36:37], s[86:87] op_sel_hi:[1,0]
	v_pk_mul_f32 v[34:35], v[34:35], s[86:87] op_sel_hi:[1,0]
	v_pk_fma_f32 v[36:37], v[32:33], v[72:73], v[36:37]
	v_pk_fma_f32 v[34:35], v[30:31], v[70:71], v[34:35]

; __device__ __forceinline__ u32x4 pack8(const f32x4 a, const f32x4 b) { u32x4 w; w.x = cvt_pk_bf16(a[0], a[1]); w.y = cvt_pk_bf16(a[2], a[3]); w.z = cvt_pk_bf16(b[0], b[1]); w.w = cvt_pk_bf16(b[2], b[3]); return w; }
;     __device__ __forceinline__ void operator()(const f32x4 (&acc)[2][2][4][2], const Unit& u, int wr, int wc, int fr, int fq) const {
;     ...
;             for (int m = 0; m < 4; ++m) { const size_t off = (size_t)(rowb + ai * HALF + m * 16) * 1024 + col0;
; #pragma unroll
;                 for (int bj = 0; bj < 2; ++bj) { f32x4 o[2];
;                     if (lat && rinB) { const u32x4 w = *(const u32x4*)(rinB + off + bj * 32);
;                         const f32x4 b0 = {__builtin_bit_cast(float, w.x << 16), __builtin_bit_cast(float, w.x & 0xffff0000u), __builtin_bit_cast(float, w.y << 16), __builtin_bit_cast(float, w.y & 0xffff0000u)};
;                         const f32x4 b1 = {__builtin_bit_cast(float, w.z << 16), __builtin_bit_cast(float, w.z & 0xffff0000u), __builtin_bit_cast(float, w.w << 16), __builtin_bit_cast(float, w.w & 0xffff0000u)};
;                         o[0] = b0 * 1.6817928305074290f + gv[bj][0] * acc[ai][bj][m][0]; o[1] = b1 * 1.6817928305074290f + gv[bj][1] * acc[ai][bj][m][1]; }
;                     else {
; #pragma unroll
;                     for (int n = 0; n < 2; ++n) { const f32x4 bs = *(const f32x4*)(ib + off + bj * 32 + n * 4); o[n] = bs * 1.6817928305074290f + gv[bj][n] * acc[ai][bj][m][n]; } }
;                     if (tobf) *(u32x4*)(vout + off + bj * 32) = pack8(o[0], o[1]);
;                     else { *(f32x4*)(ob + off + bj * 32) = o[0]; *(f32x4*)(ob + off + bj * 32 + 4) = o[1]; } }
.LBB0_1692:
	s_andn2_b64 vcc, exec, s[26:27]
	s_cbranch_vccnz .LBB0_1694
	s_waitcnt vmcnt(7)
	v_mov_b32_e32 v26, v230
	v_mov_b32_e32 v27, v231
	v_mov_b32_e32 v28, v232
	v_mov_b32_e32 v29, v233
	v_mov_b32_e32 v38, v234
	v_mov_b32_e32 v39, v235
	v_mov_b32_e32 v40, v236
	v_mov_b32_e32 v41, v237
	v_pk_mul_f32 v[28:29], v[28:29], s[86:87] op_sel_hi:[1,0]
	v_pk_mul_f32 v[26:27], v[26:27], s[86:87] op_sel_hi:[1,0]
	v_pk_fma_f32 v[28:29], v[24:25], v[56:57], v[28:29]
	v_pk_fma_f32 v[26:27], v[22:23], v[54:55], v[26:27]

; __device__ __forceinline__ u32x4 pack8(const f32x4 a, const f32x4 b) { u32x4 w; w.x = cvt_pk_bf16(a[0], a[1]); w.y = cvt_pk_bf16(a[2], a[3]); w.z = cvt_pk_bf16(b[0], b[1]); w.w = cvt_pk_bf16(b[2], b[3]); return w; }
;     __device__ __forceinline__ void operator()(const f32x4 (&acc)[2][2][4][2], const Unit& u, int wr, int wc, int fr, int fq) const {
;     ...
;             for (int m = 0; m < 4; ++m) { const size_t off = (size_t)(rowb + ai * HALF + m * 16) * 1024 + col0;
; #pragma unroll
;                 for (int bj = 0; bj < 2; ++bj) { f32x4 o[2];
;                     if (lat && rinB) { const u32x4 w = *(const u32x4*)(rinB + off + bj * 32);
;                         const f32x4 b0 = {__builtin_bit_cast(float, w.x << 16), __builtin_bit_cast(float, w.x & 0xffff0000u), __builtin_bit_cast(float, w.y << 16), __builtin_bit_cast(float, w.y & 0xffff0000u)};
;                         const f32x4 b1 = {__builtin_bit_cast(float, w.z << 16), __builtin_bit_cast(float, w.z & 0xffff0000u), __builtin_bit_cast(float, w.w << 16), __builtin_bit_cast(float, w.w & 0xffff0000u)};
;                         o[0] = b0 * 1.6817928305074290f + gv[bj][0] * acc[ai][bj][m][0]; o[1] = b1 * 1.6817928305074290f + gv[bj][1] * acc[ai][bj][m][1]; }
;                     else {
; #pragma unroll
;                     for (int n = 0; n < 2; ++n) { const f32x4 bs = *(const f32x4*)(ib + off + bj * 32 + n * 4); o[n] = bs * 1.6817928305074290f + gv[bj][n] * acc[ai][bj][m][n]; } }
;                     if (tobf) *(u32x4*)(vout + off + bj * 32) = pack8(o[0], o[1]);
;                     else { *(f32x4*)(ob + off + bj * 32) = o[0]; *(f32x4*)(ob + off + bj * 32 + 4) = o[1]; } }
.LBB0_1700:
	s_andn2_b64 vcc, exec, s[26:27]
	v_lshl_add_u64 v[26:27], v[30:31], 2, s[24:25]
	s_cbranch_vccnz .LBB0_1702
	s_waitcnt vmcnt(5)
	v_mov_b32_e32 v18, v238
	v_mov_b32_e32 v19, v239
	v_mov_b32_e32 v20, v240
	v_mov_b32_e32 v21, v241
	v_mov_b32_e32 v22, v242
	v_mov_b32_e32 v23, v243
	v_mov_b32_e32 v24, v244
	v_mov_b32_e32 v25, v245
	v_pk_mul_f32 v[20:21], v[20:21], s[86:87] op_sel_hi:[1,0]
	v_pk_mul_f32 v[18:19], v[18:19], s[86:87] op_sel_hi:[1,0]
	v_pk_fma_f32 v[20:21], v[16:17], v[72:73], v[20:21]
	v_pk_fma_f32 v[18:19], v[14:15], v[70:71], v[18:19]

; __device__ __forceinline__ u32x4 pack8(const f32x4 a, const f32x4 b) { u32x4 w; w.x = cvt_pk_bf16(a[0], a[1]); w.y = cvt_pk_bf16(a[2], a[3]); w.z = cvt_pk_bf16(b[0], b[1]); w.w = cvt_pk_bf16(b[2], b[3]); return w; }
;     __device__ __forceinline__ void operator()(const f32x4 (&acc)[2][2][4][2], const Unit& u, int wr, int wc, int fr, int fq) const {
;     ...
;             for (int m = 0; m < 4; ++m) { const size_t off = (size_t)(rowb + ai * HALF + m * 16) * 1024 + col0;
; #pragma unroll
;                 for (int bj = 0; bj < 2; ++bj) { f32x4 o[2];
;                     if (lat && rinB) { const u32x4 w = *(const u32x4*)(rinB + off + bj * 32);
;                         const f32x4 b0 = {__builtin_bit_cast(float, w.x << 16), __builtin_bit_cast(float, w.x & 0xffff0000u), __builtin_bit_cast(float, w.y << 16), __builtin_bit_cast(float, w.y & 0xffff0000u)};
;                         const f32x4 b1 = {__builtin_bit_cast(float, w.z << 16), __builtin_bit_cast(float, w.z & 0xffff0000u), __builtin_bit_cast(float, w.w << 16), __builtin_bit_cast(float, w.w & 0xffff0000u)};
;                         o[0] = b0 * 1.6817928305074290f + gv[bj][0] * acc[ai][bj][m][0]; o[1] = b1 * 1.6817928305074290f + gv[bj][1] * acc[ai][bj][m][1]; }
;                     else {
; #pragma unroll
;                     for (int n = 0; n < 2; ++n) { const f32x4 bs = *(const f32x4*)(ib + off + bj * 32 + n * 4); o[n] = bs * 1.6817928305074290f + gv[bj][n] * acc[ai][bj][m][n]; } }
;                     if (tobf) *(u32x4*)(vout + off + bj * 32) = pack8(o[0], o[1]);
;                     else { *(f32x4*)(ob + off + bj * 32) = o[0]; *(f32x4*)(ob + off + bj * 32 + 4) = o[1]; } }
.LBB0_1708:
	s_andn2_b64 vcc, exec, s[24:25]
	s_cbranch_vccnz .LBB0_1710
	s_waitcnt vmcnt(3)
	v_mov_b32_e32 v10, v208
	v_mov_b32_e32 v11, v209
	v_mov_b32_e32 v12, v210
	v_mov_b32_e32 v13, v211
	v_mov_b32_e32 v22, v226
	v_mov_b32_e32 v23, v227
	v_mov_b32_e32 v24, v228
	v_mov_b32_e32 v25, v229
	v_pk_mul_f32 v[12:13], v[12:13], s[86:87] op_sel_hi:[1,0]
	v_pk_mul_f32 v[10:11], v[10:11], s[86:87] op_sel_hi:[1,0]
	v_pk_fma_f32 v[12:13], v[8:9], v[56:57], v[12:13]
	v_pk_fma_f32 v[10:11], v[6:7], v[54:55], v[10:11]
